# LayerNorm phase stores issued write-through (sc1) so they drain during the phase instead of in the barrier leader's L2 write-back
# speedup vs baseline: 1.0050x; 1.0042x over previous
.LBB0_27:
	v_add_u32_e32 v1, s38, v32
	v_add_u32_e32 v2, s35, v32
	v_cmp_lt_i32_e32 vcc, s6, v1
	v_add_u32_e32 v0, 0xfffff000, v32
	v_add_u32_e32 v3, s33, v32
	v_cndmask_b32_e32 v88, v1, v32, vcc
	v_cmp_lt_i32_e32 vcc, s6, v2
	v_ashrrev_i32_e32 v4, 10, v0
	v_add_u32_e32 v1, 1, v4
	v_cndmask_b32_e32 v46, v2, v32, vcc
	v_cmp_lt_i32_e32 vcc, s6, v3
	v_add_u32_e32 v6, 0xfffff000, v88
	v_ashrrev_i32_e32 v5, 10, v6
	v_cndmask_b32_e32 v44, v3, v32, vcc
	v_cmp_gt_i32_e32 vcc, s2, v32
	s_waitcnt lgkmcnt(0)
	v_mov_b32_e32 v12, s87
	v_mov_b32_e32 v13, s85
	v_cndmask_b32_e64 v4, v1, 0, vcc
	v_mov_b32_e32 v14, s86
	v_mov_b32_e32 v15, s84
	v_cndmask_b32_e32 v1, 0, v33, vcc
	v_cndmask_b32_e32 v0, v0, v32, vcc
	v_add_u32_e32 v10, 1, v5
	v_mul_hi_i32_i24_e32 v5, 0x9000, v4
	v_mul_i32_i24_e32 v4, 0x9000, v4
	v_cndmask_b32_e32 v3, v12, v13, vcc
	v_cndmask_b32_e32 v2, v14, v15, vcc
	v_lshlrev_b64 v[0:1], 12, v[0:1]
	v_lshl_add_u64 v[4:5], s[60:61], 0, v[4:5]
	v_lshl_add_u64 v[0:1], v[2:3], 0, v[0:1]
	v_lshl_add_u64 v[90:91], v[4:5], 0, s[30:31]
	v_lshl_add_u64 v[92:93], v[4:5], 0, v[152:153]
	v_lshl_add_u64 v[0:1], v[0:1], 0, v[152:153]
	v_lshl_add_u64 v[4:5], v[90:91], 0, v[152:153]
	global_load_dwordx4 v[154:157], v[92:93], off offset:1024
	global_load_dwordx4 v[158:161], v[92:93], off offset:2048
	global_load_dwordx4 v[162:165], v[92:93], off offset:3072
	flat_load_dwordx4 v[48:51], v[92:93]
	global_load_dwordx4 v[166:169], v[4:5], off offset:1024
	global_load_dwordx4 v[170:173], v[4:5], off offset:2048
	global_load_dwordx4 v[174:177], v[4:5], off offset:3072
	flat_load_dwordx4 v[52:55], v[4:5]
	global_load_dwordx4 v[56:59], v[0:1], off
	v_add_u32_e32 v16, 0xfffff000, v44
	v_add_u32_e32 v8, 0xfffff000, v46
	v_ashrrev_i32_e32 v9, 10, v16
	v_ashrrev_i32_e32 v89, 31, v88
	v_ashrrev_i32_e32 v47, 31, v46
	v_ashrrev_i32_e32 v7, 10, v8
	v_cmp_gt_i32_e32 vcc, s2, v46
	v_add_u32_e32 v9, 1, v9
	v_cmp_gt_i32_e64 s[8:9], s2, v44
	v_cmp_gt_i32_e64 s[10:11], s2, v88
	v_ashrrev_i32_e32 v45, 31, v44
	v_add_u32_e32 v7, 1, v7
	v_cndmask_b32_e64 v100, v9, 0, s[8:9]
	v_cndmask_b32_e64 v3, 0, v89, s[10:11]
	v_cndmask_b32_e64 v2, v6, v88, s[10:11]
	v_cndmask_b32_e32 v9, 0, v47, vcc
	v_cndmask_b32_e32 v8, v8, v46, vcc
	v_cndmask_b32_e64 v98, v10, 0, s[10:11]
	v_cndmask_b32_e64 v99, v7, 0, vcc
	v_cndmask_b32_e64 v7, v12, v13, s[10:11]
	v_cndmask_b32_e64 v6, v14, v15, s[10:11]
	v_cndmask_b32_e32 v11, v12, v13, vcc
	v_cndmask_b32_e32 v10, v14, v15, vcc
	v_cndmask_b32_e64 v5, 0, v45, s[8:9]
	v_cndmask_b32_e64 v4, v16, v44, s[8:9]
	v_lshlrev_b64 v[2:3], 12, v[2:3]
	v_lshlrev_b64 v[8:9], 12, v[8:9]
	v_cndmask_b32_e64 v13, v12, v13, s[8:9]
	v_cndmask_b32_e64 v12, v14, v15, s[8:9]
	v_lshlrev_b64 v[4:5], 12, v[4:5]
	global_load_dwordx4 v[60:63], v[0:1], off offset:1024
	global_load_dwordx4 v[64:67], v[0:1], off offset:2048
	global_load_dwordx4 v[68:71], v[0:1], off offset:3072
	v_lshl_add_u64 v[0:1], v[6:7], 0, v[2:3]
	v_lshl_add_u64 v[2:3], v[10:11], 0, v[8:9]
	v_mov_b32_e32 v39, v153
	v_lshl_add_u64 v[4:5], v[12:13], 0, v[4:5]
	v_lshl_add_u64 v[0:1], v[0:1], 0, v[152:153]
	v_lshl_add_u64 v[2:3], v[2:3], 0, v[152:153]
	v_lshl_add_u64 v[94:95], v[90:91], 0, v[38:39]
	v_lshl_add_u64 v[96:97], v[4:5], 0, v[152:153]
	global_load_dwordx4 v[72:75], v[0:1], off
	global_load_dwordx4 v[76:79], v[0:1], off offset:1024
	global_load_dwordx4 v[80:83], v[0:1], off offset:2048
	global_load_dwordx4 v[84:87], v[0:1], off offset:3072
	global_load_dwordx4 v[28:31], v[2:3], off
	global_load_dwordx4 v[24:27], v[2:3], off offset:1024
	global_load_dwordx4 v[20:23], v[2:3], off offset:2048
	global_load_dwordx4 v[16:19], v[2:3], off offset:3072
	global_load_dwordx4 v[12:15], v[96:97], off
	global_load_dwordx4 v[8:11], v[96:97], off offset:1024
	global_load_dwordx4 v[4:7], v[96:97], off offset:2048
	s_nop 0
	global_load_dwordx4 v[0:3], v[96:97], off offset:3072
	v_mov_b32_e32 v41, v153
	v_mov_b32_e32 v43, v153
	v_lshlrev_b64 v[46:47], 11, v[46:47]
	v_lshl_add_u64 v[32:33], v[32:33], 0, s[96:97]
	v_cmp_lt_i32_e32 vcc, s6, v32
	s_or_b64 s[16:17], vcc, s[16:17]
	s_waitcnt vmcnt(0) lgkmcnt(0)
	v_pk_add_f32 v[54:55], v[54:55], 1.0 op_sel_hi:[1,0]
	v_pk_add_f32 v[52:53], v[52:53], 1.0 op_sel_hi:[1,0]
	v_pk_fma_f32 v[50:51], v[58:59], v[54:55], v[50:51]
	v_pk_fma_f32 v[48:49], v[56:57], v[52:53], v[48:49]
	v_lshl_add_u64 v[56:57], v[90:91], 0, v[40:41]
	v_cvt_pk_bf16_f32 v48, v48, v49
	v_cvt_pk_bf16_f32 v49, v50, v51
	flat_store_dwordx2 v[36:37], v[48:49] sc1
	v_mov_b64_e32 v[48:49], v[166:167]
	v_mov_b64_e32 v[50:51], v[168:169]
	s_nop 0
	v_mov_b64_e32 v[52:53], v[154:155]
	v_mov_b64_e32 v[54:55], v[156:157]
	v_pk_add_f32 v[50:51], v[50:51], 1.0 op_sel_hi:[1,0]
	v_pk_add_f32 v[48:49], v[48:49], 1.0 op_sel_hi:[1,0]
	v_pk_fma_f32 v[50:51], v[62:63], v[50:51], v[54:55]
	v_pk_fma_f32 v[48:49], v[60:61], v[48:49], v[52:53]
	s_nop 0
	v_cvt_pk_bf16_f32 v48, v48, v49
	v_cvt_pk_bf16_f32 v49, v50, v51
	flat_store_dwordx2 v[36:37], v[48:49] offset:512 sc1
	v_mov_b64_e32 v[48:49], v[170:171]
	v_mov_b64_e32 v[50:51], v[172:173]
	s_nop 0
	v_mov_b64_e32 v[52:53], v[158:159]
	v_mov_b64_e32 v[54:55], v[160:161]
	v_lshl_add_u64 v[56:57], v[90:91], 0, v[42:43]
	v_pk_add_f32 v[50:51], v[50:51], 1.0 op_sel_hi:[1,0]
	v_pk_add_f32 v[48:49], v[48:49], 1.0 op_sel_hi:[1,0]
	v_pk_fma_f32 v[50:51], v[66:67], v[50:51], v[54:55]
	v_pk_fma_f32 v[48:49], v[64:65], v[48:49], v[52:53]
	s_nop 0
	v_cvt_pk_bf16_f32 v48, v48, v49
	v_cvt_pk_bf16_f32 v49, v50, v51
	flat_store_dwordx2 v[36:37], v[48:49] offset:1024 sc1
	v_mov_b64_e32 v[48:49], v[174:175]
	v_mov_b64_e32 v[50:51], v[176:177]
	s_nop 0
	v_mov_b64_e32 v[52:53], v[162:163]
	v_mov_b64_e32 v[54:55], v[164:165]
	v_mul_hi_i32_i24_e32 v57, 0x9000, v98
	v_mul_i32_i24_e32 v56, 0x9000, v98
	v_lshl_add_u64 v[56:57], s[60:61], 0, v[56:57]
	v_lshl_add_u64 v[58:59], v[56:57], 0, s[30:31]
	v_lshl_add_u64 v[60:61], v[58:59], 0, v[152:153]
	v_lshl_add_u64 v[56:57], v[56:57], 0, v[152:153]
	v_lshl_add_u64 v[62:63], v[58:59], 0, v[38:39]
	v_pk_add_f32 v[50:51], v[50:51], 1.0 op_sel_hi:[1,0]
	v_pk_add_f32 v[48:49], v[48:49], 1.0 op_sel_hi:[1,0]
	v_pk_fma_f32 v[50:51], v[70:71], v[50:51], v[54:55]
	v_pk_fma_f32 v[48:49], v[68:69], v[48:49], v[52:53]
	s_nop 0
	v_cvt_pk_bf16_f32 v48, v48, v49
	v_cvt_pk_bf16_f32 v49, v50, v51
	flat_store_dwordx2 v[36:37], v[48:49] offset:1536 sc1
	global_load_dwordx4 v[154:157], v[60:61], off offset:1024
	global_load_dwordx4 v[158:161], v[60:61], off offset:2048
	global_load_dwordx4 v[162:165], v[60:61], off offset:3072
	flat_load_dwordx4 v[48:51], v[60:61]
	s_nop 0
	global_load_dwordx4 v[166:169], v[56:57], off offset:1024
	global_load_dwordx4 v[170:173], v[56:57], off offset:2048
	global_load_dwordx4 v[174:177], v[56:57], off offset:3072
	flat_load_dwordx4 v[52:55], v[56:57]
	v_lshlrev_b64 v[60:61], 11, v[88:89]
	v_lshl_add_u64 v[60:61], v[34:35], 0, v[60:61]
	v_lshl_add_u64 v[36:37], v[36:37], 0, s[22:23]
	s_waitcnt vmcnt(0) lgkmcnt(0)
	v_pk_add_f32 v[50:51], v[50:51], 1.0 op_sel_hi:[1,0]
	v_pk_add_f32 v[48:49], v[48:49], 1.0 op_sel_hi:[1,0]
	v_pk_fma_f32 v[50:51], v[74:75], v[50:51], v[54:55]
	v_pk_fma_f32 v[48:49], v[72:73], v[48:49], v[52:53]
	s_nop 0
	v_cvt_pk_bf16_f32 v48, v48, v49
	v_cvt_pk_bf16_f32 v49, v50, v51
	flat_store_dwordx2 v[60:61], v[48:49] sc1
	v_mov_b64_e32 v[48:49], v[154:155]
	v_mov_b64_e32 v[50:51], v[156:157]
	s_nop 0
	v_mov_b64_e32 v[52:53], v[166:167]
	v_mov_b64_e32 v[54:55], v[168:169]
	v_lshl_add_u64 v[62:63], v[58:59], 0, v[40:41]
	v_lshl_add_u64 v[58:59], v[58:59], 0, v[42:43]
	v_pk_add_f32 v[50:51], v[50:51], 1.0 op_sel_hi:[1,0]
	v_pk_add_f32 v[48:49], v[48:49], 1.0 op_sel_hi:[1,0]
	v_pk_fma_f32 v[50:51], v[78:79], v[50:51], v[54:55]
	v_pk_fma_f32 v[48:49], v[76:77], v[48:49], v[52:53]
	s_nop 0
	v_cvt_pk_bf16_f32 v48, v48, v49
	v_cvt_pk_bf16_f32 v49, v50, v51
	flat_store_dwordx2 v[60:61], v[48:49] offset:512 sc1
	v_mov_b64_e32 v[48:49], v[158:159]
	v_mov_b64_e32 v[50:51], v[160:161]
	s_nop 0
	v_mov_b64_e32 v[52:53], v[170:171]
	v_mov_b64_e32 v[54:55], v[172:173]
	v_pk_add_f32 v[50:51], v[50:51], 1.0 op_sel_hi:[1,0]
	v_pk_add_f32 v[48:49], v[48:49], 1.0 op_sel_hi:[1,0]
	v_pk_fma_f32 v[50:51], v[82:83], v[50:51], v[54:55]
	v_pk_fma_f32 v[48:49], v[80:81], v[48:49], v[52:53]
	s_nop 0
	v_cvt_pk_bf16_f32 v48, v48, v49
	v_cvt_pk_bf16_f32 v49, v50, v51
	flat_store_dwordx2 v[60:61], v[48:49] offset:1024 sc1
	v_mov_b64_e32 v[48:49], v[162:163]
	v_mov_b64_e32 v[50:51], v[164:165]
	s_nop 0
	v_mov_b64_e32 v[52:53], v[174:175]
	v_mov_b64_e32 v[54:55], v[176:177]
	v_mul_hi_i32_i24_e32 v57, 0x9000, v99
	v_mul_i32_i24_e32 v56, 0x9000, v99
	v_lshl_add_u64 v[56:57], s[60:61], 0, v[56:57]
	v_lshl_add_u64 v[58:59], v[56:57], 0, s[30:31]
	v_lshl_add_u64 v[62:63], v[58:59], 0, v[152:153]
	v_lshl_add_u64 v[56:57], v[56:57], 0, v[152:153]
	v_pk_add_f32 v[50:51], v[50:51], 1.0 op_sel_hi:[1,0]
	v_pk_add_f32 v[48:49], v[48:49], 1.0 op_sel_hi:[1,0]
	v_pk_fma_f32 v[50:51], v[86:87], v[50:51], v[54:55]
	v_pk_fma_f32 v[48:49], v[84:85], v[48:49], v[52:53]
	s_nop 0
	v_cvt_pk_bf16_f32 v48, v48, v49
	v_cvt_pk_bf16_f32 v49, v50, v51
	flat_store_dwordx2 v[60:61], v[48:49] offset:1536 sc1
	global_load_dwordx4 v[154:157], v[62:63], off offset:1024
	global_load_dwordx4 v[158:161], v[62:63], off offset:2048
	global_load_dwordx4 v[162:165], v[62:63], off offset:3072
	flat_load_dwordx4 v[48:51], v[62:63]
	s_nop 0
	global_load_dwordx4 v[166:169], v[56:57], off offset:1024
	global_load_dwordx4 v[170:173], v[56:57], off offset:2048
	global_load_dwordx4 v[174:177], v[56:57], off offset:3072
	flat_load_dwordx4 v[52:55], v[56:57]
	v_lshl_add_u64 v[60:61], v[34:35], 0, v[46:47]
	v_lshl_add_u64 v[46:47], v[58:59], 0, v[38:39]
	s_waitcnt vmcnt(0) lgkmcnt(0)
	v_pk_add_f32 v[50:51], v[50:51], 1.0 op_sel_hi:[1,0]
	v_pk_add_f32 v[48:49], v[48:49], 1.0 op_sel_hi:[1,0]
	v_pk_fma_f32 v[30:31], v[30:31], v[50:51], v[54:55]
	v_pk_fma_f32 v[28:29], v[28:29], v[48:49], v[52:53]
	v_lshl_add_u64 v[50:51], v[58:59], 0, v[40:41]
	v_cvt_pk_bf16_f32 v28, v28, v29
	v_cvt_pk_bf16_f32 v29, v30, v31
	flat_store_dwordx2 v[60:61], v[28:29] sc1
	v_mov_b64_e32 v[28:29], v[154:155]
	v_mov_b64_e32 v[30:31], v[156:157]
	s_nop 0
	v_mov_b64_e32 v[46:47], v[166:167]
	v_mov_b64_e32 v[48:49], v[168:169]
	v_pk_add_f32 v[30:31], v[30:31], 1.0 op_sel_hi:[1,0]
	v_pk_add_f32 v[28:29], v[28:29], 1.0 op_sel_hi:[1,0]
	v_pk_fma_f32 v[26:27], v[26:27], v[30:31], v[48:49]
	v_pk_fma_f32 v[24:25], v[24:25], v[28:29], v[46:47]
	v_lshl_add_u64 v[46:47], v[58:59], 0, v[42:43]
	v_cvt_pk_bf16_f32 v24, v24, v25
	v_cvt_pk_bf16_f32 v25, v26, v27
	flat_store_dwordx2 v[60:61], v[24:25] offset:512 sc1
	v_mov_b64_e32 v[24:25], v[158:159]
	v_mov_b64_e32 v[26:27], v[160:161]
	s_nop 0
	v_mov_b64_e32 v[28:29], v[170:171]
	v_mov_b64_e32 v[30:31], v[172:173]
	v_pk_add_f32 v[26:27], v[26:27], 1.0 op_sel_hi:[1,0]
	v_pk_add_f32 v[24:25], v[24:25], 1.0 op_sel_hi:[1,0]
	v_pk_fma_f32 v[22:23], v[22:23], v[26:27], v[30:31]
	v_pk_fma_f32 v[20:21], v[20:21], v[24:25], v[28:29]
	v_mul_hi_i32_i24_e32 v29, 0x9000, v100
	v_cvt_pk_bf16_f32 v20, v20, v21
	v_cvt_pk_bf16_f32 v21, v22, v23
	flat_store_dwordx2 v[60:61], v[20:21] offset:1024 sc1
	v_mov_b64_e32 v[20:21], v[162:163]
	v_mov_b64_e32 v[22:23], v[164:165]
	s_nop 0
	v_mov_b64_e32 v[24:25], v[174:175]
	v_mov_b64_e32 v[26:27], v[176:177]
	v_mul_i32_i24_e32 v28, 0x9000, v100
	v_lshl_add_u64 v[28:29], s[60:61], 0, v[28:29]
	v_lshl_add_u64 v[30:31], v[28:29], 0, s[30:31]
	v_lshl_add_u64 v[46:47], v[30:31], 0, v[152:153]
	v_lshl_add_u64 v[28:29], v[28:29], 0, v[152:153]
	v_pk_add_f32 v[22:23], v[22:23], 1.0 op_sel_hi:[1,0]
	v_pk_add_f32 v[20:21], v[20:21], 1.0 op_sel_hi:[1,0]
	v_pk_fma_f32 v[18:19], v[18:19], v[22:23], v[26:27]
	v_pk_fma_f32 v[16:17], v[16:17], v[20:21], v[24:25]
	v_lshlrev_b64 v[24:25], 11, v[44:45]
	v_cvt_pk_bf16_f32 v16, v16, v17
	v_cvt_pk_bf16_f32 v17, v18, v19
	flat_store_dwordx2 v[60:61], v[16:17] offset:1536 sc1
	global_load_dwordx4 v[154:157], v[46:47], off offset:1024
	global_load_dwordx4 v[158:161], v[46:47], off offset:2048
	global_load_dwordx4 v[162:165], v[46:47], off offset:3072
	flat_load_dwordx4 v[16:19], v[46:47]
	s_nop 0
	global_load_dwordx4 v[166:169], v[28:29], off offset:1024
	global_load_dwordx4 v[170:173], v[28:29], off offset:2048
	global_load_dwordx4 v[174:177], v[28:29], off offset:3072
	flat_load_dwordx4 v[20:23], v[28:29]
	v_lshl_add_u64 v[24:25], v[34:35], 0, v[24:25]
	v_lshl_add_u64 v[26:27], v[30:31], 0, v[38:39]
	s_waitcnt vmcnt(0) lgkmcnt(0)
	v_pk_add_f32 v[18:19], v[18:19], 1.0 op_sel_hi:[1,0]
	v_pk_add_f32 v[16:17], v[16:17], 1.0 op_sel_hi:[1,0]
	v_pk_fma_f32 v[14:15], v[14:15], v[18:19], v[22:23]
	v_pk_fma_f32 v[12:13], v[12:13], v[16:17], v[20:21]
	v_lshl_add_u64 v[20:21], v[30:31], 0, v[40:41]
	v_cvt_pk_bf16_f32 v12, v12, v13
	v_cvt_pk_bf16_f32 v13, v14, v15
	flat_store_dwordx2 v[24:25], v[12:13] sc1
	v_mov_b64_e32 v[12:13], v[154:155]
	v_mov_b64_e32 v[14:15], v[156:157]
	s_nop 0
	v_mov_b64_e32 v[16:17], v[166:167]
	v_mov_b64_e32 v[18:19], v[168:169]
	v_pk_add_f32 v[14:15], v[14:15], 1.0 op_sel_hi:[1,0]
	v_pk_add_f32 v[12:13], v[12:13], 1.0 op_sel_hi:[1,0]
	v_pk_fma_f32 v[10:11], v[10:11], v[14:15], v[18:19]
	v_pk_fma_f32 v[8:9], v[8:9], v[12:13], v[16:17]
	v_lshl_add_u64 v[16:17], v[30:31], 0, v[42:43]
	v_cvt_pk_bf16_f32 v8, v8, v9
	v_cvt_pk_bf16_f32 v9, v10, v11
	flat_store_dwordx2 v[24:25], v[8:9] offset:512 sc1
	v_mov_b64_e32 v[8:9], v[158:159]
	v_mov_b64_e32 v[10:11], v[160:161]
	s_nop 0
	v_mov_b64_e32 v[12:13], v[170:171]
	v_mov_b64_e32 v[14:15], v[172:173]
	v_pk_add_f32 v[10:11], v[10:11], 1.0 op_sel_hi:[1,0]
	v_pk_add_f32 v[8:9], v[8:9], 1.0 op_sel_hi:[1,0]
	v_pk_fma_f32 v[6:7], v[6:7], v[10:11], v[14:15]
	v_pk_fma_f32 v[4:5], v[4:5], v[8:9], v[12:13]
	s_nop 0
	v_cvt_pk_bf16_f32 v4, v4, v5
	v_cvt_pk_bf16_f32 v5, v6, v7
	flat_store_dwordx2 v[24:25], v[4:5] offset:1024 sc1
	v_mov_b64_e32 v[4:5], v[162:163]
	v_mov_b64_e32 v[6:7], v[164:165]
	s_nop 0
	v_mov_b64_e32 v[8:9], v[174:175]
	v_mov_b64_e32 v[10:11], v[176:177]
	v_pk_add_f32 v[6:7], v[6:7], 1.0 op_sel_hi:[1,0]
	v_pk_add_f32 v[4:5], v[4:5], 1.0 op_sel_hi:[1,0]
	v_pk_fma_f32 v[2:3], v[2:3], v[6:7], v[10:11]
	v_pk_fma_f32 v[0:1], v[0:1], v[4:5], v[8:9]
	s_nop 0
	v_cvt_pk_bf16_f32 v0, v0, v1
	v_cvt_pk_bf16_f32 v1, v2, v3
	flat_store_dwordx2 v[24:25], v[0:1] offset:1536 sc1
	s_andn2_b64 exec, exec, s[16:17]
	s_cbranch_execnz .LBB0_27

.LBB0_51:
	global_load_dwordx4 v[154:157], v[74:75], off
	global_load_dwordx4 v[158:161], v[76:77], off
	global_load_dwordx4 v[162:165], v[74:75], off offset:1024
	global_load_dwordx4 v[166:169], v[76:77], off offset:1024
	global_load_dwordx4 v[170:173], v[74:75], off offset:2048
	global_load_dwordx4 v[174:177], v[76:77], off offset:2048
	global_load_dwordx4 v[178:181], v[74:75], off offset:3072
	global_load_dwordx4 v[182:185], v[76:77], off offset:3072
	v_add_u32_e32 v0, 0xfffff000, v64
	v_ashrrev_i32_e32 v0, 10, v0
	v_add_u32_e32 v0, 1, v0
	v_cmp_lt_i32_e32 vcc, s33, v64
	s_mov_b32 s2, 0x1000000
	global_load_dwordx4 v[186:189], v[86:87], off offset:1024
	global_load_dwordx4 v[190:193], v[86:87], off offset:2048
	global_load_dwordx4 v[194:197], v[86:87], off offset:3072
	flat_load_dwordx4 v[8:11], v[86:87]
	v_cndmask_b32_e32 v4, 0, v0, vcc
	v_add_u32_e32 v0, s38, v64
	v_cmp_lt_i32_e32 vcc, s6, v0
	v_ashrrev_i32_e32 v5, 31, v4
	v_lshl_add_u64 v[88:89], v[4:5], 0, s[28:29]
	v_cndmask_b32_e32 v0, v0, v64, vcc
	v_add_u32_e32 v1, 0xfffff000, v0
	v_ashrrev_i32_e32 v1, 10, v1
	v_add_u32_e32 v1, 1, v1
	v_cmp_lt_i32_e32 vcc, s33, v0
	v_mad_u64_u32 v[4:5], s[4:5], v88, s7, v[78:79]
	s_nop 0
	v_cndmask_b32_e32 v2, 0, v1, vcc
	v_add_u32_e32 v1, s35, v64
	v_cmp_lt_i32_e32 vcc, s6, v1
	v_mad_i32_i24 v5, v89, s7, v5
	global_load_dwordx4 v[198:201], v[4:5], off offset:1024
	global_load_dwordx4 v[202:205], v[4:5], off offset:2048
	global_load_dwordx4 v[224:227], v[4:5], off offset:3072
	flat_load_dwordx4 v[12:15], v[4:5]
	v_cndmask_b32_e32 v40, v1, v64, vcc
	v_add_u32_e32 v1, 0xfffff000, v40
	v_ashrrev_i32_e32 v1, 10, v1
	v_add_u32_e32 v1, 1, v1
	v_cmp_lt_i32_e32 vcc, s33, v40
	v_ashrrev_i32_e32 v3, 31, v2
	v_lshl_add_u64 v[92:93], v[2:3], 0, s[28:29]
	v_cndmask_b32_e32 v42, 0, v1, vcc
	v_add_u32_e32 v1, s26, v64
	v_cmp_lt_i32_e32 vcc, s6, v1
	s_mov_b64 s[8:9], 0x1000000
	v_mad_u64_u32 v[48:49], s[4:5], v92, s7, v[78:79]
	v_cndmask_b32_e32 v20, v1, v64, vcc
	v_add_u32_e32 v1, 0xfffff000, v20
	v_ashrrev_i32_e32 v1, 10, v1
	v_add_u32_e32 v1, 1, v1
	v_cmp_lt_i32_e32 vcc, s33, v20
	v_lshlrev_b32_e32 v152, 1, v66
	v_mad_i32_i24 v49, v93, s7, v49
	v_cndmask_b32_e32 v22, 0, v1, vcc
	v_add_co_u32_e32 v6, vcc, s2, v84
	s_brev_b32 s2, 64
	s_nop 0
	v_addc_co_u32_e32 v7, vcc, 0, v85, vcc
	v_add_co_u32_e32 v24, vcc, s2, v84
	global_load_dwordx2 v[228:229], v[6:7], off offset:512
	global_load_dwordx2 v[230:231], v[6:7], off offset:1024
	global_load_dwordx2 v[232:233], v[6:7], off offset:1536
	flat_load_dwordx2 v[16:17], v[6:7]
	s_nop 0
	v_addc_co_u32_e32 v25, vcc, 0, v85, vcc
	global_load_dwordx2 v[234:235], v[24:25], off offset:512
	global_load_dwordx2 v[236:237], v[24:25], off offset:1024
	global_load_dwordx2 v[238:239], v[24:25], off offset:1536
	flat_load_dwordx2 v[26:27], v[24:25]
	v_lshlrev_b32_e32 v104, 1, v68
	v_mov_b32_e32 v105, v153
	v_lshlrev_b32_e32 v106, 1, v70
	v_mov_b32_e32 v107, v153
	v_lshlrev_b32_e32 v120, 1, v72
	v_mov_b32_e32 v121, v153
	v_ashrrev_i32_e32 v41, 31, v40
	v_ashrrev_i32_e32 v43, 31, v42
	v_lshlrev_b64 v[96:97], 11, v[40:41]
	v_lshl_add_u64 v[98:99], v[42:43], 0, s[28:29]
	v_lshl_add_u64 v[42:43], s[56:57], 0, v[96:97]
	v_ashrrev_i32_e32 v21, 31, v20
	v_ashrrev_i32_e32 v23, 31, v22
	s_mov_b32 s2, 0x3727c5ac
	s_waitcnt vmcnt(0) lgkmcnt(0)
	v_lshlrev_b32_e32 v18, 16, v16
	v_and_b32_e32 v19, 0xffff0000, v16
	v_lshlrev_b32_e32 v16, 16, v17
	v_and_b32_e32 v17, 0xffff0000, v17
	v_lshlrev_b32_e32 v28, 16, v26
	v_and_b32_e32 v29, 0xffff0000, v26
	v_lshlrev_b32_e32 v26, 16, v27
	v_and_b32_e32 v27, 0xffff0000, v27
	v_pk_add_f32 v[18:19], v[18:19], v[28:29]
	v_pk_add_f32 v[16:17], v[16:17], v[26:27]
	v_pk_mul_f32 v[12:13], v[12:13], v[18:19]
	v_pk_mul_f32 v[14:15], v[14:15], v[16:17]
	v_pk_fma_f32 v[8:9], v[8:9], s[42:43], v[12:13] op_sel_hi:[1,0,1]
	v_pk_fma_f32 v[10:11], v[10:11], s[42:43], v[14:15] op_sel_hi:[1,0,1]
	v_mov_b32_e32 v14, v8
	v_pk_mov_b32 v[12:13], v[8:9], v[10:11] op_sel:[1,0]
	v_mov_b32_e32 v15, v11
	v_pk_add_f32 v[12:13], v[12:13], v[14:15]
	s_nop 0
	v_add_f32_e32 v1, v12, v13
	v_mov_b64_e32 v[12:13], v[186:187]
	v_mov_b64_e32 v[14:15], v[188:189]
	v_mov_b64_e32 v[16:17], v[198:199]
	v_mov_b64_e32 v[18:19], v[200:201]
	v_mov_b64_e32 v[26:27], v[228:229]
	v_mov_b64_e32 v[32:33], v[234:235]
	v_add_f32_e32 v28, 0, v1
	v_ashrrev_i32_e32 v1, 31, v0
	v_lshlrev_b64 v[90:91], 11, v[0:1]
	v_lshlrev_b64 v[2:3], 12, v[0:1]
	v_lshlrev_b32_e32 v30, 16, v26
	v_and_b32_e32 v31, 0xffff0000, v26
	v_lshlrev_b32_e32 v26, 16, v27
	v_and_b32_e32 v27, 0xffff0000, v27
	v_lshlrev_b32_e32 v34, 16, v32
	v_and_b32_e32 v35, 0xffff0000, v32
	v_lshlrev_b32_e32 v32, 16, v33
	v_and_b32_e32 v33, 0xffff0000, v33
	v_pk_add_f32 v[30:31], v[30:31], v[34:35]
	v_pk_add_f32 v[26:27], v[26:27], v[32:33]
	v_pk_mul_f32 v[16:17], v[16:17], v[30:31]
	v_pk_mul_f32 v[18:19], v[18:19], v[26:27]
	v_pk_fma_f32 v[12:13], v[12:13], s[42:43], v[16:17] op_sel_hi:[1,0,1]
	v_pk_fma_f32 v[14:15], v[14:15], s[42:43], v[18:19] op_sel_hi:[1,0,1]
	v_mov_b32_e32 v18, v12
	v_pk_mov_b32 v[16:17], v[12:13], v[14:15] op_sel:[1,0]
	v_mov_b32_e32 v19, v15
	v_pk_add_f32 v[16:17], v[16:17], v[18:19]
	s_nop 0
	v_pk_add_f32 v[30:31], v[16:17], v[16:17] op_sel:[0,1] op_sel_hi:[1,0]
	v_mov_b64_e32 v[16:17], v[190:191]
	v_mov_b64_e32 v[18:19], v[192:193]
	v_mov_b64_e32 v[32:33], v[202:203]
	v_mov_b64_e32 v[34:35], v[204:205]
	v_mov_b64_e32 v[26:27], v[230:231]
	v_mov_b64_e32 v[38:39], v[236:237]
	v_lshlrev_b32_e32 v36, 16, v26
	v_and_b32_e32 v37, 0xffff0000, v26
	v_lshlrev_b32_e32 v44, 16, v38
	v_and_b32_e32 v45, 0xffff0000, v38
	v_lshlrev_b32_e32 v26, 16, v27
	v_and_b32_e32 v27, 0xffff0000, v27
	v_lshlrev_b32_e32 v38, 16, v39
	v_and_b32_e32 v39, 0xffff0000, v39
	v_pk_add_f32 v[36:37], v[36:37], v[44:45]
	v_pk_add_f32 v[26:27], v[26:27], v[38:39]
	v_pk_mul_f32 v[32:33], v[32:33], v[36:37]
	v_pk_mul_f32 v[26:27], v[34:35], v[26:27]
	v_pk_fma_f32 v[16:17], v[16:17], s[42:43], v[32:33] op_sel_hi:[1,0,1]
	v_mov_b64_e32 v[32:33], v[194:195]
	v_mov_b64_e32 v[34:35], v[196:197]
	v_mov_b64_e32 v[36:37], v[224:225]
	v_mov_b64_e32 v[38:39], v[226:227]
	s_nop 0
	v_mov_b64_e32 v[4:5], v[232:233]
	v_pk_fma_f32 v[18:19], v[18:19], s[42:43], v[26:27] op_sel_hi:[1,0,1]
	v_mov_b64_e32 v[24:25], v[238:239]
	v_add_f32_e32 v44, v16, v17
	v_add_f32_e32 v46, v18, v19
	v_lshlrev_b32_e32 v6, 16, v4
	v_and_b32_e32 v7, 0xffff0000, v4
	v_lshlrev_b32_e32 v26, 16, v24
	v_and_b32_e32 v27, 0xffff0000, v24
	v_lshlrev_b32_e32 v4, 16, v5
	v_and_b32_e32 v5, 0xffff0000, v5
	v_lshlrev_b32_e32 v24, 16, v25
	v_and_b32_e32 v25, 0xffff0000, v25
	v_pk_add_f32 v[6:7], v[6:7], v[26:27]
	v_pk_add_f32 v[4:5], v[4:5], v[24:25]
	v_pk_mul_f32 v[6:7], v[36:37], v[6:7]
	v_pk_mul_f32 v[4:5], v[38:39], v[4:5]
	v_pk_fma_f32 v[24:25], v[32:33], s[42:43], v[6:7] op_sel_hi:[1,0,1]
	v_pk_fma_f32 v[26:27], v[34:35], s[42:43], v[4:5] op_sel_hi:[1,0,1]
	v_mov_b32_e32 v29, v24
	v_mov_b32_e32 v31, v25
	v_pk_add_f32 v[4:5], v[28:29], v[30:31]
	v_mov_b32_e32 v45, v26
	v_mov_b32_e32 v47, v27
	v_lshl_add_u64 v[28:29], s[56:57], 0, v[90:91]
	v_pk_add_f32 v[6:7], v[44:45], v[46:47]
	v_lshl_add_u64 v[44:45], v[28:29], 0, s[8:9]
	v_pk_add_f32 v[4:5], v[4:5], v[6:7]
	v_lshl_add_u64 v[52:53], v[28:29], 0, v[152:153]
	v_lshl_add_u64 v[34:35], v[44:45], 0, v[152:153]
	v_add_f32_e32 v122, v4, v5
	global_load_dwordx4 v[186:189], v[48:49], off offset:1024
	global_load_dwordx4 v[190:193], v[48:49], off offset:2048
	global_load_dwordx4 v[194:197], v[48:49], off offset:3072
	flat_load_dwordx4 v[4:7], v[48:49]
	global_load_dwordx2 v[228:229], v[52:53], off offset:512
	global_load_dwordx2 v[230:231], v[52:53], off offset:1024
	global_load_dwordx2 v[232:233], v[52:53], off offset:1536
	flat_load_dwordx2 v[28:29], v[52:53]
	v_lshl_add_u64 v[32:33], v[80:81], 0, v[2:3]
	global_load_dwordx2 v[234:235], v[34:35], off offset:512
	global_load_dwordx2 v[236:237], v[34:35], off offset:1024
	global_load_dwordx2 v[238:239], v[34:35], off offset:1536
	flat_load_dwordx2 v[34:35], v[34:35]
	v_lshl_add_u64 v[38:39], v[44:45], 0, v[104:105]
	global_load_dwordx4 v[198:201], v[32:33], off offset:1024
	global_load_dwordx4 v[202:205], v[32:33], off offset:2048
	global_load_dwordx4 v[224:227], v[32:33], off offset:3072
	flat_load_dwordx4 v[0:3], v[32:33]
	v_lshl_add_u64 v[54:55], v[44:45], 0, v[106:107]
	v_lshl_add_u64 v[44:45], v[44:45], 0, v[120:121]
	s_waitcnt vmcnt(0) lgkmcnt(0)
	v_lshlrev_b32_e32 v30, 16, v28
	v_and_b32_e32 v31, 0xffff0000, v28
	v_lshlrev_b32_e32 v28, 16, v29
	v_and_b32_e32 v29, 0xffff0000, v29
	v_lshlrev_b32_e32 v36, 16, v34
	v_and_b32_e32 v37, 0xffff0000, v34
	v_lshlrev_b32_e32 v34, 16, v35
	v_and_b32_e32 v35, 0xffff0000, v35
	v_pk_add_f32 v[30:31], v[30:31], v[36:37]
	v_pk_add_f32 v[28:29], v[28:29], v[34:35]
	v_pk_mul_f32 v[4:5], v[4:5], v[30:31]
	v_pk_mul_f32 v[6:7], v[6:7], v[28:29]
	v_pk_fma_f32 v[28:29], v[0:1], s[42:43], v[4:5] op_sel_hi:[1,0,1]
	v_pk_fma_f32 v[30:31], v[2:3], s[42:43], v[6:7] op_sel_hi:[1,0,1]
	v_mov_b32_e32 v2, v28
	v_pk_mov_b32 v[0:1], v[28:29], v[30:31] op_sel:[1,0]
	v_mov_b32_e32 v3, v31
	v_pk_add_f32 v[0:1], v[0:1], v[2:3]
	s_nop 0
	v_add_f32_e32 v0, v0, v1
	v_add_f32_e32 v46, 0, v0
	v_mov_b64_e32 v[0:1], v[198:199]
	v_mov_b64_e32 v[2:3], v[200:201]
	v_mov_b64_e32 v[4:5], v[186:187]
	v_mov_b64_e32 v[6:7], v[188:189]
	v_mov_b64_e32 v[34:35], v[228:229]
	v_lshlrev_b32_e32 v36, 16, v34
	v_mov_b64_e32 v[38:39], v[234:235]
	v_and_b32_e32 v37, 0xffff0000, v34
	v_lshlrev_b32_e32 v34, 16, v35
	v_and_b32_e32 v35, 0xffff0000, v35
	v_lshlrev_b32_e32 v50, 16, v38
	v_and_b32_e32 v51, 0xffff0000, v38
	v_lshlrev_b32_e32 v38, 16, v39
	v_and_b32_e32 v39, 0xffff0000, v39
	v_pk_add_f32 v[36:37], v[36:37], v[50:51]
	v_pk_add_f32 v[34:35], v[34:35], v[38:39]
	v_pk_mul_f32 v[4:5], v[4:5], v[36:37]
	v_pk_mul_f32 v[6:7], v[6:7], v[34:35]
	v_pk_fma_f32 v[38:39], v[0:1], s[42:43], v[4:5] op_sel_hi:[1,0,1]
	v_pk_fma_f32 v[60:61], v[2:3], s[42:43], v[6:7] op_sel_hi:[1,0,1]
	v_mov_b32_e32 v2, v38
	v_pk_mov_b32 v[0:1], v[38:39], v[60:61] op_sel:[1,0]
	v_mov_b32_e32 v3, v61
	v_pk_add_f32 v[0:1], v[0:1], v[2:3]
	s_nop 0
	v_pk_add_f32 v[50:51], v[0:1], v[0:1] op_sel:[0,1] op_sel_hi:[1,0]
	v_mov_b64_e32 v[0:1], v[202:203]
	v_mov_b64_e32 v[2:3], v[204:205]
	v_mov_b64_e32 v[4:5], v[190:191]
	v_mov_b64_e32 v[6:7], v[192:193]
	v_mov_b64_e32 v[34:35], v[230:231]
	v_lshlrev_b32_e32 v36, 16, v34
	v_mov_b64_e32 v[54:55], v[236:237]
	v_and_b32_e32 v37, 0xffff0000, v34
	v_lshlrev_b32_e32 v34, 16, v35
	v_and_b32_e32 v35, 0xffff0000, v35
	v_lshlrev_b32_e32 v56, 16, v54
	v_and_b32_e32 v57, 0xffff0000, v54
	v_lshlrev_b32_e32 v54, 16, v55
	v_and_b32_e32 v55, 0xffff0000, v55
	v_pk_add_f32 v[34:35], v[34:35], v[54:55]
	v_pk_add_f32 v[36:37], v[36:37], v[56:57]
	v_pk_mul_f32 v[6:7], v[6:7], v[34:35]
	v_pk_mul_f32 v[4:5], v[4:5], v[36:37]
	v_pk_fma_f32 v[36:37], v[2:3], s[42:43], v[6:7] op_sel_hi:[1,0,1]
	v_pk_fma_f32 v[34:35], v[0:1], s[42:43], v[4:5] op_sel_hi:[1,0,1]
	v_mov_b64_e32 v[0:1], v[224:225]
	v_mov_b64_e32 v[2:3], v[226:227]
	v_mov_b64_e32 v[4:5], v[194:195]
	v_mov_b64_e32 v[6:7], v[196:197]
	s_nop 0
	v_mov_b64_e32 v[52:53], v[232:233]
	v_add_f32_e32 v54, v34, v35
	v_mov_b64_e32 v[44:45], v[238:239]
	v_add_f32_e32 v56, v36, v37
	v_lshlrev_b32_e32 v48, 16, v52
	v_and_b32_e32 v49, 0xffff0000, v52
	v_lshlrev_b32_e32 v58, 16, v44
	v_and_b32_e32 v59, 0xffff0000, v44
	v_lshlrev_b32_e32 v52, 16, v53
	v_and_b32_e32 v53, 0xffff0000, v53
	v_lshlrev_b32_e32 v44, 16, v45
	v_and_b32_e32 v45, 0xffff0000, v45
	v_pk_add_f32 v[48:49], v[48:49], v[58:59]
	v_pk_add_f32 v[44:45], v[52:53], v[44:45]
	v_pk_mul_f32 v[4:5], v[4:5], v[48:49]
	v_pk_mul_f32 v[6:7], v[6:7], v[44:45]
	v_pk_fma_f32 v[62:63], v[0:1], s[42:43], v[4:5] op_sel_hi:[1,0,1]
	v_pk_fma_f32 v[118:119], v[2:3], s[42:43], v[6:7] op_sel_hi:[1,0,1]
	v_mov_b32_e32 v47, v62
	v_mov_b32_e32 v51, v63
	v_pk_add_f32 v[0:1], v[46:47], v[50:51]
	v_mov_b32_e32 v55, v118
	v_mov_b32_e32 v57, v119
	v_lshl_add_u64 v[44:45], v[42:43], 0, s[8:9]
	v_mad_u64_u32 v[46:47], s[4:5], v98, s7, v[78:79]
	v_pk_add_f32 v[2:3], v[54:55], v[56:57]
	v_mad_i32_i24 v47, v99, s7, v47
	v_lshl_add_u64 v[42:43], v[42:43], 0, v[152:153]
	v_lshl_add_u64 v[52:53], v[44:45], 0, v[152:153]
	v_pk_add_f32 v[0:1], v[0:1], v[2:3]
	global_load_dwordx4 v[186:189], v[46:47], off offset:1024
	global_load_dwordx4 v[190:193], v[46:47], off offset:2048
	global_load_dwordx4 v[194:197], v[46:47], off offset:3072
	flat_load_dwordx4 v[4:7], v[46:47]
	global_load_dwordx2 v[228:229], v[42:43], off offset:512
	global_load_dwordx2 v[230:231], v[42:43], off offset:1024
	global_load_dwordx2 v[232:233], v[42:43], off offset:1536
	flat_load_dwordx2 v[48:49], v[42:43]
	v_add_f32_e32 v126, v0, v1
	global_load_dwordx2 v[234:235], v[52:53], off offset:512
	global_load_dwordx2 v[236:237], v[52:53], off offset:1024
	global_load_dwordx2 v[238:239], v[52:53], off offset:1536
	flat_load_dwordx2 v[52:53], v[52:53]
	v_lshlrev_b64 v[0:1], 12, v[40:41]
	v_lshl_add_u64 v[40:41], v[80:81], 0, v[0:1]
	global_load_dwordx4 v[198:201], v[40:41], off offset:1024
	global_load_dwordx4 v[202:205], v[40:41], off offset:2048
	global_load_dwordx4 v[224:227], v[40:41], off offset:3072
	flat_load_dwordx4 v[0:3], v[40:41]
	v_lshl_add_u64 v[56:57], v[44:45], 0, v[104:105]
	v_lshl_add_u64 v[102:103], v[44:45], 0, v[106:107]
	v_lshl_add_u64 v[44:45], v[44:45], 0, v[120:121]
	s_waitcnt vmcnt(0) lgkmcnt(0)
	v_lshlrev_b32_e32 v50, 16, v48
	v_and_b32_e32 v51, 0xffff0000, v48
	v_lshlrev_b32_e32 v48, 16, v49
	v_and_b32_e32 v49, 0xffff0000, v49
	v_lshlrev_b32_e32 v54, 16, v52
	v_and_b32_e32 v55, 0xffff0000, v52
	v_lshlrev_b32_e32 v52, 16, v53
	v_and_b32_e32 v53, 0xffff0000, v53
	v_pk_add_f32 v[50:51], v[50:51], v[54:55]
	v_pk_add_f32 v[48:49], v[48:49], v[52:53]
	v_pk_mul_f32 v[4:5], v[4:5], v[50:51]
	v_pk_mul_f32 v[6:7], v[6:7], v[48:49]
	v_pk_fma_f32 v[50:51], v[0:1], s[42:43], v[4:5] op_sel_hi:[1,0,1]
	v_pk_fma_f32 v[52:53], v[2:3], s[42:43], v[6:7] op_sel_hi:[1,0,1]
	v_mov_b32_e32 v2, v50
	v_pk_mov_b32 v[0:1], v[50:51], v[52:53] op_sel:[1,0]
	v_mov_b32_e32 v3, v53
	v_pk_add_f32 v[0:1], v[0:1], v[2:3]
	s_nop 0
	v_add_f32_e32 v0, v0, v1
	v_add_f32_e32 v94, 0, v0
	v_mov_b64_e32 v[0:1], v[198:199]
	v_mov_b64_e32 v[2:3], v[200:201]
	v_mov_b64_e32 v[4:5], v[186:187]
	v_mov_b64_e32 v[6:7], v[188:189]
	v_mov_b64_e32 v[48:49], v[228:229]
	v_lshlrev_b32_e32 v54, 16, v48
	v_mov_b64_e32 v[56:57], v[234:235]
	v_and_b32_e32 v55, 0xffff0000, v48
	v_lshlrev_b32_e32 v48, 16, v49
	v_and_b32_e32 v49, 0xffff0000, v49
	v_lshlrev_b32_e32 v58, 16, v56
	v_and_b32_e32 v59, 0xffff0000, v56
	v_lshlrev_b32_e32 v56, 16, v57
	v_and_b32_e32 v57, 0xffff0000, v57
	v_pk_add_f32 v[54:55], v[54:55], v[58:59]
	v_pk_add_f32 v[48:49], v[48:49], v[56:57]
	v_pk_mul_f32 v[4:5], v[4:5], v[54:55]
	v_pk_mul_f32 v[6:7], v[6:7], v[48:49]
	v_pk_fma_f32 v[56:57], v[0:1], s[42:43], v[4:5] op_sel_hi:[1,0,1]
	v_pk_fma_f32 v[58:59], v[2:3], s[42:43], v[6:7] op_sel_hi:[1,0,1]
	v_mov_b32_e32 v2, v56
	v_pk_mov_b32 v[0:1], v[56:57], v[58:59] op_sel:[1,0]
	v_mov_b32_e32 v3, v59
	v_pk_add_f32 v[0:1], v[0:1], v[2:3]
	s_nop 0
	v_pk_add_f32 v[100:101], v[0:1], v[0:1] op_sel:[0,1] op_sel_hi:[1,0]
	v_mov_b64_e32 v[0:1], v[202:203]
	v_mov_b64_e32 v[2:3], v[204:205]
	v_mov_b64_e32 v[4:5], v[190:191]
	v_mov_b64_e32 v[6:7], v[192:193]
	v_mov_b64_e32 v[48:49], v[230:231]
	v_lshlrev_b32_e32 v54, 16, v48
	v_mov_b64_e32 v[102:103], v[236:237]
	v_and_b32_e32 v55, 0xffff0000, v48
	v_lshlrev_b32_e32 v48, 16, v49
	v_and_b32_e32 v49, 0xffff0000, v49
	v_lshlrev_b32_e32 v108, 16, v102
	v_and_b32_e32 v109, 0xffff0000, v102
	v_lshlrev_b32_e32 v102, 16, v103
	v_and_b32_e32 v103, 0xffff0000, v103
	v_pk_add_f32 v[48:49], v[48:49], v[102:103]
	v_pk_add_f32 v[54:55], v[54:55], v[108:109]
	v_pk_mul_f32 v[6:7], v[6:7], v[48:49]
	v_pk_mul_f32 v[4:5], v[4:5], v[54:55]
	v_pk_fma_f32 v[116:117], v[2:3], s[42:43], v[6:7] op_sel_hi:[1,0,1]
	v_pk_fma_f32 v[54:55], v[0:1], s[42:43], v[4:5] op_sel_hi:[1,0,1]
	v_mov_b64_e32 v[0:1], v[224:225]
	v_mov_b64_e32 v[2:3], v[226:227]
	v_mov_b64_e32 v[4:5], v[194:195]
	v_mov_b64_e32 v[6:7], v[196:197]
	s_nop 0
	v_mov_b64_e32 v[42:43], v[232:233]
	v_add_f32_e32 v102, v54, v55
	v_mov_b64_e32 v[44:45], v[238:239]
	v_add_f32_e32 v108, v116, v117
	v_lshlrev_b32_e32 v46, 16, v42
	v_and_b32_e32 v47, 0xffff0000, v42
	v_lshlrev_b32_e32 v42, 16, v43
	v_and_b32_e32 v43, 0xffff0000, v43
	v_lshlrev_b32_e32 v48, 16, v44
	v_and_b32_e32 v49, 0xffff0000, v44
	v_lshlrev_b32_e32 v44, 16, v45
	v_and_b32_e32 v45, 0xffff0000, v45
	v_pk_add_f32 v[42:43], v[42:43], v[44:45]
	v_pk_add_f32 v[44:45], v[46:47], v[48:49]
	v_pk_mul_f32 v[6:7], v[6:7], v[42:43]
	v_pk_mul_f32 v[4:5], v[4:5], v[44:45]
	v_pk_fma_f32 v[48:49], v[2:3], s[42:43], v[6:7] op_sel_hi:[1,0,1]
	v_pk_fma_f32 v[46:47], v[0:1], s[42:43], v[4:5] op_sel_hi:[1,0,1]
	v_mov_b32_e32 v103, v48
	v_mov_b32_e32 v95, v46
	v_mov_b32_e32 v101, v47
	v_mov_b32_e32 v109, v49
	v_pk_add_f32 v[0:1], v[94:95], v[100:101]
	v_pk_add_f32 v[2:3], v[102:103], v[108:109]
	v_lshlrev_b64 v[94:95], 11, v[20:21]
	v_pk_add_f32 v[0:1], v[0:1], v[2:3]
	v_lshl_add_u64 v[100:101], v[22:23], 0, s[28:29]
	v_add_f32_e32 v125, v0, v1
	v_lshlrev_b64 v[0:1], 12, v[20:21]
	v_lshl_add_u64 v[20:21], s[56:57], 0, v[94:95]
	v_lshl_add_u64 v[22:23], v[20:21], 0, s[8:9]
	v_mad_u64_u32 v[128:129], s[4:5], v100, s7, v[78:79]
	v_mad_i32_i24 v129, v101, s7, v129
	v_lshl_add_u64 v[20:21], v[20:21], 0, v[152:153]
	v_lshl_add_u64 v[108:109], v[22:23], 0, v[152:153]
	global_load_dwordx4 v[186:189], v[128:129], off offset:1024
	global_load_dwordx4 v[190:193], v[128:129], off offset:2048
	global_load_dwordx4 v[194:197], v[128:129], off offset:3072
	flat_load_dwordx4 v[4:7], v[128:129]
	global_load_dwordx2 v[228:229], v[20:21], off offset:512
	global_load_dwordx2 v[230:231], v[20:21], off offset:1024
	global_load_dwordx2 v[232:233], v[20:21], off offset:1536
	flat_load_dwordx2 v[42:43], v[20:21]
	v_lshl_add_u64 v[102:103], v[80:81], 0, v[0:1]
	global_load_dwordx2 v[234:235], v[108:109], off offset:512
	global_load_dwordx2 v[236:237], v[108:109], off offset:1024
	global_load_dwordx2 v[238:239], v[108:109], off offset:1536
	flat_load_dwordx2 v[108:109], v[108:109]
	v_lshl_add_u64 v[104:105], v[22:23], 0, v[104:105]
	global_load_dwordx4 v[198:201], v[102:103], off offset:1024
	global_load_dwordx4 v[202:205], v[102:103], off offset:2048
	global_load_dwordx4 v[224:227], v[102:103], off offset:3072
	flat_load_dwordx4 v[0:3], v[102:103]
	v_lshl_add_u64 v[106:107], v[22:23], 0, v[106:107]
	v_lshl_add_u64 v[22:23], v[22:23], 0, v[120:121]
	v_readlane_b32 s4, v254, 33
	v_readlane_b32 s5, v254, 34
	s_waitcnt vmcnt(0) lgkmcnt(0)
	v_lshlrev_b32_e32 v44, 16, v42
	v_and_b32_e32 v45, 0xffff0000, v42
	v_lshlrev_b32_e32 v42, 16, v43
	v_and_b32_e32 v43, 0xffff0000, v43
	v_lshlrev_b32_e32 v110, 16, v108
	v_and_b32_e32 v111, 0xffff0000, v108
	v_lshlrev_b32_e32 v108, 16, v109
	v_and_b32_e32 v109, 0xffff0000, v109
	v_pk_add_f32 v[44:45], v[44:45], v[110:111]
	v_pk_add_f32 v[42:43], v[42:43], v[108:109]
	v_pk_mul_f32 v[4:5], v[4:5], v[44:45]
	v_pk_mul_f32 v[6:7], v[6:7], v[42:43]
	v_pk_fma_f32 v[44:45], v[0:1], s[42:43], v[4:5] op_sel_hi:[1,0,1]
	v_pk_fma_f32 v[114:115], v[2:3], s[42:43], v[6:7] op_sel_hi:[1,0,1]
	v_mov_b32_e32 v2, v44
	v_pk_mov_b32 v[0:1], v[44:45], v[114:115] op_sel:[1,0]
	v_mov_b32_e32 v3, v115
	v_pk_add_f32 v[0:1], v[0:1], v[2:3]
	s_nop 0
	v_add_f32_e32 v0, v0, v1
	v_add_f32_e32 v130, 0, v0
	v_mov_b64_e32 v[0:1], v[198:199]
	v_mov_b64_e32 v[2:3], v[200:201]
	v_mov_b64_e32 v[4:5], v[186:187]
	v_mov_b64_e32 v[6:7], v[188:189]
	v_mov_b64_e32 v[42:43], v[228:229]
	v_lshlrev_b32_e32 v108, 16, v42
	v_mov_b64_e32 v[104:105], v[234:235]
	v_and_b32_e32 v109, 0xffff0000, v42
	v_lshlrev_b32_e32 v42, 16, v43
	v_and_b32_e32 v43, 0xffff0000, v43
	v_lshlrev_b32_e32 v110, 16, v104
	v_and_b32_e32 v111, 0xffff0000, v104
	v_lshlrev_b32_e32 v104, 16, v105
	v_and_b32_e32 v105, 0xffff0000, v105
	v_pk_add_f32 v[108:109], v[108:109], v[110:111]
	v_pk_add_f32 v[42:43], v[42:43], v[104:105]
	v_pk_mul_f32 v[4:5], v[4:5], v[108:109]
	v_pk_mul_f32 v[6:7], v[6:7], v[42:43]
	v_pk_fma_f32 v[42:43], v[0:1], s[42:43], v[4:5] op_sel_hi:[1,0,1]
	v_pk_fma_f32 v[112:113], v[2:3], s[42:43], v[6:7] op_sel_hi:[1,0,1]
	v_mov_b32_e32 v2, v42
	v_pk_mov_b32 v[0:1], v[42:43], v[112:113] op_sel:[1,0]
	v_mov_b32_e32 v3, v113
	v_pk_add_f32 v[0:1], v[0:1], v[2:3]
	s_nop 0
	v_pk_add_f32 v[132:133], v[0:1], v[0:1] op_sel:[0,1] op_sel_hi:[1,0]
	v_mov_b64_e32 v[0:1], v[202:203]
	v_mov_b64_e32 v[2:3], v[204:205]
	v_mov_b64_e32 v[4:5], v[190:191]
	v_mov_b64_e32 v[6:7], v[192:193]
	v_mov_b64_e32 v[104:105], v[230:231]
	v_lshlrev_b32_e32 v108, 16, v104
	v_mov_b64_e32 v[106:107], v[236:237]
	v_and_b32_e32 v109, 0xffff0000, v104
	v_lshlrev_b32_e32 v104, 16, v105
	v_and_b32_e32 v105, 0xffff0000, v105
	v_lshlrev_b32_e32 v110, 16, v106
	v_and_b32_e32 v111, 0xffff0000, v106
	v_lshlrev_b32_e32 v106, 16, v107
	v_and_b32_e32 v107, 0xffff0000, v107
	v_pk_add_f32 v[104:105], v[104:105], v[106:107]
	v_pk_add_f32 v[106:107], v[108:109], v[110:111]
	v_pk_mul_f32 v[6:7], v[6:7], v[104:105]
	v_pk_mul_f32 v[4:5], v[4:5], v[106:107]
	v_pk_fma_f32 v[110:111], v[2:3], s[42:43], v[6:7] op_sel_hi:[1,0,1]
	v_pk_fma_f32 v[108:109], v[0:1], s[42:43], v[4:5] op_sel_hi:[1,0,1]
	v_mov_b64_e32 v[0:1], v[224:225]
	v_mov_b64_e32 v[2:3], v[226:227]
	v_mov_b64_e32 v[4:5], v[194:195]
	v_mov_b64_e32 v[6:7], v[196:197]
	s_nop 0
	v_mov_b64_e32 v[20:21], v[232:233]
	v_add_f32_e32 v134, v108, v109
	v_mov_b64_e32 v[22:23], v[238:239]
	v_add_f32_e32 v136, v110, v111
	v_lshlrev_b32_e32 v104, 16, v20
	v_and_b32_e32 v105, 0xffff0000, v20
	v_lshlrev_b32_e32 v20, 16, v21
	v_and_b32_e32 v21, 0xffff0000, v21
	v_lshlrev_b32_e32 v106, 16, v22
	v_and_b32_e32 v107, 0xffff0000, v22
	v_lshlrev_b32_e32 v22, 16, v23
	v_and_b32_e32 v23, 0xffff0000, v23
	v_pk_add_f32 v[20:21], v[20:21], v[22:23]
	v_pk_add_f32 v[22:23], v[104:105], v[106:107]
	v_pk_mul_f32 v[6:7], v[6:7], v[20:21]
	v_pk_mul_f32 v[4:5], v[4:5], v[22:23]
	v_pk_fma_f32 v[106:107], v[2:3], s[42:43], v[6:7] op_sel_hi:[1,0,1]
	v_pk_fma_f32 v[104:105], v[0:1], s[42:43], v[4:5] op_sel_hi:[1,0,1]
	v_mov_b32_e32 v135, v106
	v_mov_b32_e32 v131, v104
	v_mov_b32_e32 v133, v105
	v_mov_b32_e32 v137, v107
	v_pk_add_f32 v[0:1], v[130:131], v[132:133]
	v_pk_add_f32 v[2:3], v[134:135], v[136:137]
	ds_bpermute_b32 v22, v67, v126
	v_pk_add_f32 v[0:1], v[0:1], v[2:3]
	s_waitcnt lgkmcnt(0)
	v_add_f32_e32 v22, v126, v22
	v_add_f32_e32 v65, v0, v1
	ds_bpermute_b32 v0, v67, v122
	ds_bpermute_b32 v23, v69, v22
	s_waitcnt lgkmcnt(1)
	v_add_f32_e32 v0, v122, v0
	ds_bpermute_b32 v1, v69, v0
	s_waitcnt lgkmcnt(1)
	v_add_f32_e32 v22, v22, v23
	ds_bpermute_b32 v23, v71, v22
	s_waitcnt lgkmcnt(1)
	v_add_f32_e32 v0, v0, v1
	ds_bpermute_b32 v1, v71, v0
	s_waitcnt lgkmcnt(1)
	v_add_f32_e32 v22, v22, v23
	ds_bpermute_b32 v23, v73, v22
	s_waitcnt lgkmcnt(1)
	v_add_f32_e32 v0, v0, v1
	ds_bpermute_b32 v1, v73, v0
	s_waitcnt lgkmcnt(1)
	v_add_f32_e32 v22, v22, v23
	ds_bpermute_b32 v23, v123, v22
	s_waitcnt lgkmcnt(1)
	v_add_f32_e32 v0, v0, v1
	ds_bpermute_b32 v1, v123, v0
	s_waitcnt lgkmcnt(1)
	v_add_f32_e32 v22, v22, v23
	ds_bpermute_b32 v23, v124, v22
	s_waitcnt lgkmcnt(1)
	v_add_f32_e32 v0, v0, v1
	ds_bpermute_b32 v1, v124, v0
	s_waitcnt lgkmcnt(1)
	v_add_f32_e32 v122, v22, v23
	v_fmamk_f32 v29, v122, 0xba800000, v29
	v_fmac_f32_e32 v28, 0xba800000, v122
	v_fmamk_f32 v31, v122, 0xba800000, v31
	s_waitcnt lgkmcnt(0)
	v_add_f32_e32 v20, v0, v1
	v_fmamk_f32 v9, v20, 0xba800000, v9
	v_fmac_f32_e32 v8, 0xba800000, v20
	v_fmamk_f32 v11, v20, 0xba800000, v11
	v_fmac_f32_e32 v10, 0xba800000, v20
	v_pk_mul_f32 v[0:1], v[10:11], v[10:11]
	v_pk_mul_f32 v[2:3], v[8:9], v[8:9]
	v_fmamk_f32 v13, v20, 0xba800000, v13
	v_pk_mov_b32 v[4:5], v[2:3], v[0:1] op_sel:[1,0]
	v_mov_b32_e32 v3, v1
	v_pk_add_f32 v[0:1], v[4:5], v[2:3]
	v_fmac_f32_e32 v12, 0xba800000, v20
	v_fmamk_f32 v15, v20, 0xba800000, v15
	v_fmac_f32_e32 v14, 0xba800000, v20
	v_pk_add_f32 v[0:1], v[0:1], v[0:1] op_sel_hi:[0,1]
	v_pk_mul_f32 v[2:3], v[14:15], v[14:15]
	v_pk_mul_f32 v[4:5], v[12:13], v[12:13]
	v_fmac_f32_e32 v16, 0xba800000, v20
	v_pk_mov_b32 v[6:7], v[4:5], v[2:3] op_sel:[1,0]
	v_mov_b32_e32 v5, v3
	v_fmamk_f32 v17, v20, 0xba800000, v17
	v_fmac_f32_e32 v18, 0xba800000, v20
	v_mul_f32_e32 v0, v16, v16
	v_pk_add_f32 v[2:3], v[6:7], v[4:5]
	v_fmamk_f32 v19, v20, 0xba800000, v19
	v_pk_fma_f32 v[4:5], v[16:17], v[16:17], v[0:1] op_sel_hi:[1,1,0]
	v_mul_f32_e32 v0, v18, v18
	v_pk_add_f32 v[2:3], v[2:3], v[2:3] op_sel_hi:[0,1]
	v_pk_fma_f32 v[6:7], v[18:19], v[18:19], v[0:1] op_sel_hi:[1,1,0]
	v_fmamk_f32 v27, v20, 0xba800000, v27
	v_fmac_f32_e32 v26, 0xba800000, v20
	v_fmamk_f32 v25, v20, 0xba800000, v25
	v_fmac_f32_e32 v24, 0xba800000, v20
	v_mul_f32_e32 v4, v24, v24
	v_mul_f32_e32 v6, v25, v25
	v_mul_f32_e32 v0, v26, v26
	v_mul_f32_e32 v2, v27, v27
	v_pk_add_f32 v[4:5], v[4:5], v[6:7]
	v_pk_add_f32 v[0:1], v[0:1], v[2:3]
	v_fmac_f32_e32 v30, 0xba800000, v122
	v_pk_add_f32 v[20:21], v[4:5], v[0:1]
	v_mov_b64_e32 v[0:1], v[154:155]
	v_mov_b64_e32 v[2:3], v[156:157]
	v_mov_b64_e32 v[4:5], v[158:159]
	v_mov_b64_e32 v[6:7], v[160:161]
	v_pk_mul_f32 v[22:23], v[30:31], v[30:31]
	v_pk_mul_f32 v[120:121], v[28:29], v[28:29]
	v_fmamk_f32 v39, v122, 0xba800000, v39
	v_pk_mov_b32 v[126:127], v[120:121], v[22:23] op_sel:[1,0]
	v_mov_b32_e32 v121, v23
	v_pk_add_f32 v[22:23], v[126:127], v[120:121]
	v_fmac_f32_e32 v38, 0xba800000, v122
	v_fmamk_f32 v61, v122, 0xba800000, v61
	v_fmac_f32_e32 v60, 0xba800000, v122
	v_pk_add_f32 v[22:23], v[22:23], v[22:23] op_sel_hi:[0,1]
	v_pk_mul_f32 v[120:121], v[60:61], v[60:61]
	v_pk_mul_f32 v[126:127], v[38:39], v[38:39]
	v_fmac_f32_e32 v34, 0xba800000, v122
	v_pk_mov_b32 v[128:129], v[126:127], v[120:121] op_sel:[1,0]
	v_mov_b32_e32 v127, v121
	v_fmamk_f32 v35, v122, 0xba800000, v35
	v_fmac_f32_e32 v36, 0xba800000, v122
	v_mul_f32_e32 v22, v34, v34
	v_pk_add_f32 v[120:121], v[128:129], v[126:127]
	v_fmamk_f32 v37, v122, 0xba800000, v37
	v_pk_fma_f32 v[126:127], v[34:35], v[34:35], v[22:23] op_sel_hi:[1,1,0]
	v_mul_f32_e32 v22, v36, v36
	v_pk_add_f32 v[120:121], v[120:121], v[120:121] op_sel_hi:[0,1]
	v_pk_fma_f32 v[128:129], v[36:37], v[36:37], v[22:23] op_sel_hi:[1,1,0]
	v_fmamk_f32 v119, v122, 0xba800000, v119
	v_fmac_f32_e32 v118, 0xba800000, v122
	v_fmamk_f32 v63, v122, 0xba800000, v63
	v_fmac_f32_e32 v62, 0xba800000, v122
	v_mul_f32_e32 v126, v62, v62
	v_mul_f32_e32 v128, v63, v63
	v_mul_f32_e32 v22, v118, v118
	v_mul_f32_e32 v120, v119, v119
	v_pk_add_f32 v[126:127], v[126:127], v[128:129]
	v_pk_add_f32 v[22:23], v[22:23], v[120:121]
	v_mov_b32_e32 v121, v20
	v_pk_add_f32 v[22:23], v[126:127], v[22:23]
	s_nop 0
	v_mov_b32_e32 v120, v22
	v_mov_b32_e32 v20, v23
	v_pk_add_f32 v[20:21], v[120:121], v[20:21]
	ds_bpermute_b32 v23, v67, v21
	ds_bpermute_b32 v22, v67, v20
	v_mov_b64_e32 v[120:121], s[2:3]
	s_mov_b32 s2, 0x3a800000
	s_waitcnt lgkmcnt(0)
	v_pk_add_f32 v[20:21], v[20:21], v[22:23]
	ds_bpermute_b32 v23, v69, v21
	ds_bpermute_b32 v22, v69, v20
	s_waitcnt lgkmcnt(0)
	v_pk_add_f32 v[20:21], v[20:21], v[22:23]
	ds_bpermute_b32 v23, v71, v21
	ds_bpermute_b32 v22, v71, v20
	s_waitcnt lgkmcnt(0)
	v_pk_add_f32 v[20:21], v[20:21], v[22:23]
	ds_bpermute_b32 v23, v73, v21
	ds_bpermute_b32 v22, v73, v20
	s_waitcnt lgkmcnt(0)
	v_pk_add_f32 v[20:21], v[20:21], v[22:23]
	ds_bpermute_b32 v23, v123, v21
	ds_bpermute_b32 v22, v123, v20
	s_waitcnt lgkmcnt(0)
	v_pk_add_f32 v[20:21], v[20:21], v[22:23]
	ds_bpermute_b32 v23, v124, v21
	ds_bpermute_b32 v22, v124, v20
	s_waitcnt lgkmcnt(0)
	v_pk_add_f32 v[20:21], v[20:21], v[22:23]
	s_nop 0
	v_pk_fma_f32 v[126:127], v[20:21], s[2:3], v[120:121] op_sel_hi:[1,0,0]
	s_nop 0
	v_mul_f32_e32 v20, 0x4b800000, v127
	v_cmp_gt_f32_e64 s[8:9], s68, v127
	v_cmp_gt_f32_e32 vcc, s68, v126
	s_nop 0
	v_cndmask_b32_e64 v20, v127, v20, s[8:9]
	v_rsq_f32_e32 v20, v20
	s_nop 0
	v_mul_f32_e32 v21, 0x45800000, v20
	v_cndmask_b32_e64 v122, v20, v21, s[8:9]
	v_pk_mul_f32 v[8:9], v[8:9], v[122:123] op_sel_hi:[1,0]
	v_pk_mul_f32 v[10:11], v[10:11], v[122:123] op_sel_hi:[1,0]
	v_pk_fma_f32 v[20:21], v[0:1], v[8:9], v[4:5]
	v_pk_fma_f32 v[22:23], v[2:3], v[10:11], v[6:7]
	flat_store_dwordx4 v[86:87], v[20:23] sc1
	v_mov_b64_e32 v[0:1], v[162:163]
	v_mov_b64_e32 v[2:3], v[164:165]
	v_mov_b64_e32 v[4:5], v[166:167]
	v_mov_b64_e32 v[6:7], v[168:169]
	v_pk_mul_f32 v[8:9], v[14:15], v[122:123] op_sel_hi:[1,0]
	v_pk_mul_f32 v[10:11], v[12:13], v[122:123] op_sel_hi:[1,0]
	v_pk_fma_f32 v[14:15], v[2:3], v[8:9], v[6:7]
	v_pk_fma_f32 v[12:13], v[0:1], v[10:11], v[4:5]
	flat_store_dwordx4 v[86:87], v[12:15] offset:1024 sc1
	v_mov_b64_e32 v[0:1], v[170:171]
	v_mov_b64_e32 v[2:3], v[172:173]
	v_mov_b64_e32 v[4:5], v[174:175]
	v_mov_b64_e32 v[6:7], v[176:177]
	v_pk_mul_f32 v[8:9], v[18:19], v[122:123] op_sel_hi:[1,0]
	v_pk_mul_f32 v[10:11], v[16:17], v[122:123] op_sel_hi:[1,0]
	v_pk_mul_f32 v[18:19], v[24:25], v[122:123] op_sel_hi:[1,0]
	v_pk_mul_f32 v[16:17], v[26:27], v[122:123] op_sel_hi:[1,0]
	v_pk_fma_f32 v[4:5], v[0:1], v[10:11], v[4:5]
	v_pk_fma_f32 v[6:7], v[2:3], v[8:9], v[6:7]
	flat_store_dwordx4 v[86:87], v[4:7] offset:2048 sc1
	v_mov_b64_e32 v[0:1], v[178:179]
	v_mov_b64_e32 v[2:3], v[180:181]
	v_mov_b64_e32 v[8:9], v[182:183]
	v_mov_b64_e32 v[10:11], v[184:185]
	v_pk_fma_f32 v[0:1], v[0:1], v[18:19], v[8:9]
	v_mul_f32_e32 v8, 0x4b800000, v126
	v_cndmask_b32_e32 v8, v126, v8, vcc
	v_rsq_f32_e32 v8, v8
	v_pk_fma_f32 v[2:3], v[2:3], v[16:17], v[10:11]
	flat_store_dwordx4 v[86:87], v[0:3] offset:3072 sc1
	v_mul_f32_e32 v9, 0x45800000, v8
	v_cndmask_b32_e32 v122, v8, v9, vcc
	v_mov_b64_e32 v[8:9], v[154:155]
	v_mov_b64_e32 v[10:11], v[156:157]
	v_mov_b64_e32 v[16:17], v[158:159]
	v_mov_b64_e32 v[18:19], v[160:161]
	v_pk_mul_f32 v[24:25], v[30:31], v[122:123] op_sel_hi:[1,0]
	v_pk_mul_f32 v[26:27], v[28:29], v[122:123] op_sel_hi:[1,0]
	v_pk_mul_f32 v[30:31], v[60:61], v[122:123] op_sel_hi:[1,0]
	v_pk_mul_f32 v[28:29], v[38:39], v[122:123] op_sel_hi:[1,0]
	v_pk_mul_f32 v[36:37], v[36:37], v[122:123] op_sel_hi:[1,0]
	v_pk_mul_f32 v[34:35], v[34:35], v[122:123] op_sel_hi:[1,0]
	v_pk_mul_f32 v[38:39], v[118:119], v[122:123] op_sel_hi:[1,0]
	v_pk_mul_f32 v[60:61], v[62:63], v[122:123] op_sel_hi:[1,0]
	ds_bpermute_b32 v62, v67, v65
	s_waitcnt lgkmcnt(0)
	v_add_f32_e32 v62, v65, v62
	ds_bpermute_b32 v63, v69, v62
	s_waitcnt lgkmcnt(0)
	v_add_f32_e32 v62, v62, v63
	ds_bpermute_b32 v63, v71, v62
	s_waitcnt lgkmcnt(0)
	v_add_f32_e32 v62, v62, v63
	ds_bpermute_b32 v63, v73, v62
	s_waitcnt lgkmcnt(0)
	v_add_f32_e32 v62, v62, v63
	ds_bpermute_b32 v63, v123, v62
	s_waitcnt lgkmcnt(0)
	v_add_f32_e32 v62, v62, v63
	ds_bpermute_b32 v63, v124, v62
	s_waitcnt lgkmcnt(0)
	v_add_f32_e32 v65, v62, v63
	v_fmamk_f32 v45, v65, 0xba800000, v45
	v_fmac_f32_e32 v44, 0xba800000, v65
	v_fmamk_f32 v115, v65, 0xba800000, v115
	v_fmac_f32_e32 v114, 0xba800000, v65
	v_pk_mul_f32 v[62:63], v[114:115], v[114:115]
	v_pk_mul_f32 v[118:119], v[44:45], v[44:45]
	v_fmamk_f32 v43, v65, 0xba800000, v43
	v_pk_mov_b32 v[126:127], v[118:119], v[62:63] op_sel:[1,0]
	v_mov_b32_e32 v119, v63
	v_pk_add_f32 v[62:63], v[126:127], v[118:119]
	v_fmac_f32_e32 v42, 0xba800000, v65
	v_fmamk_f32 v113, v65, 0xba800000, v113
	v_fmac_f32_e32 v112, 0xba800000, v65
	v_pk_add_f32 v[62:63], v[62:63], v[62:63] op_sel_hi:[0,1]
	v_pk_mul_f32 v[118:119], v[112:113], v[112:113]
	v_pk_mul_f32 v[126:127], v[42:43], v[42:43]
	v_fmac_f32_e32 v108, 0xba800000, v65
	v_pk_mov_b32 v[128:129], v[126:127], v[118:119] op_sel:[1,0]
	v_mov_b32_e32 v127, v119
	v_fmamk_f32 v109, v65, 0xba800000, v109
	v_fmac_f32_e32 v110, 0xba800000, v65
	v_mul_f32_e32 v62, v108, v108
	v_pk_add_f32 v[118:119], v[128:129], v[126:127]
	v_fmamk_f32 v111, v65, 0xba800000, v111
	v_pk_fma_f32 v[126:127], v[108:109], v[108:109], v[62:63] op_sel_hi:[1,1,0]
	v_mul_f32_e32 v62, v110, v110
	v_pk_add_f32 v[118:119], v[118:119], v[118:119] op_sel_hi:[0,1]
	v_pk_fma_f32 v[128:129], v[110:111], v[110:111], v[62:63] op_sel_hi:[1,1,0]
	v_fmamk_f32 v107, v65, 0xba800000, v107
	v_fmac_f32_e32 v106, 0xba800000, v65
	v_fmamk_f32 v105, v65, 0xba800000, v105
	v_fmac_f32_e32 v104, 0xba800000, v65
	v_mul_f32_e32 v126, v104, v104
	v_mul_f32_e32 v128, v105, v105
	v_mul_f32_e32 v62, v106, v106
	v_pk_fma_f32 v[8:9], v[8:9], v[26:27], v[16:17]
	v_pk_fma_f32 v[10:11], v[10:11], v[24:25], v[18:19]
	flat_store_dwordx4 v[32:33], v[8:11] sc1
	v_mov_b64_e32 v[16:17], v[162:163]
	v_mov_b64_e32 v[18:19], v[164:165]
	v_mov_b64_e32 v[24:25], v[166:167]
	v_mov_b64_e32 v[26:27], v[168:169]
	v_mul_f32_e32 v118, v107, v107
	v_pk_add_f32 v[126:127], v[126:127], v[128:129]
	v_pk_add_f32 v[62:63], v[62:63], v[118:119]
	v_pk_fma_f32 v[28:29], v[16:17], v[28:29], v[24:25]
	v_pk_fma_f32 v[30:31], v[18:19], v[30:31], v[26:27]
	flat_store_dwordx4 v[32:33], v[28:31] offset:1024 sc1
	v_mov_b64_e32 v[16:17], v[170:171]
	v_mov_b64_e32 v[18:19], v[172:173]
	v_mov_b64_e32 v[24:25], v[174:175]
	v_mov_b64_e32 v[26:27], v[176:177]
	v_pk_add_f32 v[62:63], v[126:127], v[62:63]
	v_pk_fma_f32 v[24:25], v[16:17], v[34:35], v[24:25]
	v_pk_fma_f32 v[26:27], v[18:19], v[36:37], v[26:27]
	flat_store_dwordx4 v[32:33], v[24:27] offset:2048 sc1
	v_mov_b64_e32 v[16:17], v[178:179]
	v_mov_b64_e32 v[18:19], v[180:181]
	v_mov_b64_e32 v[34:35], v[182:183]
	v_mov_b64_e32 v[36:37], v[184:185]
	v_mov_b32_e32 v118, v62
	v_pk_fma_f32 v[16:17], v[16:17], v[60:61], v[34:35]
	v_pk_fma_f32 v[18:19], v[18:19], v[38:39], v[36:37]
	flat_store_dwordx4 v[32:33], v[16:19] offset:3072 sc1
	ds_bpermute_b32 v32, v67, v125
	s_waitcnt lgkmcnt(0)
	v_add_f32_e32 v32, v125, v32
	ds_bpermute_b32 v33, v69, v32
	s_waitcnt lgkmcnt(0)
	v_add_f32_e32 v32, v32, v33
	ds_bpermute_b32 v33, v71, v32
	s_waitcnt lgkmcnt(0)
	v_add_f32_e32 v32, v32, v33
	ds_bpermute_b32 v33, v73, v32
	s_waitcnt lgkmcnt(0)
	v_add_f32_e32 v32, v32, v33
	ds_bpermute_b32 v33, v123, v32
	s_waitcnt lgkmcnt(0)
	v_add_f32_e32 v32, v32, v33
	ds_bpermute_b32 v33, v124, v32
	s_waitcnt lgkmcnt(0)
	v_add_f32_e32 v60, v32, v33
	v_fmamk_f32 v51, v60, 0xba800000, v51
	v_fmac_f32_e32 v50, 0xba800000, v60
	v_fmamk_f32 v53, v60, 0xba800000, v53
	v_fmac_f32_e32 v52, 0xba800000, v60
	v_pk_mul_f32 v[32:33], v[52:53], v[52:53]
	v_pk_mul_f32 v[34:35], v[50:51], v[50:51]
	v_fmamk_f32 v57, v60, 0xba800000, v57
	v_pk_mov_b32 v[36:37], v[34:35], v[32:33] op_sel:[1,0]
	v_mov_b32_e32 v35, v33
	v_pk_add_f32 v[32:33], v[36:37], v[34:35]
	v_fmac_f32_e32 v56, 0xba800000, v60
	v_fmamk_f32 v59, v60, 0xba800000, v59
	v_fmac_f32_e32 v58, 0xba800000, v60
	v_pk_add_f32 v[32:33], v[32:33], v[32:33] op_sel_hi:[0,1]
	v_pk_mul_f32 v[34:35], v[58:59], v[58:59]
	v_pk_mul_f32 v[36:37], v[56:57], v[56:57]
	v_fmac_f32_e32 v54, 0xba800000, v60
	v_pk_mov_b32 v[38:39], v[36:37], v[34:35] op_sel:[1,0]
	v_mov_b32_e32 v37, v35
	v_fmamk_f32 v55, v60, 0xba800000, v55
	v_fmac_f32_e32 v116, 0xba800000, v60
	v_mul_f32_e32 v32, v54, v54
	v_pk_add_f32 v[34:35], v[38:39], v[36:37]
	v_fmamk_f32 v117, v60, 0xba800000, v117
	v_pk_fma_f32 v[36:37], v[54:55], v[54:55], v[32:33] op_sel_hi:[1,1,0]
	v_mul_f32_e32 v32, v116, v116
	v_pk_add_f32 v[34:35], v[34:35], v[34:35] op_sel_hi:[0,1]
	v_pk_fma_f32 v[38:39], v[116:117], v[116:117], v[32:33] op_sel_hi:[1,1,0]
	v_fmamk_f32 v49, v60, 0xba800000, v49
	v_fmac_f32_e32 v48, 0xba800000, v60
	v_fmamk_f32 v47, v60, 0xba800000, v47
	v_fmac_f32_e32 v46, 0xba800000, v60
	v_mul_f32_e32 v36, v46, v46
	v_mul_f32_e32 v38, v47, v47
	v_mul_f32_e32 v32, v48, v48
	v_mul_f32_e32 v34, v49, v49
	v_pk_add_f32 v[36:37], v[36:37], v[38:39]
	v_pk_add_f32 v[32:33], v[32:33], v[34:35]
	s_nop 0
	v_pk_add_f32 v[60:61], v[36:37], v[32:33]
	v_mov_b64_e32 v[32:33], v[154:155]
	v_mov_b64_e32 v[34:35], v[156:157]
	v_mov_b64_e32 v[36:37], v[158:159]
	v_mov_b64_e32 v[38:39], v[160:161]
	v_mov_b32_e32 v119, v60
	v_mov_b32_e32 v60, v63
	v_pk_add_f32 v[60:61], v[118:119], v[60:61]
	ds_bpermute_b32 v63, v67, v61
	ds_bpermute_b32 v62, v67, v60
	s_waitcnt lgkmcnt(0)
	v_pk_add_f32 v[60:61], v[60:61], v[62:63]
	ds_bpermute_b32 v63, v69, v61
	ds_bpermute_b32 v62, v69, v60
	s_waitcnt lgkmcnt(0)
	v_pk_add_f32 v[60:61], v[60:61], v[62:63]
	ds_bpermute_b32 v63, v71, v61
	ds_bpermute_b32 v62, v71, v60
	s_waitcnt lgkmcnt(0)
	v_pk_add_f32 v[60:61], v[60:61], v[62:63]
	ds_bpermute_b32 v63, v73, v61
	ds_bpermute_b32 v62, v73, v60
	s_waitcnt lgkmcnt(0)
	v_pk_add_f32 v[60:61], v[60:61], v[62:63]
	ds_bpermute_b32 v63, v123, v61
	ds_bpermute_b32 v62, v123, v60
	s_waitcnt lgkmcnt(0)
	v_pk_add_f32 v[60:61], v[60:61], v[62:63]
	ds_bpermute_b32 v63, v124, v61
	ds_bpermute_b32 v62, v124, v60
	s_waitcnt lgkmcnt(0)
	v_pk_add_f32 v[60:61], v[60:61], v[62:63]
	s_nop 0
	v_pk_fma_f32 v[118:119], v[60:61], s[2:3], v[120:121] op_sel_hi:[1,0,0]
	s_nop 0
	v_mul_f32_e32 v60, 0x4b800000, v119
	v_cmp_gt_f32_e64 s[8:9], s68, v119
	v_cmp_gt_f32_e32 vcc, s68, v118
	s_nop 0
	v_cndmask_b32_e64 v60, v119, v60, s[8:9]
	v_rsq_f32_e32 v60, v60
	s_nop 0
	v_mul_f32_e32 v61, 0x45800000, v60
	v_cndmask_b32_e64 v120, v60, v61, s[8:9]
	v_pk_mul_f32 v[52:53], v[52:53], v[120:121] op_sel_hi:[1,0]
	v_pk_mul_f32 v[50:51], v[50:51], v[120:121] op_sel_hi:[1,0]
	v_pk_mul_f32 v[46:47], v[46:47], v[120:121] op_sel_hi:[1,0]
	v_pk_fma_f32 v[60:61], v[32:33], v[50:51], v[36:37]
	v_pk_fma_f32 v[62:63], v[34:35], v[52:53], v[38:39]
	flat_store_dwordx4 v[40:41], v[60:63] sc1
	v_mov_b64_e32 v[32:33], v[162:163]
	v_mov_b64_e32 v[34:35], v[164:165]
	v_mov_b64_e32 v[36:37], v[166:167]
	v_mov_b64_e32 v[38:39], v[168:169]
	v_pk_mul_f32 v[50:51], v[58:59], v[120:121] op_sel_hi:[1,0]
	v_pk_mul_f32 v[52:53], v[56:57], v[120:121] op_sel_hi:[1,0]
	v_pk_fma_f32 v[58:59], v[34:35], v[50:51], v[38:39]
	v_pk_fma_f32 v[56:57], v[32:33], v[52:53], v[36:37]
	flat_store_dwordx4 v[40:41], v[56:59] offset:1024 sc1
	v_mov_b64_e32 v[32:33], v[170:171]
	v_mov_b64_e32 v[34:35], v[172:173]
	v_mov_b64_e32 v[36:37], v[174:175]
	v_mov_b64_e32 v[38:39], v[176:177]
	v_pk_mul_f32 v[50:51], v[116:117], v[120:121] op_sel_hi:[1,0]
	v_pk_mul_f32 v[52:53], v[54:55], v[120:121] op_sel_hi:[1,0]
	v_pk_fma_f32 v[54:55], v[34:35], v[50:51], v[38:39]
	v_pk_fma_f32 v[52:53], v[32:33], v[52:53], v[36:37]
	flat_store_dwordx4 v[40:41], v[52:55] offset:2048 sc1
	v_mov_b64_e32 v[32:33], v[178:179]
	v_mov_b64_e32 v[34:35], v[180:181]
	v_mov_b64_e32 v[36:37], v[182:183]
	v_mov_b64_e32 v[38:39], v[184:185]
	v_pk_mul_f32 v[50:51], v[48:49], v[120:121] op_sel_hi:[1,0]
	v_pk_fma_f32 v[48:49], v[32:33], v[46:47], v[36:37]
	v_mul_f32_e32 v32, 0x4b800000, v118
	v_cndmask_b32_e32 v32, v118, v32, vcc
	v_rsq_f32_e32 v32, v32
	v_pk_fma_f32 v[50:51], v[34:35], v[50:51], v[38:39]
	flat_store_dwordx4 v[40:41], v[48:51] offset:3072 sc1
	v_mul_f32_e32 v33, 0x45800000, v32
	v_cndmask_b32_e32 v116, v32, v33, vcc
	v_mov_b64_e32 v[32:33], v[154:155]
	v_mov_b64_e32 v[34:35], v[156:157]
	v_mov_b64_e32 v[36:37], v[158:159]
	v_mov_b64_e32 v[38:39], v[160:161]
	v_pk_mul_f32 v[40:41], v[114:115], v[116:117] op_sel_hi:[1,0]
	v_pk_mul_f32 v[44:45], v[44:45], v[116:117] op_sel_hi:[1,0]
	v_pk_mul_f32 v[112:113], v[112:113], v[116:117] op_sel_hi:[1,0]
	v_pk_mul_f32 v[110:111], v[110:111], v[116:117] op_sel_hi:[1,0]
	v_pk_mul_f32 v[108:109], v[108:109], v[116:117] op_sel_hi:[1,0]
	s_andn2_b64 vcc, exec, s[4:5]
	v_pk_fma_f32 v[44:45], v[32:33], v[44:45], v[36:37]
	v_pk_fma_f32 v[46:47], v[34:35], v[40:41], v[38:39]
	flat_store_dwordx4 v[102:103], v[44:47] sc1
	v_mov_b64_e32 v[32:33], v[162:163]
	v_mov_b64_e32 v[34:35], v[164:165]
	v_mov_b64_e32 v[36:37], v[166:167]
	v_mov_b64_e32 v[38:39], v[168:169]
	v_pk_mul_f32 v[40:41], v[42:43], v[116:117] op_sel_hi:[1,0]
	v_pk_fma_f32 v[42:43], v[34:35], v[112:113], v[38:39]
	v_pk_fma_f32 v[40:41], v[32:33], v[40:41], v[36:37]
	flat_store_dwordx4 v[102:103], v[40:43] offset:1024 sc1
	v_mov_b64_e32 v[32:33], v[170:171]
	v_mov_b64_e32 v[34:35], v[172:173]
	v_mov_b64_e32 v[36:37], v[174:175]
	v_mov_b64_e32 v[38:39], v[176:177]
	v_pk_fma_f32 v[36:37], v[32:33], v[108:109], v[36:37]
	v_pk_fma_f32 v[38:39], v[34:35], v[110:111], v[38:39]
	flat_store_dwordx4 v[102:103], v[36:39] offset:2048 sc1
	v_pk_mul_f32 v[108:109], v[106:107], v[116:117] op_sel_hi:[1,0]
	v_pk_mul_f32 v[110:111], v[104:105], v[116:117] op_sel_hi:[1,0]
	v_mov_b64_e32 v[32:33], v[178:179]
	v_mov_b64_e32 v[34:35], v[180:181]
	v_mov_b64_e32 v[104:105], v[182:183]
	v_mov_b64_e32 v[106:107], v[184:185]
	v_pk_fma_f32 v[32:33], v[32:33], v[110:111], v[104:105]
	v_pk_fma_f32 v[34:35], v[34:35], v[108:109], v[106:107]
	flat_store_dwordx4 v[102:103], v[32:35] offset:3072 sc1
	s_cbranch_vccnz .LBB0_50
	v_mad_u64_u32 v[104:105], s[4:5], v88, s7, 0
	v_mad_u64_u32 v[102:103], s[4:5], v92, s7, 0
	v_mad_i32_i24 v105, v89, s7, v105
	v_mad_i32_i24 v103, v93, s7, v103
	v_mad_u64_u32 v[92:93], s[4:5], v98, s7, 0
	v_mad_u64_u32 v[88:89], s[4:5], v100, s7, 0
	v_mad_i32_i24 v93, v99, s7, v93
	v_lshl_add_u64 v[98:99], s[60:61], 0, v[104:105]
	s_mov_b64 s[4:5], 0x6000
	s_mov_b64 s[8:9], 0x7000
	v_mad_i32_i24 v89, v101, s7, v89
	v_lshl_add_u64 v[100:101], v[98:99], 0, s[4:5]
	v_lshl_add_u64 v[98:99], v[98:99], 0, s[8:9]
	v_lshlrev_b32_e32 v152, 2, v66
	v_lshl_add_u64 v[104:105], v[100:101], 0, v[152:153]
	v_lshl_add_u64 v[108:109], v[98:99], 0, v[152:153]
	global_load_dwordx4 v[186:189], v[104:105], off offset:1024
	global_load_dwordx4 v[190:193], v[104:105], off offset:2048
	global_load_dwordx4 v[194:197], v[104:105], off offset:3072
	flat_load_dwordx4 v[104:107], v[104:105]
	s_nop 0
	global_load_dwordx4 v[198:201], v[108:109], off offset:1024
	global_load_dwordx4 v[202:205], v[108:109], off offset:2048
	global_load_dwordx4 v[224:227], v[108:109], off offset:3072
	flat_load_dwordx4 v[108:111], v[108:109]
	s_waitcnt vmcnt(0) lgkmcnt(0)
	v_pk_add_f32 v[110:111], v[110:111], 1.0 op_sel_hi:[1,0]
	v_pk_add_f32 v[108:109], v[108:109], 1.0 op_sel_hi:[1,0]
	v_pk_fma_f32 v[22:23], v[22:23], v[110:111], v[106:107]
	v_pk_fma_f32 v[20:21], v[20:21], v[108:109], v[104:105]
	s_nop 0
	v_cvt_pk_bf16_f32 v20, v20, v21
	v_cvt_pk_bf16_f32 v21, v22, v23
	flat_store_dwordx2 v[84:85], v[20:21] sc1
	v_lshlrev_b32_e32 v20, 2, v68
	v_mov_b32_e32 v21, v153
	v_lshl_add_u64 v[22:23], v[100:101], 0, v[20:21]
	v_mov_b64_e32 v[104:105], v[186:187]
	v_mov_b64_e32 v[106:107], v[188:189]
	v_lshl_add_u64 v[22:23], v[98:99], 0, v[20:21]
	v_mov_b64_e32 v[108:109], v[198:199]
	v_mov_b64_e32 v[110:111], v[200:201]
	v_pk_add_f32 v[22:23], v[110:111], 1.0 op_sel_hi:[1,0]
	v_pk_add_f32 v[108:109], v[108:109], 1.0 op_sel_hi:[1,0]
	v_pk_fma_f32 v[14:15], v[14:15], v[22:23], v[106:107]
	v_pk_fma_f32 v[12:13], v[12:13], v[108:109], v[104:105]
	s_nop 0
	v_cvt_pk_bf16_f32 v12, v12, v13
	v_cvt_pk_bf16_f32 v13, v14, v15
	flat_store_dwordx2 v[84:85], v[12:13] offset:512 sc1
	v_lshlrev_b32_e32 v12, 2, v70
	v_mov_b32_e32 v13, v153
	v_lshl_add_u64 v[14:15], v[100:101], 0, v[12:13]
	v_mov_b64_e32 v[104:105], v[190:191]
	v_mov_b64_e32 v[106:107], v[192:193]
	v_lshl_add_u64 v[14:15], v[98:99], 0, v[12:13]
	v_mov_b64_e32 v[108:109], v[202:203]
	v_mov_b64_e32 v[110:111], v[204:205]
	v_pk_add_f32 v[14:15], v[110:111], 1.0 op_sel_hi:[1,0]
	v_pk_add_f32 v[22:23], v[108:109], 1.0 op_sel_hi:[1,0]
	v_pk_fma_f32 v[6:7], v[6:7], v[14:15], v[106:107]
	v_pk_fma_f32 v[4:5], v[4:5], v[22:23], v[104:105]
	s_nop 0
	v_cvt_pk_bf16_f32 v4, v4, v5
	v_cvt_pk_bf16_f32 v5, v6, v7
	flat_store_dwordx2 v[84:85], v[4:5] offset:1024 sc1
	v_lshlrev_b32_e32 v4, 2, v72
	v_mov_b32_e32 v5, v153
	v_lshl_add_u64 v[6:7], v[100:101], 0, v[4:5]
	v_mov_b64_e32 v[104:105], v[194:195]
	v_mov_b64_e32 v[106:107], v[196:197]
	v_lshl_add_u64 v[6:7], v[98:99], 0, v[4:5]
	v_mov_b64_e32 v[98:99], v[224:225]
	v_mov_b64_e32 v[100:101], v[226:227]
	v_pk_add_f32 v[6:7], v[100:101], 1.0 op_sel_hi:[1,0]
	v_pk_add_f32 v[14:15], v[98:99], 1.0 op_sel_hi:[1,0]
	v_pk_fma_f32 v[2:3], v[2:3], v[6:7], v[106:107]
	v_pk_fma_f32 v[0:1], v[0:1], v[14:15], v[104:105]
	s_nop 0
	v_cvt_pk_bf16_f32 v0, v0, v1
	v_cvt_pk_bf16_f32 v1, v2, v3
	flat_store_dwordx2 v[84:85], v[0:1] offset:1536 sc1
	v_lshl_add_u64 v[0:1], s[60:61], 0, v[102:103]
	v_lshl_add_u64 v[2:3], v[0:1], 0, s[4:5]
	v_lshl_add_u64 v[0:1], v[0:1], 0, s[8:9]
	v_lshl_add_u64 v[6:7], v[2:3], 0, v[152:153]
	global_load_dwordx4 v[186:189], v[6:7], off offset:1024
	global_load_dwordx4 v[190:193], v[6:7], off offset:2048
	global_load_dwordx4 v[194:197], v[6:7], off offset:3072
	flat_load_dwordx4 v[98:101], v[6:7]
	v_lshl_add_u64 v[6:7], v[0:1], 0, v[152:153]
	global_load_dwordx4 v[198:201], v[6:7], off offset:1024
	global_load_dwordx4 v[202:205], v[6:7], off offset:2048
	global_load_dwordx4 v[224:227], v[6:7], off offset:3072
	flat_load_dwordx4 v[102:105], v[6:7]
	s_waitcnt vmcnt(0) lgkmcnt(0)
	v_pk_add_f32 v[6:7], v[104:105], 1.0 op_sel_hi:[1,0]
	v_pk_add_f32 v[14:15], v[102:103], 1.0 op_sel_hi:[1,0]
	v_pk_fma_f32 v[6:7], v[10:11], v[6:7], v[100:101]
	v_pk_fma_f32 v[8:9], v[8:9], v[14:15], v[98:99]
	v_lshl_add_u64 v[10:11], v[82:83], 0, v[90:91]
	v_cvt_pk_bf16_f32 v8, v8, v9
	v_cvt_pk_bf16_f32 v9, v6, v7
	flat_store_dwordx2 v[10:11], v[8:9] sc1
	v_lshl_add_u64 v[6:7], v[2:3], 0, v[20:21]
	v_lshl_add_u64 v[14:15], v[0:1], 0, v[20:21]
	v_mov_b64_e32 v[6:7], v[186:187]
	v_mov_b64_e32 v[8:9], v[188:189]
	s_nop 0
	v_mov_b64_e32 v[98:99], v[198:199]
	v_mov_b64_e32 v[100:101], v[200:201]
	v_pk_add_f32 v[14:15], v[100:101], 1.0 op_sel_hi:[1,0]
	v_pk_add_f32 v[22:23], v[98:99], 1.0 op_sel_hi:[1,0]
	v_pk_fma_f32 v[8:9], v[30:31], v[14:15], v[8:9]
	v_pk_fma_f32 v[6:7], v[28:29], v[22:23], v[6:7]
	v_lshl_add_u64 v[14:15], v[0:1], 0, v[12:13]
	v_cvt_pk_bf16_f32 v6, v6, v7
	v_cvt_pk_bf16_f32 v7, v8, v9
	flat_store_dwordx2 v[10:11], v[6:7] offset:512 sc1
	v_lshl_add_u64 v[6:7], v[2:3], 0, v[12:13]
	v_mov_b64_e32 v[6:7], v[190:191]
	v_mov_b64_e32 v[8:9], v[192:193]
	v_lshl_add_u64 v[2:3], v[2:3], 0, v[4:5]
	v_mov_b64_e32 v[28:29], v[202:203]
	v_mov_b64_e32 v[30:31], v[204:205]
	v_lshl_add_u64 v[0:1], v[0:1], 0, v[4:5]
	v_pk_add_f32 v[14:15], v[30:31], 1.0 op_sel_hi:[1,0]
	v_pk_add_f32 v[22:23], v[28:29], 1.0 op_sel_hi:[1,0]
	v_pk_fma_f32 v[8:9], v[26:27], v[14:15], v[8:9]
	v_pk_fma_f32 v[6:7], v[24:25], v[22:23], v[6:7]
	s_nop 0
	v_cvt_pk_bf16_f32 v6, v6, v7
	v_cvt_pk_bf16_f32 v7, v8, v9
	flat_store_dwordx2 v[10:11], v[6:7] offset:1024 sc1
	v_mov_b64_e32 v[6:7], v[194:195]
	v_mov_b64_e32 v[8:9], v[196:197]
	s_nop 0
	v_mov_b64_e32 v[0:1], v[224:225]
	v_mov_b64_e32 v[2:3], v[226:227]
	v_pk_add_f32 v[2:3], v[2:3], 1.0 op_sel_hi:[1,0]
	v_pk_add_f32 v[0:1], v[0:1], 1.0 op_sel_hi:[1,0]
	v_pk_fma_f32 v[2:3], v[18:19], v[2:3], v[8:9]
	v_pk_fma_f32 v[0:1], v[16:17], v[0:1], v[6:7]
	v_lshl_add_u64 v[18:19], v[82:83], 0, v[94:95]
	v_cvt_pk_bf16_f32 v0, v0, v1
	v_cvt_pk_bf16_f32 v1, v2, v3
	flat_store_dwordx2 v[10:11], v[0:1] offset:1536 sc1
	v_lshl_add_u64 v[0:1], s[60:61], 0, v[92:93]
	v_lshl_add_u64 v[2:3], v[0:1], 0, s[4:5]
	v_lshl_add_u64 v[0:1], v[0:1], 0, s[8:9]
	v_lshl_add_u64 v[6:7], v[2:3], 0, v[152:153]
	v_lshl_add_u64 v[10:11], v[0:1], 0, v[152:153]
	global_load_dwordx4 v[186:189], v[6:7], off offset:1024
	global_load_dwordx4 v[190:193], v[6:7], off offset:2048
	global_load_dwordx4 v[194:197], v[6:7], off offset:3072
	flat_load_dwordx4 v[6:9], v[6:7]
	s_nop 0
	global_load_dwordx4 v[198:201], v[10:11], off offset:1024
	global_load_dwordx4 v[202:205], v[10:11], off offset:2048
	global_load_dwordx4 v[224:227], v[10:11], off offset:3072
	flat_load_dwordx4 v[14:17], v[10:11]
	s_waitcnt vmcnt(0) lgkmcnt(0)
	v_pk_add_f32 v[10:11], v[16:17], 1.0 op_sel_hi:[1,0]
	v_pk_add_f32 v[14:15], v[14:15], 1.0 op_sel_hi:[1,0]
	v_pk_fma_f32 v[8:9], v[62:63], v[10:11], v[8:9]
	v_pk_fma_f32 v[6:7], v[60:61], v[14:15], v[6:7]
	v_lshl_add_u64 v[10:11], v[82:83], 0, v[96:97]
	v_cvt_pk_bf16_f32 v6, v6, v7
	v_cvt_pk_bf16_f32 v7, v8, v9
	flat_store_dwordx2 v[10:11], v[6:7] sc1
	v_lshl_add_u64 v[6:7], v[2:3], 0, v[20:21]
	v_lshl_add_u64 v[14:15], v[0:1], 0, v[20:21]
	v_mov_b64_e32 v[6:7], v[186:187]
	v_mov_b64_e32 v[8:9], v[188:189]
	s_nop 0
	v_mov_b64_e32 v[14:15], v[198:199]
	v_mov_b64_e32 v[16:17], v[200:201]
	v_pk_add_f32 v[16:17], v[16:17], 1.0 op_sel_hi:[1,0]
	v_pk_add_f32 v[14:15], v[14:15], 1.0 op_sel_hi:[1,0]
	v_pk_fma_f32 v[8:9], v[58:59], v[16:17], v[8:9]
	v_pk_fma_f32 v[6:7], v[56:57], v[14:15], v[6:7]
	v_lshl_add_u64 v[14:15], v[0:1], 0, v[12:13]
	v_cvt_pk_bf16_f32 v6, v6, v7
	v_cvt_pk_bf16_f32 v7, v8, v9
	flat_store_dwordx2 v[10:11], v[6:7] offset:512 sc1
	v_lshl_add_u64 v[6:7], v[2:3], 0, v[12:13]
	v_mov_b64_e32 v[6:7], v[190:191]
	v_mov_b64_e32 v[8:9], v[192:193]
	v_lshl_add_u64 v[2:3], v[2:3], 0, v[4:5]
	v_mov_b64_e32 v[14:15], v[202:203]
	v_mov_b64_e32 v[16:17], v[204:205]
	v_lshl_add_u64 v[0:1], v[0:1], 0, v[4:5]
	v_pk_add_f32 v[16:17], v[16:17], 1.0 op_sel_hi:[1,0]
	v_pk_add_f32 v[14:15], v[14:15], 1.0 op_sel_hi:[1,0]
	v_pk_fma_f32 v[8:9], v[54:55], v[16:17], v[8:9]
	v_pk_fma_f32 v[6:7], v[52:53], v[14:15], v[6:7]
	s_nop 0
	v_cvt_pk_bf16_f32 v6, v6, v7
	v_cvt_pk_bf16_f32 v7, v8, v9
	flat_store_dwordx2 v[10:11], v[6:7] offset:1024 sc1
	v_mov_b64_e32 v[6:7], v[194:195]
	v_mov_b64_e32 v[8:9], v[196:197]
	s_nop 0
	v_mov_b64_e32 v[0:1], v[224:225]
	v_mov_b64_e32 v[2:3], v[226:227]
	v_pk_add_f32 v[2:3], v[2:3], 1.0 op_sel_hi:[1,0]
	v_pk_add_f32 v[0:1], v[0:1], 1.0 op_sel_hi:[1,0]
	v_pk_fma_f32 v[2:3], v[50:51], v[2:3], v[8:9]
	v_pk_fma_f32 v[0:1], v[48:49], v[0:1], v[6:7]
	s_nop 0
	v_cvt_pk_bf16_f32 v0, v0, v1
	v_cvt_pk_bf16_f32 v1, v2, v3
	flat_store_dwordx2 v[10:11], v[0:1] offset:1536 sc1
	v_lshl_add_u64 v[0:1], s[60:61], 0, v[88:89]
	v_lshl_add_u64 v[2:3], v[0:1], 0, s[4:5]
	v_lshl_add_u64 v[0:1], v[0:1], 0, s[8:9]
	v_lshl_add_u64 v[6:7], v[2:3], 0, v[152:153]
	v_lshl_add_u64 v[10:11], v[0:1], 0, v[152:153]
	global_load_dwordx4 v[186:189], v[6:7], off offset:1024
	global_load_dwordx4 v[190:193], v[6:7], off offset:2048
	global_load_dwordx4 v[194:197], v[6:7], off offset:3072
	flat_load_dwordx4 v[6:9], v[6:7]
	s_nop 0
	global_load_dwordx4 v[198:201], v[10:11], off offset:1024
	global_load_dwordx4 v[202:205], v[10:11], off offset:2048
	global_load_dwordx4 v[224:227], v[10:11], off offset:3072
	flat_load_dwordx4 v[14:17], v[10:11]
	s_waitcnt vmcnt(0) lgkmcnt(0)
	v_pk_add_f32 v[10:11], v[16:17], 1.0 op_sel_hi:[1,0]
	v_pk_add_f32 v[14:15], v[14:15], 1.0 op_sel_hi:[1,0]
	v_pk_fma_f32 v[8:9], v[46:47], v[10:11], v[8:9]
	v_pk_fma_f32 v[6:7], v[44:45], v[14:15], v[6:7]
	v_lshl_add_u64 v[10:11], v[0:1], 0, v[20:21]
	v_cvt_pk_bf16_f32 v6, v6, v7
	v_cvt_pk_bf16_f32 v7, v8, v9
	flat_store_dwordx2 v[18:19], v[6:7] sc1
	v_lshl_add_u64 v[6:7], v[2:3], 0, v[20:21]
	v_mov_b64_e32 v[6:7], v[186:187]
	v_mov_b64_e32 v[8:9], v[188:189]
	s_nop 0
	v_mov_b64_e32 v[14:15], v[198:199]
	v_mov_b64_e32 v[16:17], v[200:201]
	v_pk_add_f32 v[10:11], v[16:17], 1.0 op_sel_hi:[1,0]
	v_pk_add_f32 v[14:15], v[14:15], 1.0 op_sel_hi:[1,0]
	v_pk_fma_f32 v[8:9], v[42:43], v[10:11], v[8:9]
	v_pk_fma_f32 v[6:7], v[40:41], v[14:15], v[6:7]
	v_lshl_add_u64 v[10:11], v[0:1], 0, v[12:13]
	v_cvt_pk_bf16_f32 v6, v6, v7
	v_cvt_pk_bf16_f32 v7, v8, v9
	flat_store_dwordx2 v[18:19], v[6:7] offset:512 sc1
	v_lshl_add_u64 v[6:7], v[2:3], 0, v[12:13]
	v_mov_b64_e32 v[6:7], v[190:191]
	v_mov_b64_e32 v[8:9], v[192:193]
	v_lshl_add_u64 v[2:3], v[2:3], 0, v[4:5]
	v_mov_b64_e32 v[10:11], v[202:203]
	v_mov_b64_e32 v[12:13], v[204:205]
	v_lshl_add_u64 v[0:1], v[0:1], 0, v[4:5]
	v_pk_add_f32 v[12:13], v[12:13], 1.0 op_sel_hi:[1,0]
	v_pk_add_f32 v[10:11], v[10:11], 1.0 op_sel_hi:[1,0]
	v_pk_fma_f32 v[8:9], v[38:39], v[12:13], v[8:9]
	v_pk_fma_f32 v[6:7], v[36:37], v[10:11], v[6:7]
	s_nop 0
	v_cvt_pk_bf16_f32 v6, v6, v7
	v_cvt_pk_bf16_f32 v7, v8, v9
	flat_store_dwordx2 v[18:19], v[6:7] offset:1024 sc1
	v_mov_b64_e32 v[6:7], v[194:195]
	v_mov_b64_e32 v[8:9], v[196:197]
	s_nop 0
	v_mov_b64_e32 v[0:1], v[224:225]
	v_mov_b64_e32 v[2:3], v[226:227]
	v_pk_add_f32 v[2:3], v[2:3], 1.0 op_sel_hi:[1,0]
	v_pk_add_f32 v[0:1], v[0:1], 1.0 op_sel_hi:[1,0]
	v_pk_fma_f32 v[2:3], v[34:35], v[2:3], v[8:9]
	v_pk_fma_f32 v[0:1], v[32:33], v[0:1], v[6:7]
	s_nop 0
	v_cvt_pk_bf16_f32 v0, v0, v1
	v_cvt_pk_bf16_f32 v1, v2, v3
	flat_store_dwordx2 v[18:19], v[0:1] offset:1536 sc1
	s_branch .LBB0_50

.LBB0_212:
	s_waitcnt vmcnt(0) lgkmcnt(0)
	v_lshlrev_b32_e32 v228, 16, v202
	v_and_b32_e32 v229, 0xffff0000, v202
	v_lshlrev_b32_e32 v202, 16, v203
	v_and_b32_e32 v203, 0xffff0000, v203
	v_lshlrev_b32_e32 v230, 16, v204
	v_and_b32_e32 v231, 0xffff0000, v204
	v_lshlrev_b32_e32 v204, 16, v205
	v_and_b32_e32 v205, 0xffff0000, v205
	v_pk_mul_f32 v[94:95], v[94:95], 0.5 op_sel_hi:[1,0]
	v_pk_mul_f32 v[92:93], v[92:93], 0.5 op_sel_hi:[1,0]
	v_pk_add_f32 v[202:203], v[202:203], v[204:205]
	v_pk_add_f32 v[204:205], v[228:229], v[230:231]
	v_pk_mul_f32 v[94:95], v[94:95], v[202:203]
	v_pk_mul_f32 v[92:93], v[92:93], v[204:205]
	v_pk_fma_f32 v[90:91], v[90:91], s[42:43], v[94:95] op_sel_hi:[1,0,1]
	v_pk_fma_f32 v[88:89], v[88:89], s[42:43], v[92:93] op_sel_hi:[1,0,1]
	v_add_f32_e32 v93, v90, v91
	v_add_f32_e32 v92, v88, v89
	v_add_f32_e32 v92, v92, v93
	v_add_f32_e32 v143, 0, v92
	v_lshlrev_b32_e32 v92, 16, v198
	v_and_b32_e32 v93, 0xffff0000, v198
	v_lshlrev_b32_e32 v94, 16, v199
	v_and_b32_e32 v95, 0xffff0000, v199
	v_lshlrev_b32_e32 v198, 16, v200
	v_and_b32_e32 v199, 0xffff0000, v200
	v_lshlrev_b32_e32 v200, 16, v201
	v_and_b32_e32 v201, 0xffff0000, v201
	v_pk_mul_f32 v[86:87], v[86:87], 0.5 op_sel_hi:[1,0]
	v_pk_mul_f32 v[84:85], v[84:85], 0.5 op_sel_hi:[1,0]
	v_pk_add_f32 v[94:95], v[94:95], v[200:201]
	v_pk_add_f32 v[92:93], v[92:93], v[198:199]
	v_pk_mul_f32 v[86:87], v[86:87], v[94:95]
	v_pk_mul_f32 v[84:85], v[84:85], v[92:93]
	v_pk_fma_f32 v[86:87], v[78:79], s[42:43], v[86:87] op_sel_hi:[1,0,1]
	v_pk_fma_f32 v[84:85], v[76:77], s[42:43], v[84:85] op_sel_hi:[1,0,1]
	v_add_f32_e32 v77, v86, v87
	v_add_f32_e32 v76, v84, v85
	v_add_f32_e32 v76, v76, v77
	v_add_f32_e32 v143, v143, v76
	v_lshlrev_b32_e32 v76, 16, v194
	v_and_b32_e32 v77, 0xffff0000, v194
	v_lshlrev_b32_e32 v78, 16, v195
	v_and_b32_e32 v79, 0xffff0000, v195
	v_lshlrev_b32_e32 v92, 16, v196
	v_and_b32_e32 v93, 0xffff0000, v196
	v_lshlrev_b32_e32 v94, 16, v197
	v_and_b32_e32 v95, 0xffff0000, v197
	v_pk_mul_f32 v[82:83], v[82:83], 0.5 op_sel_hi:[1,0]
	v_pk_mul_f32 v[80:81], v[80:81], 0.5 op_sel_hi:[1,0]
	v_pk_add_f32 v[78:79], v[78:79], v[94:95]
	v_pk_add_f32 v[76:77], v[76:77], v[92:93]
	v_pk_mul_f32 v[78:79], v[82:83], v[78:79]
	v_pk_mul_f32 v[76:77], v[80:81], v[76:77]
	v_pk_fma_f32 v[82:83], v[74:75], s[42:43], v[78:79] op_sel_hi:[1,0,1]
	v_pk_fma_f32 v[80:81], v[72:73], s[42:43], v[76:77] op_sel_hi:[1,0,1]
	v_lshlrev_b32_e32 v72, 16, v188
	v_and_b32_e32 v73, 0xffff0000, v188
	v_lshlrev_b32_e32 v74, 16, v189
	v_and_b32_e32 v75, 0xffff0000, v189
	v_lshlrev_b32_e32 v76, 16, v190
	v_and_b32_e32 v77, 0xffff0000, v190
	v_lshlrev_b32_e32 v78, 16, v191
	v_and_b32_e32 v79, 0xffff0000, v191
	v_pk_mul_f32 v[70:71], v[70:71], 0.5 op_sel_hi:[1,0]
	v_pk_mul_f32 v[68:69], v[68:69], 0.5 op_sel_hi:[1,0]
	v_pk_add_f32 v[74:75], v[74:75], v[78:79]
	v_pk_add_f32 v[72:73], v[72:73], v[76:77]
	v_pk_mul_f32 v[70:71], v[70:71], v[74:75]
	v_pk_mul_f32 v[68:69], v[68:69], v[72:73]
	v_pk_fma_f32 v[188:189], v[66:67], s[42:43], v[70:71] op_sel_hi:[1,0,1]
	v_pk_fma_f32 v[190:191], v[64:65], s[42:43], v[68:69] op_sel_hi:[1,0,1]
	v_add_f32_e32 v65, v188, v189
	v_add_f32_e32 v64, v190, v191
	v_add_f32_e32 v64, v64, v65
	v_add_f32_e32 v72, 0, v64
	v_lshlrev_b32_e32 v64, 16, v184
	v_and_b32_e32 v65, 0xffff0000, v184
	v_lshlrev_b32_e32 v66, 16, v185
	v_and_b32_e32 v67, 0xffff0000, v185
	v_lshlrev_b32_e32 v68, 16, v186
	v_and_b32_e32 v69, 0xffff0000, v186
	v_lshlrev_b32_e32 v70, 16, v187
	v_and_b32_e32 v71, 0xffff0000, v187
	v_pk_mul_f32 v[62:63], v[62:63], 0.5 op_sel_hi:[1,0]
	v_pk_mul_f32 v[60:61], v[60:61], 0.5 op_sel_hi:[1,0]
	v_pk_add_f32 v[66:67], v[66:67], v[70:71]
	v_pk_add_f32 v[64:65], v[64:65], v[68:69]
	v_pk_mul_f32 v[62:63], v[62:63], v[66:67]
	v_pk_mul_f32 v[60:61], v[60:61], v[64:65]
	v_pk_fma_f32 v[186:187], v[54:55], s[42:43], v[62:63] op_sel_hi:[1,0,1]
	v_pk_fma_f32 v[184:185], v[52:53], s[42:43], v[60:61] op_sel_hi:[1,0,1]
	v_add_f32_e32 v53, v186, v187
	v_add_f32_e32 v52, v184, v185
	v_add_f32_e32 v52, v52, v53
	v_add_f32_e32 v64, v72, v52
	v_lshlrev_b32_e32 v52, 16, v180
	v_and_b32_e32 v53, 0xffff0000, v180
	v_lshlrev_b32_e32 v54, 16, v181
	v_and_b32_e32 v55, 0xffff0000, v181
	v_lshlrev_b32_e32 v60, 16, v182
	v_and_b32_e32 v61, 0xffff0000, v182
	v_lshlrev_b32_e32 v62, 16, v183
	v_and_b32_e32 v63, 0xffff0000, v183
	v_pk_mul_f32 v[58:59], v[58:59], 0.5 op_sel_hi:[1,0]
	v_pk_mul_f32 v[56:57], v[56:57], 0.5 op_sel_hi:[1,0]
	v_pk_add_f32 v[54:55], v[54:55], v[62:63]
	v_pk_add_f32 v[52:53], v[52:53], v[60:61]
	v_pk_mul_f32 v[54:55], v[58:59], v[54:55]
	v_pk_mul_f32 v[52:53], v[56:57], v[52:53]
	v_pk_fma_f32 v[50:51], v[50:51], s[42:43], v[54:55] op_sel_hi:[1,0,1]
	v_pk_fma_f32 v[48:49], v[48:49], s[42:43], v[52:53] op_sel_hi:[1,0,1]
	v_add_f32_e32 v53, v50, v51
	v_add_f32_e32 v52, v48, v49
	v_add_f32_e32 v52, v52, v53
	v_add_f32_e32 v60, v64, v52
	v_lshlrev_b32_e32 v52, 16, v176
	v_and_b32_e32 v53, 0xffff0000, v176
	v_lshlrev_b32_e32 v54, 16, v177
	v_and_b32_e32 v55, 0xffff0000, v177
	v_lshlrev_b32_e32 v56, 16, v178
	v_and_b32_e32 v57, 0xffff0000, v178
	v_lshlrev_b32_e32 v58, 16, v179
	v_and_b32_e32 v59, 0xffff0000, v179
	v_pk_mul_f32 v[46:47], v[46:47], 0.5 op_sel_hi:[1,0]
	v_pk_mul_f32 v[44:45], v[44:45], 0.5 op_sel_hi:[1,0]
	v_pk_add_f32 v[54:55], v[54:55], v[58:59]
	v_pk_add_f32 v[52:53], v[52:53], v[56:57]
	v_pk_mul_f32 v[46:47], v[46:47], v[54:55]
	v_pk_mul_f32 v[44:45], v[44:45], v[52:53]
	v_pk_fma_f32 v[178:179], v[42:43], s[42:43], v[46:47] op_sel_hi:[1,0,1]
	v_pk_fma_f32 v[176:177], v[40:41], s[42:43], v[44:45] op_sel_hi:[1,0,1]
	v_add_f32_e32 v41, v178, v179
	v_add_f32_e32 v40, v176, v177
	v_add_f32_e32 v40, v40, v41
	v_add_f32_e32 v42, v60, v40
	ds_bpermute_b32 v43, v99, v42
	v_add_f32_e32 v92, v80, v81
	v_add_f32_e32 v93, v82, v83
	v_add_f32_e32 v40, v92, v93
	v_add_f32_e32 v52, v143, v40
	s_waitcnt lgkmcnt(0)
	v_add_f32_e32 v46, v42, v43
	ds_bpermute_b32 v47, v101, v46
	v_lshlrev_b32_e32 v40, 16, v172
	v_and_b32_e32 v41, 0xffff0000, v172
	v_lshlrev_b32_e32 v44, 16, v174
	v_and_b32_e32 v45, 0xffff0000, v174
	s_waitcnt lgkmcnt(0)
	v_add_f32_e32 v53, v46, v47
	ds_bpermute_b32 v54, v103, v53
	v_pk_mul_f32 v[36:37], v[36:37], 0.5 op_sel_hi:[1,0]
	v_pk_add_f32 v[40:41], v[40:41], v[44:45]
	v_lshlrev_b32_e32 v42, 16, v173
	v_pk_mul_f32 v[36:37], v[36:37], v[40:41]
	s_waitcnt lgkmcnt(0)
	v_add_f32_e32 v53, v53, v54
	ds_bpermute_b32 v54, v105, v53
	v_and_b32_e32 v43, 0xffff0000, v173
	v_lshlrev_b32_e32 v46, 16, v175
	v_and_b32_e32 v47, 0xffff0000, v175
	v_pk_mul_f32 v[38:39], v[38:39], 0.5 op_sel_hi:[1,0]
	s_waitcnt lgkmcnt(0)
	v_add_f32_e32 v40, v53, v54
	ds_bpermute_b32 v41, v225, v40
	v_pk_add_f32 v[42:43], v[42:43], v[46:47]
	v_pk_fma_f32 v[92:93], v[32:33], s[42:43], v[36:37] op_sel_hi:[1,0,1]
	v_pk_mul_f32 v[38:39], v[38:39], v[42:43]
	v_add_f32_e32 v32, v92, v93
	v_pk_fma_f32 v[94:95], v[34:35], s[42:43], v[38:39] op_sel_hi:[1,0,1]
	s_waitcnt lgkmcnt(0)
	v_add_f32_e32 v34, v40, v41
	ds_bpermute_b32 v35, v226, v34
	v_add_f32_e32 v33, v94, v95
	v_add_f32_e32 v32, v32, v33
	v_add_f32_e32 v42, v52, v32
	v_lshlrev_b64 v[32:33], 11, v[192:193]
	s_waitcnt lgkmcnt(0)
	v_add_f32_e32 v43, v34, v35
	v_fmamk_f32 v191, v43, 0xba800000, v191
	v_fmac_f32_e32 v190, 0xba800000, v43
	v_fmamk_f32 v189, v43, 0xba800000, v189
	v_fmac_f32_e32 v188, 0xba800000, v43
	v_pk_mul_f32 v[34:35], v[188:189], v[188:189]
	v_pk_mul_f32 v[36:37], v[190:191], v[190:191]
	v_fmamk_f32 v185, v43, 0xba800000, v185
	v_pk_mov_b32 v[38:39], v[36:37], v[34:35] op_sel:[1,0]
	v_mov_b32_e32 v37, v35
	v_pk_add_f32 v[34:35], v[38:39], v[36:37]
	v_fmac_f32_e32 v184, 0xba800000, v43
	v_pk_add_f32 v[34:35], v[34:35], v[34:35] op_sel_hi:[0,1]
	v_fmamk_f32 v187, v43, 0xba800000, v187
	v_fmac_f32_e32 v186, 0xba800000, v43
	ds_bpermute_b32 v34, v99, v42
	v_pk_mul_f32 v[36:37], v[186:187], v[186:187]
	v_pk_mul_f32 v[38:39], v[184:185], v[184:185]
	v_fmac_f32_e32 v48, 0xba800000, v43
	v_pk_mov_b32 v[40:41], v[38:39], v[36:37] op_sel:[1,0]
	v_mov_b32_e32 v39, v37
	v_pk_add_f32 v[36:37], v[40:41], v[38:39]
	v_fmamk_f32 v49, v43, 0xba800000, v49
	v_pk_add_f32 v[36:37], v[36:37], v[36:37] op_sel_hi:[0,1]
	s_waitcnt lgkmcnt(0)
	v_add_f32_e32 v36, v42, v34
	ds_bpermute_b32 v38, v101, v36
	v_fmac_f32_e32 v50, 0xba800000, v43
	v_mul_f32_e32 v34, v48, v48
	v_fmamk_f32 v51, v43, 0xba800000, v51
	v_fmamk_f32 v179, v43, 0xba800000, v179
	s_waitcnt lgkmcnt(0)
	v_add_f32_e32 v36, v36, v38
	ds_bpermute_b32 v42, v103, v36
	v_pk_fma_f32 v[38:39], v[48:49], v[48:49], v[34:35] op_sel_hi:[1,1,0]
	v_mul_f32_e32 v34, v50, v50
	v_pk_fma_f32 v[40:41], v[50:51], v[50:51], v[34:35] op_sel_hi:[1,1,0]
	v_fmac_f32_e32 v178, 0xba800000, v43
	s_waitcnt lgkmcnt(0)
	v_add_f32_e32 v34, v36, v42
	ds_bpermute_b32 v36, v105, v34
	v_fmamk_f32 v177, v43, 0xba800000, v177
	v_fmac_f32_e32 v176, 0xba800000, v43
	v_mul_f32_e32 v38, v176, v176
	v_mul_f32_e32 v40, v177, v177
	s_waitcnt lgkmcnt(0)
	v_add_f32_e32 v42, v34, v36
	v_mul_f32_e32 v34, v178, v178
	v_mul_f32_e32 v36, v179, v179
	v_pk_add_f32 v[38:39], v[38:39], v[40:41]
	v_pk_add_f32 v[34:35], v[34:35], v[36:37]
	ds_bpermute_b32 v43, v225, v42
	v_pk_add_f32 v[34:35], v[38:39], v[34:35]
	ds_read_b128 v[36:39], v210
	ds_read_b128 v[56:59], v210 offset:4096
	v_lshl_add_u64 v[32:33], s[56:57], 0, v[32:33]
	s_mov_b64 s[4:5], 0x1000000
	s_waitcnt lgkmcnt(0)
	v_add_f32_e32 v40, v42, v43
	ds_bpermute_b32 v41, v226, v40
	v_ashrrev_i32_e32 v136, 10, v136
	v_lshl_add_u64 v[60:61], v[32:33], 0, s[4:5]
	v_mov_b32_e32 v145, v153
	v_add_u32_e32 v136, 1, v136
	s_waitcnt lgkmcnt(0)
	v_add_f32_e32 v52, v40, v41
	v_fmamk_f32 v89, v52, 0xba800000, v89
	v_fmac_f32_e32 v88, 0xba800000, v52
	v_fmamk_f32 v91, v52, 0xba800000, v91
	v_fmac_f32_e32 v90, 0xba800000, v52
	v_pk_mul_f32 v[40:41], v[90:91], v[90:91]
	v_pk_mul_f32 v[42:43], v[88:89], v[88:89]
	v_fmamk_f32 v85, v52, 0xba800000, v85
	v_pk_mov_b32 v[44:45], v[42:43], v[40:41] op_sel:[1,0]
	v_mov_b32_e32 v43, v41
	v_pk_add_f32 v[40:41], v[44:45], v[42:43]
	v_fmac_f32_e32 v84, 0xba800000, v52
	v_fmamk_f32 v87, v52, 0xba800000, v87
	v_fmac_f32_e32 v86, 0xba800000, v52
	v_pk_add_f32 v[40:41], v[40:41], v[40:41] op_sel_hi:[0,1]
	v_pk_mul_f32 v[42:43], v[86:87], v[86:87]
	v_pk_mul_f32 v[44:45], v[84:85], v[84:85]
	v_fmac_f32_e32 v80, 0xba800000, v52
	v_pk_mov_b32 v[46:47], v[44:45], v[42:43] op_sel:[1,0]
	v_mov_b32_e32 v45, v43
	v_fmamk_f32 v81, v52, 0xba800000, v81
	v_fmac_f32_e32 v82, 0xba800000, v52
	v_mul_f32_e32 v40, v80, v80
	v_pk_add_f32 v[42:43], v[46:47], v[44:45]
	v_fmamk_f32 v83, v52, 0xba800000, v83
	v_pk_fma_f32 v[44:45], v[80:81], v[80:81], v[40:41] op_sel_hi:[1,1,0]
	v_mul_f32_e32 v40, v82, v82
	v_pk_add_f32 v[42:43], v[42:43], v[42:43] op_sel_hi:[0,1]
	v_pk_fma_f32 v[46:47], v[82:83], v[82:83], v[40:41] op_sel_hi:[1,1,0]
	v_fmamk_f32 v95, v52, 0xba800000, v95
	v_fmac_f32_e32 v94, 0xba800000, v52
	v_fmamk_f32 v93, v52, 0xba800000, v93
	v_fmac_f32_e32 v92, 0xba800000, v52
	v_mul_f32_e32 v44, v92, v92
	v_mul_f32_e32 v46, v93, v93
	v_mul_f32_e32 v40, v94, v94
	v_mul_f32_e32 v42, v95, v95
	v_pk_add_f32 v[44:45], v[44:45], v[46:47]
	v_pk_add_f32 v[40:41], v[40:41], v[42:43]
	v_mov_b32_e32 v43, v34
	v_pk_add_f32 v[40:41], v[44:45], v[40:41]
	v_mov_b32_e32 v147, v153
	v_mov_b32_e32 v42, v40
	v_mov_b32_e32 v34, v41
	v_pk_add_f32 v[34:35], v[42:43], v[34:35]
	ds_bpermute_b32 v41, v99, v35
	ds_bpermute_b32 v40, v99, v34
	v_lshl_add_u64 v[192:193], v[60:61], 0, v[144:145]
	v_cndmask_b32_e64 v136, v136, 0, s[10:11]
	v_lshl_add_u64 v[172:173], v[32:33], 0, v[146:147]
	v_lshl_add_u64 v[180:181], v[60:61], 0, v[146:147]
	s_waitcnt lgkmcnt(0)
	v_pk_add_f32 v[34:35], v[34:35], v[40:41]
	ds_bpermute_b32 v41, v101, v35
	ds_bpermute_b32 v40, v101, v34
	v_ashrrev_i32_e32 v137, 31, v136
	v_lshl_add_u64 v[136:137], v[136:137], 0, s[28:29]
	v_mad_u64_u32 v[62:63], s[4:5], v136, s7, v[110:111]
	s_waitcnt lgkmcnt(0)
	v_pk_add_f32 v[46:47], v[34:35], v[40:41]
	ds_bpermute_b32 v53, v103, v47
	ds_bpermute_b32 v52, v103, v46
	v_lshl_add_u64 v[44:45], v[170:171], 0, v[152:153]
	v_mad_i32_i24 v63, v137, s7, v63
	flat_load_dwordx4 v[40:43], v[44:45]
	flat_load_dwordx4 v[32:35], v[44:45] offset:1024
	flat_load_dwordx4 v[68:71], v[62:63]
	flat_load_dwordx4 v[64:67], v[62:63] offset:1024
	v_mov_b32_e32 v149, v153
	s_waitcnt lgkmcnt(0)
	v_pk_add_f32 v[46:47], v[46:47], v[52:53]
	ds_bpermute_b32 v53, v105, v47
	ds_bpermute_b32 v52, v105, v46
	v_mov_b32_e32 v143, v153
	s_mov_b32 s2, 0x3727c5ac
	v_lshl_add_u64 v[148:149], v[60:61], 0, v[148:149]
	v_lshl_add_u64 v[60:61], v[60:61], 0, v[142:143]
	s_waitcnt lgkmcnt(0)
	v_pk_add_f32 v[144:145], v[46:47], v[52:53]
	ds_bpermute_b32 v147, v225, v145
	ds_bpermute_b32 v146, v225, v144
	flat_load_dwordx4 v[52:55], v[44:45] offset:2048
	s_nop 0
	flat_load_dwordx4 v[44:47], v[44:45] offset:3072
	s_nop 0
	flat_load_dwordx4 v[76:79], v[62:63] offset:2048
	flat_load_dwordx4 v[72:75], v[62:63] offset:3072
	v_mov_b64_e32 v[142:143], s[2:3]
	s_mov_b32 s2, 0x3a800000
	v_pk_mul_f32 v[230:231], v[24:25], 0.5 op_sel_hi:[1,0]
	s_waitcnt lgkmcnt(0)
	v_pk_add_f32 v[62:63], v[144:145], v[146:147]
	ds_bpermute_b32 v183, v226, v63
	ds_bpermute_b32 v182, v226, v62
	flat_load_dwordx2 v[174:175], v[172:173]
	flat_load_dwordx2 v[170:171], v[172:173] offset:512
	flat_load_dwordx2 v[146:147], v[172:173] offset:1024
	flat_load_dwordx2 v[144:145], v[172:173] offset:1536
	v_pk_mul_f32 v[228:229], v[26:27], 0.5 op_sel_hi:[1,0]
	v_pk_mul_f32 v[196:197], v[28:29], 0.5 op_sel_hi:[1,0]
	v_lshlrev_b32_e32 v198, 16, v162
	s_waitcnt lgkmcnt(0)
	v_pk_add_f32 v[62:63], v[62:63], v[182:183]
	flat_load_dwordx2 v[182:183], v[180:181]
	s_nop 0
	flat_load_dwordx2 v[180:181], v[192:193]
	flat_load_dwordx2 v[172:173], v[148:149]
	s_nop 0
	flat_load_dwordx2 v[148:149], v[60:61]
	v_pk_fma_f32 v[194:195], v[62:63], s[2:3], v[142:143] op_sel_hi:[1,0,0]
	v_lshlrev_b64 v[60:61], 12, v[138:139]
	v_mul_f32_e32 v62, 0x4b800000, v195
	v_cmp_gt_f32_e32 vcc, s68, v195
	v_lshl_add_u64 v[138:139], v[112:113], 0, v[60:61]
	v_mul_f32_e32 v24, 0x4b800000, v194
	v_cndmask_b32_e32 v62, v195, v62, vcc
	v_rsq_f32_e32 v62, v62
	v_and_b32_e32 v199, 0xffff0000, v162
	v_lshlrev_b32_e32 v162, 16, v163
	v_and_b32_e32 v163, 0xffff0000, v163
	v_mul_f32_e32 v60, 0x45800000, v62
	v_cndmask_b32_e32 v192, v62, v60, vcc
	v_pk_mul_f32 v[60:61], v[190:191], v[192:193] op_sel_hi:[1,0]
	v_pk_mul_f32 v[62:63], v[188:189], v[192:193] op_sel_hi:[1,0]
	s_waitcnt vmcnt(0) lgkmcnt(0)
	v_pk_fma_f32 v[60:61], v[36:37], v[60:61], v[56:57]
	v_pk_fma_f32 v[62:63], v[38:39], v[62:63], v[58:59]
	flat_store_dwordx4 v[138:139], v[60:63] sc1
	ds_read_b128 v[36:39], v210 offset:1024
	ds_read_b128 v[56:59], v210 offset:5120
	v_pk_mul_f32 v[186:187], v[186:187], v[192:193] op_sel_hi:[1,0]
	v_pk_mul_f32 v[184:185], v[184:185], v[192:193] op_sel_hi:[1,0]
	v_pk_mul_f32 v[50:51], v[50:51], v[192:193] op_sel_hi:[1,0]
	v_pk_mul_f32 v[48:49], v[48:49], v[192:193] op_sel_hi:[1,0]
	v_pk_mul_f32 v[178:179], v[178:179], v[192:193] op_sel_hi:[1,0]
	v_pk_mul_f32 v[176:177], v[176:177], v[192:193] op_sel_hi:[1,0]
	v_cmp_gt_f32_e32 vcc, s68, v194
	v_pk_mul_f32 v[192:193], v[30:31], 0.5 op_sel_hi:[1,0]
	v_lshlrev_b32_e32 v188, 16, v166
	v_cndmask_b32_e32 v24, v194, v24, vcc
	v_rsq_f32_e32 v26, v24
	v_lshlrev_b64 v[24:25], 12, v[140:141]
	v_and_b32_e32 v189, 0xffff0000, v166
	v_lshlrev_b32_e32 v166, 16, v167
	v_and_b32_e32 v167, 0xffff0000, v167
	v_lshlrev_b32_e32 v190, 16, v168
	v_and_b32_e32 v191, 0xffff0000, v168
	v_lshlrev_b32_e32 v168, 16, v169
	v_and_b32_e32 v169, 0xffff0000, v169
	v_lshlrev_b32_e32 v200, 16, v164
	v_and_b32_e32 v201, 0xffff0000, v164
	v_lshlrev_b32_e32 v164, 16, v165
	v_and_b32_e32 v165, 0xffff0000, v165
	v_lshlrev_b32_e32 v202, 16, v158
	v_and_b32_e32 v203, 0xffff0000, v158
	v_lshlrev_b32_e32 v158, 16, v159
	v_and_b32_e32 v159, 0xffff0000, v159
	v_lshlrev_b32_e32 v204, 16, v160
	v_and_b32_e32 v205, 0xffff0000, v160
	v_lshlrev_b32_e32 v160, 16, v161
	v_and_b32_e32 v161, 0xffff0000, v161
	v_pk_add_f32 v[166:167], v[166:167], v[168:169]
	v_pk_add_f32 v[168:169], v[188:189], v[190:191]
	v_pk_mul_f32 v[22:23], v[22:23], 0.5 op_sel_hi:[1,0]
	v_pk_mul_f32 v[20:21], v[20:21], 0.5 op_sel_hi:[1,0]
	v_lshlrev_b32_e32 v232, 16, v150
	v_and_b32_e32 v233, 0xffff0000, v150
	v_lshlrev_b32_e32 v150, 16, v151
	v_and_b32_e32 v151, 0xffff0000, v151
	v_lshlrev_b32_e32 v234, 16, v156
	v_and_b32_e32 v235, 0xffff0000, v156
	v_lshlrev_b32_e32 v156, 16, v157
	v_and_b32_e32 v157, 0xffff0000, v157
	v_pk_add_f32 v[162:163], v[162:163], v[164:165]
	v_pk_add_f32 v[164:165], v[198:199], v[200:201]
	v_pk_add_f32 v[158:159], v[158:159], v[160:161]
	v_pk_add_f32 v[160:161], v[202:203], v[204:205]
	v_pk_mul_f32 v[168:169], v[196:197], v[168:169]
	v_pk_mul_f32 v[166:167], v[192:193], v[166:167]
	v_pk_mul_f32 v[18:19], v[18:19], 0.5 op_sel_hi:[1,0]
	v_pk_mul_f32 v[16:17], v[16:17], 0.5 op_sel_hi:[1,0]
	v_pk_add_f32 v[150:151], v[150:151], v[156:157]
	v_pk_add_f32 v[156:157], v[232:233], v[234:235]
	v_pk_mul_f32 v[164:165], v[20:21], v[164:165]
	v_pk_mul_f32 v[162:163], v[22:23], v[162:163]
	v_pk_mul_f32 v[160:161], v[230:231], v[160:161]
	v_pk_fma_f32 v[22:23], v[2:3], s[42:43], v[166:167] op_sel_hi:[1,0,1]
	v_pk_fma_f32 v[20:21], v[0:1], s[42:43], v[168:169] op_sel_hi:[1,0,1]
	v_pk_mul_f32 v[158:159], v[228:229], v[158:159]
	v_pk_mul_f32 v[156:157], v[16:17], v[156:157]
	v_pk_mul_f32 v[150:151], v[18:19], v[150:151]
	v_pk_fma_f32 v[18:19], v[6:7], s[42:43], v[162:163] op_sel_hi:[1,0,1]
	v_pk_fma_f32 v[16:17], v[4:5], s[42:43], v[164:165] op_sel_hi:[1,0,1]
	v_pk_fma_f32 v[4:5], v[8:9], s[42:43], v[160:161] op_sel_hi:[1,0,1]
	v_add_f32_e32 v8, v20, v21
	v_add_f32_e32 v9, v22, v23
	v_pk_fma_f32 v[6:7], v[10:11], s[42:43], v[158:159] op_sel_hi:[1,0,1]
	v_add_f32_e32 v10, v16, v17
	v_add_f32_e32 v11, v18, v19
	v_add_f32_e32 v8, v8, v9
	v_pk_fma_f32 v[2:3], v[14:15], s[42:43], v[150:151] op_sel_hi:[1,0,1]
	v_pk_fma_f32 v[0:1], v[12:13], s[42:43], v[156:157] op_sel_hi:[1,0,1]
	v_add_f32_e32 v12, v4, v5
	v_add_f32_e32 v13, v6, v7
	v_add_f32_e32 v9, v10, v11
	v_add_f32_e32 v8, 0, v8
	v_add_f32_e32 v14, v0, v1
	v_add_f32_e32 v15, v2, v3
	v_add_f32_e32 v10, v12, v13
	s_waitcnt vmcnt(1) lgkmcnt(0)
	v_pk_fma_f32 v[56:57], v[36:37], v[184:185], v[56:57]
	v_pk_fma_f32 v[58:59], v[38:39], v[186:187], v[58:59]
	flat_store_dwordx4 v[138:139], v[56:59] offset:1024 sc1
	ds_read_b128 v[36:39], v210 offset:2048
	ds_read_b128 v[184:187], v210 offset:6144
	v_add_f32_e32 v8, v8, v9
	v_add_f32_e32 v11, v14, v15
	v_add_f32_e32 v8, v8, v10
	v_add_f32_e32 v8, v8, v11
	ds_bpermute_b32 v9, v99, v8
	v_lshlrev_b32_e32 v14, 16, v171
	v_and_b32_e32 v15, 0xffff0000, v171
	s_waitcnt lgkmcnt(0)
	v_lshlrev_b32_e32 v162, 16, v182
	v_and_b32_e32 v163, 0xffff0000, v182
	v_add_f32_e32 v8, v8, v9
	ds_bpermute_b32 v9, v101, v8
	v_lshlrev_b32_e32 v164, 16, v183
	v_and_b32_e32 v165, 0xffff0000, v183
	v_lshlrev_b32_e32 v168, 16, v181
	v_and_b32_e32 v169, 0xffff0000, v181
	s_waitcnt lgkmcnt(0)
	v_add_f32_e32 v8, v8, v9
	ds_bpermute_b32 v9, v103, v8
	v_and_b32_e32 v13, 0xffff0000, v170
	v_lshlrev_b32_e32 v166, 16, v180
	v_and_b32_e32 v167, 0xffff0000, v180
	v_pk_add_f32 v[14:15], v[14:15], v[168:169]
	s_waitcnt lgkmcnt(0)
	v_add_f32_e32 v8, v8, v9
	ds_bpermute_b32 v9, v105, v8
	v_pk_mul_f32 v[70:71], v[70:71], 0.5 op_sel_hi:[1,0]
	v_pk_mul_f32 v[68:69], v[68:69], 0.5 op_sel_hi:[1,0]
	v_pk_mul_f32 v[66:67], v[66:67], 0.5 op_sel_hi:[1,0]
	v_pk_mul_f32 v[64:65], v[64:65], 0.5 op_sel_hi:[1,0]
	s_waitcnt lgkmcnt(0)
	v_add_f32_e32 v8, v8, v9
	ds_bpermute_b32 v9, v225, v8
	v_pk_mul_f32 v[66:67], v[66:67], v[14:15]
	v_lshlrev_b32_e32 v158, 16, v146
	v_and_b32_e32 v159, 0xffff0000, v146
	v_lshlrev_b32_e32 v146, 16, v147
	s_waitcnt lgkmcnt(0)
	v_add_f32_e32 v8, v8, v9
	ds_bpermute_b32 v9, v226, v8
	v_and_b32_e32 v147, 0xffff0000, v147
	v_lshlrev_b32_e32 v160, 16, v144
	v_and_b32_e32 v161, 0xffff0000, v144
	v_lshlrev_b32_e32 v144, 16, v145
	s_waitcnt lgkmcnt(0)
	v_add_f32_e32 v12, v8, v9
	v_fmamk_f32 v21, v12, 0xba800000, v21
	v_fmac_f32_e32 v20, 0xba800000, v12
	v_fmamk_f32 v23, v12, 0xba800000, v23
	v_fmac_f32_e32 v22, 0xba800000, v12
	v_fmamk_f32 v17, v12, 0xba800000, v17
	v_fmac_f32_e32 v16, 0xba800000, v12
	v_fmamk_f32 v19, v12, 0xba800000, v19
	v_fmac_f32_e32 v18, 0xba800000, v12
	v_fmamk_f32 v5, v12, 0xba800000, v5
	v_fmac_f32_e32 v4, 0xba800000, v12
	v_fmamk_f32 v7, v12, 0xba800000, v7
	v_fmac_f32_e32 v6, 0xba800000, v12
	v_fmamk_f32 v3, v12, 0xba800000, v3
	v_fmac_f32_e32 v2, 0xba800000, v12
	v_fmamk_f32 v1, v12, 0xba800000, v1
	v_fmac_f32_e32 v0, 0xba800000, v12
	v_lshlrev_b32_e32 v12, 16, v170
	v_pk_add_f32 v[12:13], v[12:13], v[166:167]
	v_and_b32_e32 v145, 0xffff0000, v145
	v_pk_mul_f32 v[64:65], v[64:65], v[12:13]
	v_lshlrev_b32_e32 v170, 16, v172
	v_and_b32_e32 v171, 0xffff0000, v172
	v_lshlrev_b32_e32 v172, 16, v173
	v_and_b32_e32 v173, 0xffff0000, v173
	v_pk_add_f32 v[158:159], v[158:159], v[170:171]
	v_pk_add_f32 v[146:147], v[146:147], v[172:173]
	v_pk_mul_f32 v[78:79], v[78:79], 0.5 op_sel_hi:[1,0]
	v_pk_mul_f32 v[76:77], v[76:77], 0.5 op_sel_hi:[1,0]
	v_pk_mul_f32 v[74:75], v[74:75], 0.5 op_sel_hi:[1,0]
	v_pk_mul_f32 v[72:73], v[72:73], 0.5 op_sel_hi:[1,0]
	v_pk_mul_f32 v[150:151], v[22:23], v[22:23]
	v_pk_mul_f32 v[156:157], v[20:21], v[20:21]
	v_readlane_b32 s4, v254, 33
	v_readlane_b32 s5, v254, 34
	s_waitcnt vmcnt(2) lgkmcnt(0)
	v_pk_fma_f32 v[48:49], v[36:37], v[48:49], v[184:185]
	v_pk_fma_f32 v[50:51], v[38:39], v[50:51], v[186:187]
	flat_store_dwordx4 v[138:139], v[48:51] offset:2048 sc1
	ds_read_b128 v[36:39], v210 offset:3072
	ds_read_b128 v[184:187], v210 offset:7168
	s_waitcnt vmcnt(3) lgkmcnt(0)
	v_pk_fma_f32 v[36:37], v[36:37], v[176:177], v[184:185]
	v_pk_fma_f32 v[38:39], v[38:39], v[178:179], v[186:187]
	flat_store_dwordx4 v[138:139], v[36:39] offset:3072 sc1
	ds_read_b128 v[176:179], v210
	ds_read_b128 v[184:187], v210 offset:4096
	v_lshl_add_u64 v[138:139], v[112:113], 0, v[24:25]
	v_mul_f32_e32 v24, 0x45800000, v26
	v_cndmask_b32_e32 v140, v26, v24, vcc
	v_pk_mul_f32 v[26:27], v[90:91], v[140:141] op_sel_hi:[1,0]
	v_pk_mul_f32 v[24:25], v[88:89], v[140:141] op_sel_hi:[1,0]
	v_pk_mul_f32 v[8:9], v[86:87], v[140:141] op_sel_hi:[1,0]
	v_pk_mul_f32 v[10:11], v[84:85], v[140:141] op_sel_hi:[1,0]
	s_waitcnt vmcnt(4) lgkmcnt(0)
	v_pk_fma_f32 v[24:25], v[176:177], v[24:25], v[184:185]
	v_pk_fma_f32 v[26:27], v[178:179], v[26:27], v[186:187]
	flat_store_dwordx4 v[138:139], v[24:27] sc1
	ds_read_b128 v[28:31], v210 offset:1024
	ds_read_b128 v[88:91], v210 offset:5120
	s_waitcnt vmcnt(5) lgkmcnt(0)
	v_pk_fma_f32 v[28:29], v[28:29], v[10:11], v[88:89]
	v_pk_fma_f32 v[30:31], v[30:31], v[8:9], v[90:91]
	flat_store_dwordx4 v[138:139], v[28:31] offset:1024 sc1
	ds_read_b128 v[84:87], v210 offset:2048
	ds_read_b128 v[88:91], v210 offset:6144
	v_lshlrev_b32_e32 v8, 16, v174
	v_and_b32_e32 v9, 0xffff0000, v174
	v_lshlrev_b32_e32 v10, 16, v175
	v_and_b32_e32 v11, 0xffff0000, v175
	v_pk_add_f32 v[8:9], v[8:9], v[162:163]
	v_pk_add_f32 v[10:11], v[10:11], v[164:165]
	v_pk_mul_f32 v[8:9], v[68:69], v[8:9]
	v_pk_mul_f32 v[10:11], v[70:71], v[10:11]
	v_pk_fma_f32 v[12:13], v[40:41], s[42:43], v[8:9] op_sel_hi:[1,0,1]
	v_pk_fma_f32 v[14:15], v[42:43], s[42:43], v[10:11] op_sel_hi:[1,0,1]
	v_pk_fma_f32 v[8:9], v[34:35], s[42:43], v[66:67] op_sel_hi:[1,0,1]
	v_pk_mul_f32 v[10:11], v[82:83], v[140:141] op_sel_hi:[1,0]
	v_pk_mul_f32 v[34:35], v[80:81], v[140:141] op_sel_hi:[1,0]
	v_lshlrev_b32_e32 v174, 16, v148
	v_and_b32_e32 v175, 0xffff0000, v148
	v_lshlrev_b32_e32 v148, 16, v149
	v_and_b32_e32 v149, 0xffff0000, v149
	v_pk_add_f32 v[160:161], v[160:161], v[174:175]
	v_pk_add_f32 v[144:145], v[144:145], v[148:149]
	v_pk_mul_f32 v[68:69], v[78:79], v[146:147]
	v_pk_mul_f32 v[146:147], v[76:77], v[158:159]
	v_pk_mul_f32 v[144:145], v[74:75], v[144:145]
	v_pk_mul_f32 v[148:149], v[72:73], v[160:161]
	v_pk_fma_f32 v[66:67], v[46:47], s[42:43], v[144:145] op_sel_hi:[1,0,1]
	v_mov_b32_e32 v47, v9
	v_pk_fma_f32 v[70:71], v[54:55], s[42:43], v[68:69] op_sel_hi:[1,0,1]
	v_pk_fma_f32 v[68:69], v[52:53], s[42:43], v[146:147] op_sel_hi:[1,0,1]
	v_add_f32_e32 v54, v70, v71
	v_add_f32_e32 v52, v68, v69
	v_mov_b32_e32 v53, v66
	v_mov_b32_e32 v55, v67
	s_waitcnt vmcnt(6) lgkmcnt(0)
	v_pk_fma_f32 v[40:41], v[84:85], v[34:35], v[88:89]
	v_pk_fma_f32 v[42:43], v[86:87], v[10:11], v[90:91]
	flat_store_dwordx4 v[138:139], v[40:43] offset:2048 sc1
	ds_read_b128 v[72:75], v210 offset:3072
	ds_read_b128 v[76:79], v210 offset:7168
	v_pk_fma_f32 v[10:11], v[32:33], s[42:43], v[64:65] op_sel_hi:[1,0,1]
	v_pk_fma_f32 v[64:65], v[44:45], s[42:43], v[148:149] op_sel_hi:[1,0,1]
	v_pk_mov_b32 v[32:33], v[12:13], v[14:15] op_sel:[1,0]
	v_mov_b32_e32 v34, v12
	v_mov_b32_e32 v35, v15
	v_pk_mov_b32 v[44:45], v[10:11], v[8:9] op_sel:[1,0]
	v_mov_b32_e32 v46, v10
	v_pk_add_f32 v[32:33], v[32:33], v[34:35]
	v_pk_add_f32 v[34:35], v[44:45], v[46:47]
	v_add_f32_e32 v46, v32, v33
	v_pk_add_f32 v[32:33], v[34:35], v[34:35] op_sel:[0,1] op_sel_hi:[1,0]
	v_mov_b32_e32 v81, v64
	v_add_f32_e32 v80, 0, v46
	v_mov_b32_e32 v33, v65
	v_pk_add_f32 v[44:45], v[52:53], v[54:55]
	v_pk_add_f32 v[32:33], v[80:81], v[32:33]
	v_pk_mul_f32 v[34:35], v[16:17], v[16:17]
	v_pk_add_f32 v[32:33], v[32:33], v[44:45]
	v_mul_f32_e32 v44, v4, v4
	v_add_f32_e32 v45, v32, v33
	ds_bpermute_b32 v47, v99, v45
	v_pk_mul_f32 v[32:33], v[18:19], v[18:19]
	v_mul_f32_e32 v46, v6, v6
	v_pk_mov_b32 v[52:53], v[156:157], v[150:151] op_sel:[1,0]
	v_mov_b32_e32 v157, v151
	s_waitcnt lgkmcnt(0)
	v_add_f32_e32 v45, v45, v47
	ds_bpermute_b32 v47, v101, v45
	v_pk_mov_b32 v[54:55], v[34:35], v[32:33] op_sel:[1,0]
	v_mov_b32_e32 v35, v33
	v_pk_fma_f32 v[32:33], v[4:5], v[4:5], v[44:45] op_sel_hi:[1,1,0]
	v_pk_add_f32 v[34:35], v[54:55], v[34:35]
	s_waitcnt lgkmcnt(0)
	v_add_f32_e32 v80, v45, v47
	ds_bpermute_b32 v81, v103, v80
	v_pk_fma_f32 v[44:45], v[6:7], v[6:7], v[46:47] op_sel_hi:[1,1,0]
	v_pk_add_f32 v[46:47], v[52:53], v[156:157]
	v_mul_f32_e32 v32, v0, v0
	v_mul_f32_e32 v44, v1, v1
	s_waitcnt lgkmcnt(0)
	v_add_f32_e32 v52, v80, v81
	ds_bpermute_b32 v53, v105, v52
	v_pk_add_f32 v[32:33], v[32:33], v[44:45]
	v_pk_add_f32 v[46:47], v[46:47], v[46:47] op_sel_hi:[0,1]
	v_pk_add_f32 v[34:35], v[34:35], v[34:35] op_sel_hi:[0,1]
	v_mul_f32_e32 v46, v2, v2
	s_waitcnt lgkmcnt(0)
	v_add_f32_e32 v52, v52, v53
	ds_bpermute_b32 v53, v225, v52
	v_mul_f32_e32 v34, v3, v3
	v_pk_add_f32 v[34:35], v[46:47], v[34:35]
	s_waitcnt lgkmcnt(0)
	v_add_f32_e32 v44, v52, v53
	ds_bpermute_b32 v45, v226, v44
	v_pk_add_f32 v[80:81], v[32:33], v[34:35]
	v_pk_mul_f32 v[32:33], v[94:95], v[140:141] op_sel_hi:[1,0]
	v_pk_mul_f32 v[34:35], v[92:93], v[140:141] op_sel_hi:[1,0]
	v_mov_b32_e32 v83, v80
	s_waitcnt lgkmcnt(0)
	v_add_f32_e32 v44, v44, v45
	v_fmamk_f32 v13, v44, 0xba800000, v13
	v_fmac_f32_e32 v12, 0xba800000, v44
	v_fmamk_f32 v15, v44, 0xba800000, v15
	v_fmac_f32_e32 v14, 0xba800000, v44
	v_fmamk_f32 v11, v44, 0xba800000, v11
	v_fmac_f32_e32 v10, 0xba800000, v44
	v_fmamk_f32 v9, v44, 0xba800000, v9
	v_fmac_f32_e32 v8, 0xba800000, v44
	v_fmamk_f32 v69, v44, 0xba800000, v69
	v_fmac_f32_e32 v68, 0xba800000, v44
	v_fmamk_f32 v71, v44, 0xba800000, v71
	v_fmac_f32_e32 v70, 0xba800000, v44
	v_fmamk_f32 v67, v44, 0xba800000, v67
	v_fmac_f32_e32 v66, 0xba800000, v44
	v_fmamk_f32 v65, v44, 0xba800000, v65
	v_fmac_f32_e32 v64, 0xba800000, v44
	v_pk_mul_f32 v[84:85], v[14:15], v[14:15]
	v_mul_f32_e32 v80, v70, v70
	s_waitcnt vmcnt(7) lgkmcnt(0)
	v_pk_fma_f32 v[52:53], v[72:73], v[34:35], v[76:77]
	v_pk_fma_f32 v[54:55], v[74:75], v[32:33], v[78:79]
	flat_store_dwordx4 v[138:139], v[52:55] offset:3072 sc1
	ds_read_b128 v[32:35], v210
	ds_read_b128 v[44:47], v210 offset:4096
	v_pk_mul_f32 v[72:73], v[12:13], v[12:13]
	v_pk_mul_f32 v[74:75], v[8:9], v[8:9]
	v_pk_mul_f32 v[76:77], v[10:11], v[10:11]
	v_pk_mov_b32 v[86:87], v[72:73], v[84:85] op_sel:[1,0]
	v_mov_b32_e32 v73, v85
	v_pk_mov_b32 v[84:85], v[76:77], v[74:75] op_sel:[1,0]
	v_mov_b32_e32 v77, v75
	v_mul_f32_e32 v78, v68, v68
	v_pk_add_f32 v[72:73], v[86:87], v[72:73]
	v_pk_add_f32 v[76:77], v[84:85], v[76:77]
	v_pk_fma_f32 v[74:75], v[68:69], v[68:69], v[78:79] op_sel_hi:[1,1,0]
	v_pk_fma_f32 v[78:79], v[70:71], v[70:71], v[80:81] op_sel_hi:[1,1,0]
	v_pk_add_f32 v[72:73], v[72:73], v[72:73] op_sel_hi:[0,1]
	v_pk_add_f32 v[76:77], v[76:77], v[76:77] op_sel_hi:[0,1]
	v_mul_f32_e32 v74, v64, v64
	v_mul_f32_e32 v78, v65, v65
	v_mul_f32_e32 v72, v66, v66
	v_mul_f32_e32 v76, v67, v67
	v_pk_add_f32 v[74:75], v[74:75], v[78:79]
	v_pk_add_f32 v[72:73], v[72:73], v[76:77]
	s_nop 0
	v_pk_add_f32 v[72:73], v[74:75], v[72:73]
	s_nop 0
	v_mov_b32_e32 v82, v72
	v_mov_b32_e32 v80, v73
	v_pk_add_f32 v[72:73], v[82:83], v[80:81]
	ds_bpermute_b32 v75, v99, v73
	ds_bpermute_b32 v74, v99, v72
	s_waitcnt lgkmcnt(0)
	v_pk_add_f32 v[72:73], v[72:73], v[74:75]
	ds_bpermute_b32 v75, v101, v73
	ds_bpermute_b32 v74, v101, v72
	s_waitcnt lgkmcnt(0)
	v_pk_add_f32 v[72:73], v[72:73], v[74:75]
	ds_bpermute_b32 v75, v103, v73
	ds_bpermute_b32 v74, v103, v72
	s_waitcnt lgkmcnt(0)
	v_pk_add_f32 v[72:73], v[72:73], v[74:75]
	ds_bpermute_b32 v75, v105, v73
	ds_bpermute_b32 v74, v105, v72
	s_waitcnt lgkmcnt(0)
	v_pk_add_f32 v[72:73], v[72:73], v[74:75]
	ds_bpermute_b32 v75, v225, v73
	ds_bpermute_b32 v74, v225, v72
	s_waitcnt lgkmcnt(0)
	v_pk_add_f32 v[72:73], v[72:73], v[74:75]
	ds_bpermute_b32 v75, v226, v73
	ds_bpermute_b32 v74, v226, v72
	s_waitcnt lgkmcnt(0)
	v_pk_add_f32 v[72:73], v[72:73], v[74:75]
	s_nop 0
	v_pk_fma_f32 v[72:73], v[72:73], s[2:3], v[142:143] op_sel_hi:[1,0,0]
	s_nop 0
	v_mul_f32_e32 v74, 0x4b800000, v73
	v_cmp_gt_f32_e32 vcc, s68, v73
	s_nop 1
	v_cndmask_b32_e32 v73, v73, v74, vcc
	v_rsq_f32_e32 v73, v73
	v_lshlrev_b64 v[74:75], 12, v[132:133]
	v_lshl_add_u64 v[74:75], v[112:113], 0, v[74:75]
	v_mul_f32_e32 v76, 0x45800000, v73
	v_cndmask_b32_e32 v76, v73, v76, vcc
	v_pk_mul_f32 v[22:23], v[22:23], v[76:77] op_sel_hi:[1,0]
	v_pk_mul_f32 v[20:21], v[20:21], v[76:77] op_sel_hi:[1,0]
	s_waitcnt vmcnt(8) lgkmcnt(0)
	v_pk_fma_f32 v[46:47], v[34:35], v[22:23], v[46:47]
	v_pk_fma_f32 v[44:45], v[32:33], v[20:21], v[44:45]
	flat_store_dwordx4 v[74:75], v[44:47] sc1
	ds_read_b128 v[20:23], v210 offset:1024
	ds_read_b128 v[32:35], v210 offset:5120
	v_pk_mul_f32 v[18:19], v[18:19], v[76:77] op_sel_hi:[1,0]
	v_pk_mul_f32 v[16:17], v[16:17], v[76:77] op_sel_hi:[1,0]
	v_pk_mul_f32 v[6:7], v[6:7], v[76:77] op_sel_hi:[1,0]
	v_pk_mul_f32 v[4:5], v[4:5], v[76:77] op_sel_hi:[1,0]
	v_pk_mul_f32 v[2:3], v[2:3], v[76:77] op_sel_hi:[1,0]
	v_pk_mul_f32 v[0:1], v[0:1], v[76:77] op_sel_hi:[1,0]
	v_mul_f32_e32 v73, 0x4b800000, v72
	v_cmp_gt_f32_e32 vcc, s68, v72
	s_waitcnt vmcnt(9) lgkmcnt(0)
	v_pk_fma_f32 v[32:33], v[20:21], v[16:17], v[32:33]
	v_pk_fma_f32 v[34:35], v[22:23], v[18:19], v[34:35]
	flat_store_dwordx4 v[74:75], v[32:35] offset:1024 sc1
	ds_read_b128 v[16:19], v210 offset:2048
	ds_read_b128 v[20:23], v210 offset:6144
	v_cndmask_b32_e32 v72, v72, v73, vcc
	s_waitcnt vmcnt(10) lgkmcnt(0)
	v_pk_fma_f32 v[20:21], v[16:17], v[4:5], v[20:21]
	v_pk_fma_f32 v[22:23], v[18:19], v[6:7], v[22:23]
	flat_store_dwordx4 v[74:75], v[20:23] offset:2048 sc1
	ds_read_b128 v[4:7], v210 offset:3072
	ds_read_b128 v[16:19], v210 offset:7168
	s_waitcnt vmcnt(11) lgkmcnt(0)
	v_pk_fma_f32 v[16:17], v[4:5], v[0:1], v[16:17]
	v_pk_fma_f32 v[18:19], v[6:7], v[2:3], v[18:19]
	flat_store_dwordx4 v[74:75], v[16:19] offset:3072 sc1
	ds_read_b128 v[0:3], v210
	ds_read_b128 v[4:7], v210 offset:4096
	v_rsq_f32_e32 v74, v72
	v_lshl_add_u64 v[72:73], v[112:113], 0, v[134:135]
	v_mul_f32_e32 v75, 0x45800000, v74
	v_cndmask_b32_e32 v74, v74, v75, vcc
	v_pk_mul_f32 v[14:15], v[14:15], v[74:75] op_sel_hi:[1,0]
	v_pk_mul_f32 v[12:13], v[12:13], v[74:75] op_sel_hi:[1,0]
	v_pk_mul_f32 v[76:77], v[8:9], v[74:75] op_sel_hi:[1,0]
	v_pk_mul_f32 v[8:9], v[10:11], v[74:75] op_sel_hi:[1,0]
	v_pk_mul_f32 v[70:71], v[70:71], v[74:75] op_sel_hi:[1,0]
	v_pk_mul_f32 v[68:69], v[68:69], v[74:75] op_sel_hi:[1,0]
	v_pk_mul_f32 v[66:67], v[66:67], v[74:75] op_sel_hi:[1,0]
	v_pk_mul_f32 v[64:65], v[64:65], v[74:75] op_sel_hi:[1,0]
	s_andn2_b64 vcc, exec, s[4:5]
	s_waitcnt vmcnt(12) lgkmcnt(0)
	v_pk_fma_f32 v[12:13], v[0:1], v[12:13], v[4:5]
	v_pk_fma_f32 v[14:15], v[2:3], v[14:15], v[6:7]
	flat_store_dwordx4 v[72:73], v[12:15] sc1
	ds_read_b128 v[0:3], v210 offset:1024
	ds_read_b128 v[4:7], v210 offset:5120
	s_waitcnt vmcnt(13) lgkmcnt(0)
	v_pk_fma_f32 v[8:9], v[0:1], v[8:9], v[4:5]
	v_pk_fma_f32 v[10:11], v[2:3], v[76:77], v[6:7]
	flat_store_dwordx4 v[72:73], v[8:11] offset:1024 sc1
	ds_read_b128 v[0:3], v210 offset:2048
	ds_read_b128 v[4:7], v210 offset:6144
	s_waitcnt vmcnt(14) lgkmcnt(0)
	v_pk_fma_f32 v[4:5], v[0:1], v[68:69], v[4:5]
	v_pk_fma_f32 v[6:7], v[2:3], v[70:71], v[6:7]
	flat_store_dwordx4 v[72:73], v[4:7] offset:2048 sc1
	ds_read_b128 v[0:3], v210 offset:3072
	ds_read_b128 v[68:71], v210 offset:7168
	s_waitcnt vmcnt(15) lgkmcnt(0)
	v_pk_fma_f32 v[0:1], v[0:1], v[64:65], v[68:69]
	v_pk_fma_f32 v[2:3], v[2:3], v[66:67], v[70:71]
	flat_store_dwordx4 v[72:73], v[0:3] offset:3072 sc1
	s_cbranch_vccnz .LBB0_179
	v_mad_u64_u32 v[70:71], s[4:5], v126, s7, 0
	v_mad_i32_i24 v71, v127, s7, v71
	v_mad_u64_u32 v[68:69], s[4:5], v128, s7, 0
	v_mad_u64_u32 v[66:67], s[4:5], v130, s7, 0
	v_mad_u64_u32 v[64:65], s[4:5], v136, s7, 0
	v_lshl_add_u64 v[70:71], s[60:61], 0, v[70:71]
	s_mov_b64 s[4:5], 0x3000
	s_mov_b64 s[8:9], 0x4000
	v_lshl_add_u64 v[72:73], v[70:71], 0, s[4:5]
	v_lshl_add_u64 v[70:71], v[70:71], 0, s[8:9]
	v_lshl_add_u64 v[74:75], v[72:73], 0, v[152:153]
	v_lshl_add_u64 v[78:79], v[70:71], 0, v[152:153]
	global_load_dwordx4 v[214:217], v[74:75], off offset:1024
	global_load_dwordx4 v[218:221], v[74:75], off offset:2048
	flat_load_dwordx4 v[74:77], v[74:75]
	v_mad_i32_i24 v69, v129, s7, v69
	global_load_dwordx4 v[236:239], v[78:79], off offset:1024
	global_load_dwordx4 v[240:243], v[78:79], off offset:2048
	flat_load_dwordx4 v[78:81], v[78:79]
	v_mad_i32_i24 v67, v131, s7, v67
	v_mad_i32_i24 v65, v137, s7, v65
	s_waitcnt vmcnt(0) lgkmcnt(0)
	v_pk_add_f32 v[80:81], v[80:81], 1.0 op_sel_hi:[1,0]
	v_pk_add_f32 v[78:79], v[78:79], 1.0 op_sel_hi:[1,0]
	v_pk_fma_f32 v[62:63], v[62:63], v[80:81], v[76:77]
	v_pk_fma_f32 v[60:61], v[60:61], v[78:79], v[74:75]
	s_nop 0
	v_cvt_pk_bf16_f32 v60, v60, v61
	v_cvt_pk_bf16_f32 v61, v62, v63
	flat_store_dwordx2 v[118:119], v[60:61] sc1
	v_lshlrev_b32_e32 v60, 2, v100
	v_mov_b32_e32 v61, v153
	v_lshl_add_u64 v[62:63], v[72:73], 0, v[60:61]
	v_mov_b64_e32 v[74:75], v[214:215]
	v_mov_b64_e32 v[76:77], v[216:217]
	v_lshl_add_u64 v[62:63], v[70:71], 0, v[60:61]
	v_mov_b64_e32 v[78:79], v[236:237]
	v_mov_b64_e32 v[80:81], v[238:239]
	v_pk_add_f32 v[62:63], v[80:81], 1.0 op_sel_hi:[1,0]
	v_pk_add_f32 v[78:79], v[78:79], 1.0 op_sel_hi:[1,0]
	v_pk_fma_f32 v[58:59], v[58:59], v[62:63], v[76:77]
	v_pk_fma_f32 v[56:57], v[56:57], v[78:79], v[74:75]
	s_nop 0
	v_cvt_pk_bf16_f32 v56, v56, v57
	v_cvt_pk_bf16_f32 v57, v58, v59
	flat_store_dwordx2 v[118:119], v[56:57] offset:512 sc1
	v_lshlrev_b32_e32 v56, 2, v102
	v_mov_b32_e32 v57, v153
	v_lshl_add_u64 v[58:59], v[72:73], 0, v[56:57]
	v_mov_b64_e32 v[74:75], v[218:219]
	v_mov_b64_e32 v[76:77], v[220:221]
	v_lshl_add_u64 v[58:59], v[70:71], 0, v[56:57]
	v_mov_b64_e32 v[78:79], v[240:241]
	v_mov_b64_e32 v[80:81], v[242:243]
	v_pk_add_f32 v[58:59], v[80:81], 1.0 op_sel_hi:[1,0]
	v_pk_add_f32 v[62:63], v[78:79], 1.0 op_sel_hi:[1,0]
	v_pk_fma_f32 v[50:51], v[50:51], v[58:59], v[76:77]
	v_pk_fma_f32 v[48:49], v[48:49], v[62:63], v[74:75]
	s_nop 0
	v_cvt_pk_bf16_f32 v48, v48, v49
	v_cvt_pk_bf16_f32 v49, v50, v51
	flat_store_dwordx2 v[118:119], v[48:49] offset:1024 sc1
	v_lshlrev_b32_e32 v48, 2, v104
	v_mov_b32_e32 v49, v153
	v_lshl_add_u64 v[50:51], v[72:73], 0, v[48:49]
	flat_load_dwordx4 v[72:75], v[50:51]
	v_lshl_add_u64 v[50:51], v[70:71], 0, v[48:49]
	flat_load_dwordx4 v[76:79], v[50:51]
	s_waitcnt vmcnt(0) lgkmcnt(0)
	v_pk_add_f32 v[50:51], v[78:79], 1.0 op_sel_hi:[1,0]
	v_pk_add_f32 v[58:59], v[76:77], 1.0 op_sel_hi:[1,0]
	v_pk_fma_f32 v[38:39], v[38:39], v[50:51], v[74:75]
	v_pk_fma_f32 v[36:37], v[36:37], v[58:59], v[72:73]
	v_lshlrev_b64 v[50:51], 11, v[124:125]
	v_cvt_pk_bf16_f32 v36, v36, v37
	v_cvt_pk_bf16_f32 v37, v38, v39
	flat_store_dwordx2 v[118:119], v[36:37] offset:1536 sc1
	v_lshl_add_u64 v[36:37], s[60:61], 0, v[68:69]
	v_lshl_add_u64 v[38:39], v[36:37], 0, s[4:5]
	v_lshl_add_u64 v[36:37], v[36:37], 0, s[8:9]
	v_lshl_add_u64 v[58:59], v[38:39], 0, v[152:153]
	global_load_dwordx4 v[214:217], v[58:59], off offset:1024
	global_load_dwordx4 v[218:221], v[58:59], off offset:2048
	flat_load_dwordx4 v[68:71], v[58:59]
	v_lshl_add_u64 v[58:59], v[36:37], 0, v[152:153]
	global_load_dwordx4 v[236:239], v[58:59], off offset:1024
	global_load_dwordx4 v[240:243], v[58:59], off offset:2048
	flat_load_dwordx4 v[72:75], v[58:59]
	v_lshl_add_u64 v[50:51], v[114:115], 0, v[50:51]
	s_waitcnt vmcnt(0) lgkmcnt(0)
	v_pk_add_f32 v[58:59], v[74:75], 1.0 op_sel_hi:[1,0]
	v_pk_add_f32 v[62:63], v[72:73], 1.0 op_sel_hi:[1,0]
	v_pk_fma_f32 v[26:27], v[26:27], v[58:59], v[70:71]
	v_pk_fma_f32 v[24:25], v[24:25], v[62:63], v[68:69]
	v_lshl_add_u64 v[58:59], v[36:37], 0, v[60:61]
	v_cvt_pk_bf16_f32 v24, v24, v25
	v_cvt_pk_bf16_f32 v25, v26, v27
	flat_store_dwordx2 v[50:51], v[24:25] sc1
	v_lshl_add_u64 v[24:25], v[38:39], 0, v[60:61]
	v_mov_b64_e32 v[24:25], v[214:215]
	v_mov_b64_e32 v[26:27], v[216:217]
	s_nop 0
	v_mov_b64_e32 v[68:69], v[236:237]
	v_mov_b64_e32 v[70:71], v[238:239]
	v_pk_add_f32 v[58:59], v[70:71], 1.0 op_sel_hi:[1,0]
	v_pk_add_f32 v[62:63], v[68:69], 1.0 op_sel_hi:[1,0]
	v_pk_fma_f32 v[26:27], v[30:31], v[58:59], v[26:27]
	v_pk_fma_f32 v[24:25], v[28:29], v[62:63], v[24:25]
	v_lshl_add_u64 v[28:29], v[36:37], 0, v[56:57]
	v_cvt_pk_bf16_f32 v24, v24, v25
	v_cvt_pk_bf16_f32 v25, v26, v27
	flat_store_dwordx2 v[50:51], v[24:25] offset:512 sc1
	v_lshl_add_u64 v[24:25], v[38:39], 0, v[56:57]
	v_mov_b64_e32 v[24:25], v[218:219]
	v_mov_b64_e32 v[26:27], v[220:221]
	s_nop 0
	v_mov_b64_e32 v[28:29], v[240:241]
	v_mov_b64_e32 v[30:31], v[242:243]
	v_pk_add_f32 v[30:31], v[30:31], 1.0 op_sel_hi:[1,0]
	v_pk_add_f32 v[28:29], v[28:29], 1.0 op_sel_hi:[1,0]
	v_pk_fma_f32 v[26:27], v[42:43], v[30:31], v[26:27]
	v_pk_fma_f32 v[24:25], v[40:41], v[28:29], v[24:25]
	v_lshl_add_u64 v[28:29], v[36:37], 0, v[48:49]
	v_cvt_pk_bf16_f32 v24, v24, v25
	v_cvt_pk_bf16_f32 v25, v26, v27
	flat_store_dwordx2 v[50:51], v[24:25] offset:1024 sc1
	v_lshl_add_u64 v[24:25], v[38:39], 0, v[48:49]
	flat_load_dwordx4 v[24:27], v[24:25]
	s_nop 0
	flat_load_dwordx4 v[28:31], v[28:29]
	s_waitcnt vmcnt(0) lgkmcnt(0)
	v_pk_add_f32 v[30:31], v[30:31], 1.0 op_sel_hi:[1,0]
	v_pk_add_f32 v[28:29], v[28:29], 1.0 op_sel_hi:[1,0]
	v_pk_fma_f32 v[26:27], v[54:55], v[30:31], v[26:27]
	v_pk_fma_f32 v[24:25], v[52:53], v[28:29], v[24:25]
	v_lshlrev_b64 v[30:31], 11, v[122:123]
	v_cvt_pk_bf16_f32 v24, v24, v25
	v_cvt_pk_bf16_f32 v25, v26, v27
	flat_store_dwordx2 v[50:51], v[24:25] offset:1536 sc1
	v_lshl_add_u64 v[24:25], s[60:61], 0, v[66:67]
	v_lshl_add_u64 v[40:41], v[24:25], 0, s[4:5]
	v_lshl_add_u64 v[24:25], v[24:25], 0, s[8:9]
	v_lshl_add_u64 v[26:27], v[40:41], 0, v[152:153]
	v_lshl_add_u64 v[36:37], v[24:25], 0, v[152:153]
	global_load_dwordx4 v[214:217], v[26:27], off offset:1024
	global_load_dwordx4 v[218:221], v[26:27], off offset:2048
	flat_load_dwordx4 v[26:29], v[26:27]
	v_lshl_add_u64 v[42:43], v[114:115], 0, v[30:31]
	global_load_dwordx4 v[236:239], v[36:37], off offset:1024
	global_load_dwordx4 v[240:243], v[36:37], off offset:2048
	flat_load_dwordx4 v[36:39], v[36:37]
	v_lshl_add_u64 v[30:31], v[24:25], 0, v[60:61]
	s_waitcnt vmcnt(0) lgkmcnt(0)
	v_pk_add_f32 v[38:39], v[38:39], 1.0 op_sel_hi:[1,0]
	v_pk_add_f32 v[36:37], v[36:37], 1.0 op_sel_hi:[1,0]
	v_pk_fma_f32 v[28:29], v[46:47], v[38:39], v[28:29]
	v_pk_fma_f32 v[26:27], v[44:45], v[36:37], v[26:27]
	s_nop 0
	v_cvt_pk_bf16_f32 v26, v26, v27
	v_cvt_pk_bf16_f32 v27, v28, v29
	flat_store_dwordx2 v[42:43], v[26:27] sc1
	v_lshl_add_u64 v[26:27], v[40:41], 0, v[60:61]
	v_mov_b64_e32 v[26:27], v[214:215]
	v_mov_b64_e32 v[28:29], v[216:217]
	s_nop 0
	v_mov_b64_e32 v[36:37], v[236:237]
	v_mov_b64_e32 v[38:39], v[238:239]
	v_pk_add_f32 v[30:31], v[38:39], 1.0 op_sel_hi:[1,0]
	v_pk_add_f32 v[36:37], v[36:37], 1.0 op_sel_hi:[1,0]
	v_pk_fma_f32 v[28:29], v[34:35], v[30:31], v[28:29]
	v_pk_fma_f32 v[26:27], v[32:33], v[36:37], v[26:27]
	v_lshl_add_u64 v[30:31], v[24:25], 0, v[56:57]
	v_cvt_pk_bf16_f32 v26, v26, v27
	v_cvt_pk_bf16_f32 v27, v28, v29
	flat_store_dwordx2 v[42:43], v[26:27] offset:512 sc1
	v_lshl_add_u64 v[26:27], v[40:41], 0, v[56:57]
	v_mov_b64_e32 v[26:27], v[218:219]
	v_mov_b64_e32 v[28:29], v[220:221]
	v_lshl_add_u64 v[24:25], v[24:25], 0, v[48:49]
	v_mov_b64_e32 v[30:31], v[240:241]
	v_mov_b64_e32 v[32:33], v[242:243]
	v_pk_add_f32 v[32:33], v[32:33], 1.0 op_sel_hi:[1,0]
	v_pk_add_f32 v[30:31], v[30:31], 1.0 op_sel_hi:[1,0]
	v_pk_fma_f32 v[22:23], v[22:23], v[32:33], v[28:29]
	v_pk_fma_f32 v[20:21], v[20:21], v[30:31], v[26:27]
	v_lshlrev_b64 v[28:29], 11, v[120:121]
	v_cvt_pk_bf16_f32 v20, v20, v21
	v_cvt_pk_bf16_f32 v21, v22, v23
	flat_store_dwordx2 v[42:43], v[20:21] offset:1024 sc1
	v_lshl_add_u64 v[20:21], v[40:41], 0, v[48:49]
	flat_load_dwordx4 v[20:23], v[20:21]
	s_nop 0
	flat_load_dwordx4 v[24:27], v[24:25]
	s_waitcnt vmcnt(0) lgkmcnt(0)
	v_pk_add_f32 v[26:27], v[26:27], 1.0 op_sel_hi:[1,0]
	v_pk_add_f32 v[24:25], v[24:25], 1.0 op_sel_hi:[1,0]
	v_pk_fma_f32 v[18:19], v[18:19], v[26:27], v[22:23]
	v_pk_fma_f32 v[16:17], v[16:17], v[24:25], v[20:21]
	s_nop 0
	v_cvt_pk_bf16_f32 v16, v16, v17
	v_cvt_pk_bf16_f32 v17, v18, v19
	flat_store_dwordx2 v[42:43], v[16:17] offset:1536 sc1
	v_lshl_add_u64 v[16:17], s[60:61], 0, v[64:65]
	v_lshl_add_u64 v[26:27], v[16:17], 0, s[4:5]
	v_lshl_add_u64 v[16:17], v[16:17], 0, s[8:9]
	v_lshl_add_u64 v[18:19], v[26:27], 0, v[152:153]
	v_lshl_add_u64 v[22:23], v[16:17], 0, v[152:153]
	global_load_dwordx4 v[214:217], v[18:19], off offset:1024
	global_load_dwordx4 v[218:221], v[18:19], off offset:2048
	flat_load_dwordx4 v[18:21], v[18:19]
	s_nop 0
	global_load_dwordx4 v[236:239], v[22:23], off offset:1024
	global_load_dwordx4 v[240:243], v[22:23], off offset:2048
	flat_load_dwordx4 v[22:25], v[22:23]
	s_waitcnt vmcnt(0) lgkmcnt(0)
	v_pk_add_f32 v[24:25], v[24:25], 1.0 op_sel_hi:[1,0]
	v_pk_add_f32 v[22:23], v[22:23], 1.0 op_sel_hi:[1,0]
	v_pk_fma_f32 v[14:15], v[14:15], v[24:25], v[20:21]
	v_pk_fma_f32 v[12:13], v[12:13], v[22:23], v[18:19]
	v_lshl_add_u64 v[22:23], v[114:115], 0, v[28:29]
	v_cvt_pk_bf16_f32 v12, v12, v13
	v_cvt_pk_bf16_f32 v13, v14, v15
	flat_store_dwordx2 v[22:23], v[12:13] sc1
	v_lshl_add_u64 v[12:13], v[26:27], 0, v[60:61]
	v_lshl_add_u64 v[18:19], v[16:17], 0, v[60:61]
	v_mov_b64_e32 v[12:13], v[214:215]
	v_mov_b64_e32 v[14:15], v[216:217]
	s_nop 0
	v_mov_b64_e32 v[18:19], v[236:237]
	v_mov_b64_e32 v[20:21], v[238:239]
	v_pk_add_f32 v[20:21], v[20:21], 1.0 op_sel_hi:[1,0]
	v_pk_add_f32 v[18:19], v[18:19], 1.0 op_sel_hi:[1,0]
	v_pk_fma_f32 v[10:11], v[10:11], v[20:21], v[14:15]
	v_pk_fma_f32 v[8:9], v[8:9], v[18:19], v[12:13]
	v_lshl_add_u64 v[12:13], v[16:17], 0, v[56:57]
	v_cvt_pk_bf16_f32 v8, v8, v9
	v_cvt_pk_bf16_f32 v9, v10, v11
	flat_store_dwordx2 v[22:23], v[8:9] offset:512 sc1
	v_lshl_add_u64 v[8:9], v[26:27], 0, v[56:57]
	v_mov_b64_e32 v[8:9], v[218:219]
	v_mov_b64_e32 v[10:11], v[220:221]
	s_nop 0
	v_mov_b64_e32 v[12:13], v[240:241]
	v_mov_b64_e32 v[14:15], v[242:243]
	v_pk_add_f32 v[14:15], v[14:15], 1.0 op_sel_hi:[1,0]
	v_pk_add_f32 v[12:13], v[12:13], 1.0 op_sel_hi:[1,0]
	v_pk_fma_f32 v[6:7], v[6:7], v[14:15], v[10:11]
	v_pk_fma_f32 v[4:5], v[4:5], v[12:13], v[8:9]
	v_lshl_add_u64 v[8:9], v[16:17], 0, v[48:49]
	v_cvt_pk_bf16_f32 v4, v4, v5
	v_cvt_pk_bf16_f32 v5, v6, v7
	flat_store_dwordx2 v[22:23], v[4:5] offset:1024 sc1
	v_lshl_add_u64 v[4:5], v[26:27], 0, v[48:49]
	flat_load_dwordx4 v[4:7], v[4:5]
	s_nop 0
	flat_load_dwordx4 v[8:11], v[8:9]
	s_waitcnt vmcnt(0) lgkmcnt(0)
	v_pk_add_f32 v[10:11], v[10:11], 1.0 op_sel_hi:[1,0]
	v_pk_add_f32 v[8:9], v[8:9], 1.0 op_sel_hi:[1,0]
	v_pk_fma_f32 v[2:3], v[2:3], v[10:11], v[6:7]
	v_pk_fma_f32 v[0:1], v[0:1], v[8:9], v[4:5]
	s_nop 0
	v_cvt_pk_bf16_f32 v0, v0, v1
	v_cvt_pk_bf16_f32 v1, v2, v3
	flat_store_dwordx2 v[22:23], v[0:1] offset:1536 sc1
	s_branch .LBB0_179

.LBB0_225:
	global_load_dwordx4 v[154:157], v[74:75], off
	global_load_dwordx4 v[158:161], v[76:77], off
	global_load_dwordx4 v[162:165], v[74:75], off offset:1024
	global_load_dwordx4 v[166:169], v[76:77], off offset:1024
	global_load_dwordx4 v[170:173], v[74:75], off offset:2048
	global_load_dwordx4 v[174:177], v[76:77], off offset:2048
	global_load_dwordx4 v[178:181], v[74:75], off offset:3072
	global_load_dwordx4 v[182:185], v[76:77], off offset:3072
	v_add_u32_e32 v0, 0xfffff000, v64
	v_ashrrev_i32_e32 v0, 10, v0
	v_add_u32_e32 v0, 1, v0
	v_cmp_lt_i32_e32 vcc, s33, v64
	global_load_dwordx4 v[186:189], v[86:87], off offset:1024
	global_load_dwordx4 v[190:193], v[86:87], off offset:2048
	global_load_dwordx4 v[194:197], v[86:87], off offset:3072
	flat_load_dwordx4 v[8:11], v[86:87]
	s_mov_b64 s[8:9], 0x1000000
	v_cndmask_b32_e32 v94, 0, v0, vcc
	v_add_u32_e32 v0, s38, v64
	v_cmp_lt_i32_e32 vcc, s6, v0
	v_ashrrev_i32_e32 v95, 31, v94
	v_lshl_add_u64 v[4:5], v[94:95], 0, s[28:29]
	v_cndmask_b32_e32 v0, v0, v64, vcc
	v_add_u32_e32 v1, 0xfffff000, v0
	v_ashrrev_i32_e32 v1, 10, v1
	v_add_u32_e32 v1, 1, v1
	v_cmp_lt_i32_e32 vcc, s33, v0
	v_mad_u64_u32 v[2:3], s[4:5], v4, s7, v[78:79]
	s_nop 0
	v_cndmask_b32_e32 v92, 0, v1, vcc
	v_add_u32_e32 v1, s35, v64
	v_cmp_lt_i32_e32 vcc, s6, v1
	s_mov_b32 s4, 0x1000000
	v_mad_i32_i24 v3, v5, s7, v3
	v_cndmask_b32_e32 v18, v1, v64, vcc
	v_add_u32_e32 v1, 0xfffff000, v18
	v_ashrrev_i32_e32 v1, 10, v1
	v_add_u32_e32 v1, 1, v1
	v_cmp_lt_i32_e32 vcc, s33, v18
	global_load_dwordx4 v[198:201], v[2:3], off offset:1024
	global_load_dwordx4 v[202:205], v[2:3], off offset:2048
	global_load_dwordx4 v[224:227], v[2:3], off offset:3072
	flat_load_dwordx4 v[12:15], v[2:3]
	v_ashrrev_i32_e32 v93, 31, v92
	v_cndmask_b32_e32 v90, 0, v1, vcc
	v_add_u32_e32 v1, s26, v64
	v_cmp_lt_i32_e32 vcc, s6, v1
	v_lshlrev_b32_e32 v152, 1, v66
	v_lshlrev_b32_e32 v42, 1, v68
	v_cndmask_b32_e32 v16, v1, v64, vcc
	v_add_u32_e32 v1, 0xfffff000, v16
	v_ashrrev_i32_e32 v1, 10, v1
	v_add_u32_e32 v1, 1, v1
	v_cmp_lt_i32_e32 vcc, s33, v16
	v_mov_b32_e32 v43, v153
	v_lshlrev_b32_e32 v104, 1, v70
	v_cndmask_b32_e32 v88, 0, v1, vcc
	v_add_co_u32_e32 v4, vcc, s4, v84
	s_brev_b32 s4, 64
	s_nop 0
	v_addc_co_u32_e32 v5, vcc, 0, v85, vcc
	global_load_dwordx2 v[228:229], v[4:5], off offset:512
	global_load_dwordx2 v[230:231], v[4:5], off offset:1024
	global_load_dwordx2 v[232:233], v[4:5], off offset:1536
	flat_load_dwordx2 v[6:7], v[4:5]
	v_mov_b32_e32 v105, v153
	v_lshlrev_b32_e32 v106, 1, v72
	v_mov_b32_e32 v107, v153
	v_ashrrev_i32_e32 v19, 31, v18
	v_ashrrev_i32_e32 v91, 31, v90
	v_lshlrev_b64 v[100:101], 11, v[18:19]
	v_ashrrev_i32_e32 v17, 31, v16
	v_ashrrev_i32_e32 v89, 31, v88
	s_waitcnt vmcnt(0) lgkmcnt(0)
	v_pk_mul_f32 v[14:15], v[14:15], 0.5 op_sel_hi:[1,0]
	v_pk_mul_f32 v[12:13], v[12:13], 0.5 op_sel_hi:[1,0]
	v_lshlrev_b32_e32 v20, 16, v6
	v_and_b32_e32 v21, 0xffff0000, v6
	v_add_co_u32_e32 v6, vcc, s4, v84
	v_lshlrev_b32_e32 v22, 16, v7
	v_and_b32_e32 v23, 0xffff0000, v7
	v_addc_co_u32_e32 v7, vcc, 0, v85, vcc
	global_load_dwordx2 v[234:235], v[6:7], off offset:512
	global_load_dwordx2 v[236:237], v[6:7], off offset:1024
	global_load_dwordx2 v[238:239], v[6:7], off offset:1536
	flat_load_dwordx2 v[24:25], v[6:7]
	s_waitcnt vmcnt(0) lgkmcnt(0)
	v_lshlrev_b32_e32 v26, 16, v24
	v_and_b32_e32 v27, 0xffff0000, v24
	v_lshlrev_b32_e32 v24, 16, v25
	v_and_b32_e32 v25, 0xffff0000, v25
	v_pk_add_f32 v[20:21], v[20:21], v[26:27]
	v_pk_add_f32 v[22:23], v[22:23], v[24:25]
	v_pk_mul_f32 v[12:13], v[12:13], v[20:21]
	v_pk_mul_f32 v[14:15], v[14:15], v[22:23]
	v_pk_fma_f32 v[8:9], v[8:9], s[42:43], v[12:13] op_sel_hi:[1,0,1]
	v_pk_fma_f32 v[10:11], v[10:11], s[42:43], v[14:15] op_sel_hi:[1,0,1]
	v_mov_b32_e32 v14, v8
	v_pk_mov_b32 v[12:13], v[8:9], v[10:11] op_sel:[1,0]
	v_mov_b32_e32 v15, v11
	v_pk_add_f32 v[12:13], v[12:13], v[14:15]
	s_nop 0
	v_add_f32_e32 v1, v12, v13
	v_mov_b64_e32 v[12:13], v[186:187]
	v_mov_b64_e32 v[14:15], v[188:189]
	v_mov_b64_e32 v[20:21], v[198:199]
	v_mov_b64_e32 v[22:23], v[200:201]
	v_mov_b64_e32 v[24:25], v[228:229]
	v_mov_b64_e32 v[30:31], v[234:235]
	v_add_f32_e32 v28, 0, v1
	v_ashrrev_i32_e32 v1, 31, v0
	v_lshlrev_b64 v[96:97], 11, v[0:1]
	v_pk_mul_f32 v[22:23], v[22:23], 0.5 op_sel_hi:[1,0]
	v_lshlrev_b32_e32 v26, 16, v24
	v_and_b32_e32 v27, 0xffff0000, v24
	v_lshlrev_b32_e32 v24, 16, v25
	v_and_b32_e32 v25, 0xffff0000, v25
	v_lshlrev_b32_e32 v32, 16, v30
	v_and_b32_e32 v33, 0xffff0000, v30
	v_lshlrev_b32_e32 v30, 16, v31
	v_and_b32_e32 v31, 0xffff0000, v31
	v_pk_mul_f32 v[20:21], v[20:21], 0.5 op_sel_hi:[1,0]
	v_pk_add_f32 v[26:27], v[26:27], v[32:33]
	v_pk_add_f32 v[24:25], v[24:25], v[30:31]
	v_pk_mul_f32 v[20:21], v[20:21], v[26:27]
	v_pk_mul_f32 v[22:23], v[22:23], v[24:25]
	v_pk_fma_f32 v[12:13], v[12:13], s[42:43], v[20:21] op_sel_hi:[1,0,1]
	v_pk_fma_f32 v[14:15], v[14:15], s[42:43], v[22:23] op_sel_hi:[1,0,1]
	v_mov_b32_e32 v22, v12
	v_pk_mov_b32 v[20:21], v[12:13], v[14:15] op_sel:[1,0]
	v_mov_b32_e32 v23, v15
	v_pk_add_f32 v[20:21], v[20:21], v[22:23]
	s_nop 0
	v_pk_add_f32 v[30:31], v[20:21], v[20:21] op_sel:[0,1] op_sel_hi:[1,0]
	v_mov_b64_e32 v[20:21], v[190:191]
	v_mov_b64_e32 v[22:23], v[192:193]
	v_mov_b64_e32 v[24:25], v[202:203]
	v_mov_b64_e32 v[26:27], v[204:205]
	v_mov_b64_e32 v[32:33], v[230:231]
	v_mov_b64_e32 v[36:37], v[236:237]
	v_pk_mul_f32 v[26:27], v[26:27], 0.5 op_sel_hi:[1,0]
	v_lshlrev_b32_e32 v34, 16, v32
	v_and_b32_e32 v35, 0xffff0000, v32
	v_lshlrev_b32_e32 v32, 16, v33
	v_and_b32_e32 v33, 0xffff0000, v33
	v_lshlrev_b32_e32 v38, 16, v36
	v_and_b32_e32 v39, 0xffff0000, v36
	v_lshlrev_b32_e32 v36, 16, v37
	v_and_b32_e32 v37, 0xffff0000, v37
	v_pk_mul_f32 v[24:25], v[24:25], 0.5 op_sel_hi:[1,0]
	v_pk_add_f32 v[32:33], v[32:33], v[36:37]
	v_pk_add_f32 v[34:35], v[34:35], v[38:39]
	v_pk_mul_f32 v[26:27], v[26:27], v[32:33]
	v_pk_mul_f32 v[24:25], v[24:25], v[34:35]
	v_pk_fma_f32 v[22:23], v[22:23], s[42:43], v[26:27] op_sel_hi:[1,0,1]
	v_pk_fma_f32 v[20:21], v[20:21], s[42:43], v[24:25] op_sel_hi:[1,0,1]
	v_mov_b64_e32 v[24:25], v[194:195]
	v_mov_b64_e32 v[26:27], v[196:197]
	v_mov_b64_e32 v[32:33], v[224:225]
	v_mov_b64_e32 v[34:35], v[226:227]
	s_nop 0
	v_mov_b64_e32 v[2:3], v[232:233]
	v_add_f32_e32 v36, v20, v21
	v_mov_b64_e32 v[6:7], v[238:239]
	v_add_f32_e32 v38, v22, v23
	v_pk_mul_f32 v[34:35], v[34:35], 0.5 op_sel_hi:[1,0]
	v_lshlrev_b32_e32 v4, 16, v2
	v_and_b32_e32 v5, 0xffff0000, v2
	v_lshlrev_b32_e32 v2, 16, v3
	v_and_b32_e32 v3, 0xffff0000, v3
	v_lshlrev_b32_e32 v40, 16, v6
	v_and_b32_e32 v41, 0xffff0000, v6
	v_lshlrev_b32_e32 v6, 16, v7
	v_and_b32_e32 v7, 0xffff0000, v7
	v_pk_mul_f32 v[32:33], v[32:33], 0.5 op_sel_hi:[1,0]
	v_pk_add_f32 v[2:3], v[2:3], v[6:7]
	v_pk_add_f32 v[4:5], v[4:5], v[40:41]
	v_pk_mul_f32 v[2:3], v[34:35], v[2:3]
	v_pk_mul_f32 v[4:5], v[32:33], v[4:5]
	v_pk_fma_f32 v[26:27], v[26:27], s[42:43], v[2:3] op_sel_hi:[1,0,1]
	v_pk_fma_f32 v[24:25], v[24:25], s[42:43], v[4:5] op_sel_hi:[1,0,1]
	v_mov_b32_e32 v37, v26
	v_mov_b32_e32 v29, v24
	v_mov_b32_e32 v31, v25
	v_mov_b32_e32 v39, v27
	v_lshl_add_u64 v[34:35], s[56:57], 0, v[96:97]
	v_pk_add_f32 v[2:3], v[28:29], v[30:31]
	v_pk_add_f32 v[4:5], v[36:37], v[38:39]
	v_lshl_add_u64 v[6:7], v[92:93], 0, s[28:29]
	v_lshl_add_u64 v[46:47], v[34:35], 0, s[8:9]
	v_pk_add_f32 v[2:3], v[2:3], v[4:5]
	v_mad_u64_u32 v[4:5], s[4:5], v6, s7, v[78:79]
	v_lshl_add_u64 v[48:49], v[34:35], 0, v[152:153]
	v_lshl_add_u64 v[36:37], v[46:47], 0, v[152:153]
	v_mad_i32_i24 v5, v7, s7, v5
	global_load_dwordx2 v[228:229], v[48:49], off offset:512
	global_load_dwordx2 v[230:231], v[48:49], off offset:1024
	global_load_dwordx2 v[232:233], v[48:49], off offset:1536
	flat_load_dwordx2 v[6:7], v[48:49]
	v_add_f32_e32 v120, v2, v3
	global_load_dwordx2 v[234:235], v[36:37], off offset:512
	global_load_dwordx2 v[236:237], v[36:37], off offset:1024
	global_load_dwordx2 v[238:239], v[36:37], off offset:1536
	flat_load_dwordx2 v[36:37], v[36:37]
	v_lshlrev_b64 v[2:3], 12, v[0:1]
	global_load_dwordx4 v[186:189], v[4:5], off offset:1024
	global_load_dwordx4 v[190:193], v[4:5], off offset:2048
	global_load_dwordx4 v[194:197], v[4:5], off offset:3072
	flat_load_dwordx4 v[28:31], v[4:5]
	v_lshl_add_u64 v[32:33], v[80:81], 0, v[2:3]
	global_load_dwordx4 v[198:201], v[32:33], off offset:1024
	global_load_dwordx4 v[202:205], v[32:33], off offset:2048
	global_load_dwordx4 v[224:227], v[32:33], off offset:3072
	flat_load_dwordx4 v[0:3], v[32:33]
	v_lshl_add_u64 v[44:45], v[46:47], 0, v[42:43]
	v_lshl_add_u64 v[52:53], v[46:47], 0, v[104:105]
	v_lshl_add_u64 v[46:47], v[46:47], 0, v[106:107]
	s_waitcnt vmcnt(0) lgkmcnt(0)
	v_lshlrev_b32_e32 v34, 16, v6
	v_and_b32_e32 v35, 0xffff0000, v6
	v_lshlrev_b32_e32 v6, 16, v7
	v_and_b32_e32 v7, 0xffff0000, v7
	v_lshlrev_b32_e32 v38, 16, v36
	v_and_b32_e32 v39, 0xffff0000, v36
	v_lshlrev_b32_e32 v36, 16, v37
	v_and_b32_e32 v37, 0xffff0000, v37
	v_pk_mul_f32 v[30:31], v[30:31], 0.5 op_sel_hi:[1,0]
	v_pk_mul_f32 v[28:29], v[28:29], 0.5 op_sel_hi:[1,0]
	v_pk_add_f32 v[34:35], v[34:35], v[38:39]
	v_pk_add_f32 v[6:7], v[6:7], v[36:37]
	v_pk_mul_f32 v[28:29], v[28:29], v[34:35]
	v_pk_mul_f32 v[6:7], v[30:31], v[6:7]
	v_pk_fma_f32 v[34:35], v[0:1], s[42:43], v[28:29] op_sel_hi:[1,0,1]
	v_pk_fma_f32 v[36:37], v[2:3], s[42:43], v[6:7] op_sel_hi:[1,0,1]
	v_mov_b32_e32 v2, v34
	v_pk_mov_b32 v[0:1], v[34:35], v[36:37] op_sel:[1,0]
	v_mov_b32_e32 v3, v37
	v_pk_add_f32 v[0:1], v[0:1], v[2:3]
	s_nop 0
	v_add_f32_e32 v0, v0, v1
	v_add_f32_e32 v40, 0, v0
	v_mov_b64_e32 v[0:1], v[198:199]
	v_mov_b64_e32 v[2:3], v[200:201]
	v_mov_b64_e32 v[28:29], v[186:187]
	v_mov_b64_e32 v[30:31], v[188:189]
	v_mov_b64_e32 v[6:7], v[228:229]
	v_pk_mul_f32 v[30:31], v[30:31], 0.5 op_sel_hi:[1,0]
	v_mov_b64_e32 v[44:45], v[234:235]
	v_lshlrev_b32_e32 v38, 16, v6
	v_and_b32_e32 v39, 0xffff0000, v6
	v_lshlrev_b32_e32 v6, 16, v7
	v_and_b32_e32 v7, 0xffff0000, v7
	v_pk_mul_f32 v[28:29], v[28:29], 0.5 op_sel_hi:[1,0]
	v_lshlrev_b32_e32 v50, 16, v44
	v_and_b32_e32 v51, 0xffff0000, v44
	v_lshlrev_b32_e32 v44, 16, v45
	v_and_b32_e32 v45, 0xffff0000, v45
	v_pk_add_f32 v[38:39], v[38:39], v[50:51]
	v_pk_add_f32 v[6:7], v[6:7], v[44:45]
	v_pk_mul_f32 v[28:29], v[28:29], v[38:39]
	v_pk_mul_f32 v[6:7], v[30:31], v[6:7]
	v_pk_fma_f32 v[38:39], v[0:1], s[42:43], v[28:29] op_sel_hi:[1,0,1]
	v_pk_fma_f32 v[60:61], v[2:3], s[42:43], v[6:7] op_sel_hi:[1,0,1]
	v_mov_b32_e32 v2, v38
	v_pk_mov_b32 v[0:1], v[38:39], v[60:61] op_sel:[1,0]
	v_mov_b32_e32 v3, v61
	v_pk_add_f32 v[0:1], v[0:1], v[2:3]
	s_nop 0
	v_pk_add_f32 v[44:45], v[0:1], v[0:1] op_sel:[0,1] op_sel_hi:[1,0]
	v_mov_b64_e32 v[0:1], v[202:203]
	v_mov_b64_e32 v[2:3], v[204:205]
	v_mov_b64_e32 v[28:29], v[190:191]
	v_mov_b64_e32 v[30:31], v[192:193]
	v_mov_b64_e32 v[6:7], v[230:231]
	v_pk_mul_f32 v[30:31], v[30:31], 0.5 op_sel_hi:[1,0]
	v_mov_b64_e32 v[52:53], v[236:237]
	v_lshlrev_b32_e32 v50, 16, v6
	v_and_b32_e32 v51, 0xffff0000, v6
	v_lshlrev_b32_e32 v6, 16, v7
	v_and_b32_e32 v7, 0xffff0000, v7
	v_pk_mul_f32 v[28:29], v[28:29], 0.5 op_sel_hi:[1,0]
	v_lshlrev_b32_e32 v54, 16, v52
	v_and_b32_e32 v55, 0xffff0000, v52
	v_lshlrev_b32_e32 v52, 16, v53
	v_and_b32_e32 v53, 0xffff0000, v53
	v_pk_add_f32 v[6:7], v[6:7], v[52:53]
	v_pk_add_f32 v[50:51], v[50:51], v[54:55]
	v_pk_mul_f32 v[6:7], v[30:31], v[6:7]
	v_pk_mul_f32 v[28:29], v[28:29], v[50:51]
	v_pk_fma_f32 v[30:31], v[2:3], s[42:43], v[6:7] op_sel_hi:[1,0,1]
	v_pk_fma_f32 v[28:29], v[0:1], s[42:43], v[28:29] op_sel_hi:[1,0,1]
	v_mov_b64_e32 v[0:1], v[224:225]
	v_mov_b64_e32 v[2:3], v[226:227]
	s_nop 0
	v_mov_b64_e32 v[4:5], v[194:195]
	v_mov_b64_e32 v[6:7], v[196:197]
	s_nop 0
	v_mov_b64_e32 v[54:55], v[232:233]
	v_add_f32_e32 v50, v28, v29
	v_mov_b64_e32 v[46:47], v[238:239]
	v_add_f32_e32 v52, v30, v31
	v_pk_mul_f32 v[6:7], v[6:7], 0.5 op_sel_hi:[1,0]
	v_lshlrev_b32_e32 v48, 16, v54
	v_and_b32_e32 v49, 0xffff0000, v54
	v_lshlrev_b32_e32 v54, 16, v55
	v_and_b32_e32 v55, 0xffff0000, v55
	v_lshlrev_b32_e32 v56, 16, v46
	v_and_b32_e32 v57, 0xffff0000, v46
	v_lshlrev_b32_e32 v46, 16, v47
	v_and_b32_e32 v47, 0xffff0000, v47
	v_pk_mul_f32 v[4:5], v[4:5], 0.5 op_sel_hi:[1,0]
	v_pk_add_f32 v[46:47], v[54:55], v[46:47]
	v_pk_add_f32 v[48:49], v[48:49], v[56:57]
	v_pk_mul_f32 v[6:7], v[6:7], v[46:47]
	v_pk_mul_f32 v[4:5], v[4:5], v[48:49]
	v_pk_fma_f32 v[118:119], v[2:3], s[42:43], v[6:7] op_sel_hi:[1,0,1]
	v_pk_fma_f32 v[62:63], v[0:1], s[42:43], v[4:5] op_sel_hi:[1,0,1]
	v_mov_b32_e32 v51, v118
	v_mov_b32_e32 v41, v62
	v_mov_b32_e32 v45, v63
	v_mov_b32_e32 v53, v119
	v_pk_add_f32 v[0:1], v[40:41], v[44:45]
	v_pk_add_f32 v[2:3], v[50:51], v[52:53]
	v_lshl_add_u64 v[4:5], v[90:91], 0, s[28:29]
	v_pk_add_f32 v[0:1], v[0:1], v[2:3]
	v_mad_u64_u32 v[48:49], s[4:5], v4, s7, v[78:79]
	v_add_f32_e32 v121, v0, v1
	v_lshlrev_b64 v[0:1], 12, v[18:19]
	v_lshl_add_u64 v[18:19], s[56:57], 0, v[100:101]
	v_lshl_add_u64 v[46:47], v[18:19], 0, s[8:9]
	v_mad_i32_i24 v49, v5, s7, v49
	v_lshl_add_u64 v[18:19], v[18:19], 0, v[152:153]
	v_lshl_add_u64 v[52:53], v[46:47], 0, v[152:153]
	global_load_dwordx4 v[186:189], v[48:49], off offset:1024
	global_load_dwordx4 v[190:193], v[48:49], off offset:2048
	global_load_dwordx4 v[194:197], v[48:49], off offset:3072
	flat_load_dwordx4 v[4:7], v[48:49]
	global_load_dwordx2 v[228:229], v[18:19], off offset:512
	global_load_dwordx2 v[230:231], v[18:19], off offset:1024
	global_load_dwordx2 v[232:233], v[18:19], off offset:1536
	flat_load_dwordx2 v[44:45], v[18:19]
	v_lshl_add_u64 v[40:41], v[80:81], 0, v[0:1]
	global_load_dwordx2 v[234:235], v[52:53], off offset:512
	global_load_dwordx2 v[236:237], v[52:53], off offset:1024
	global_load_dwordx2 v[238:239], v[52:53], off offset:1536
	flat_load_dwordx2 v[52:53], v[52:53]
	v_lshl_add_u64 v[56:57], v[46:47], 0, v[42:43]
	global_load_dwordx4 v[198:201], v[40:41], off offset:1024
	global_load_dwordx4 v[202:205], v[40:41], off offset:2048
	global_load_dwordx4 v[224:227], v[40:41], off offset:3072
	flat_load_dwordx4 v[0:3], v[40:41]
	v_lshl_add_u64 v[108:109], v[46:47], 0, v[104:105]
	v_lshl_add_u64 v[46:47], v[46:47], 0, v[106:107]
	s_waitcnt vmcnt(0) lgkmcnt(0)
	v_pk_mul_f32 v[6:7], v[6:7], 0.5 op_sel_hi:[1,0]
	v_lshlrev_b32_e32 v50, 16, v44
	v_and_b32_e32 v51, 0xffff0000, v44
	v_lshlrev_b32_e32 v44, 16, v45
	v_and_b32_e32 v45, 0xffff0000, v45
	v_lshlrev_b32_e32 v54, 16, v52
	v_and_b32_e32 v55, 0xffff0000, v52
	v_lshlrev_b32_e32 v52, 16, v53
	v_and_b32_e32 v53, 0xffff0000, v53
	v_pk_mul_f32 v[4:5], v[4:5], 0.5 op_sel_hi:[1,0]
	v_pk_add_f32 v[50:51], v[50:51], v[54:55]
	v_pk_add_f32 v[44:45], v[44:45], v[52:53]
	v_pk_mul_f32 v[4:5], v[4:5], v[50:51]
	v_pk_mul_f32 v[6:7], v[6:7], v[44:45]
	v_pk_fma_f32 v[44:45], v[0:1], s[42:43], v[4:5] op_sel_hi:[1,0,1]
	v_pk_fma_f32 v[50:51], v[2:3], s[42:43], v[6:7] op_sel_hi:[1,0,1]
	v_mov_b32_e32 v2, v44
	v_pk_mov_b32 v[0:1], v[44:45], v[50:51] op_sel:[1,0]
	v_mov_b32_e32 v3, v51
	v_pk_add_f32 v[0:1], v[0:1], v[2:3]
	s_nop 0
	v_add_f32_e32 v0, v0, v1
	v_add_f32_e32 v98, 0, v0
	v_mov_b64_e32 v[0:1], v[198:199]
	v_mov_b64_e32 v[2:3], v[200:201]
	v_mov_b64_e32 v[4:5], v[186:187]
	v_mov_b64_e32 v[6:7], v[188:189]
	v_mov_b64_e32 v[52:53], v[228:229]
	v_pk_mul_f32 v[6:7], v[6:7], 0.5 op_sel_hi:[1,0]
	v_mov_b64_e32 v[56:57], v[234:235]
	v_lshlrev_b32_e32 v54, 16, v52
	v_and_b32_e32 v55, 0xffff0000, v52
	v_lshlrev_b32_e32 v52, 16, v53
	v_and_b32_e32 v53, 0xffff0000, v53
	v_pk_mul_f32 v[4:5], v[4:5], 0.5 op_sel_hi:[1,0]
	v_lshlrev_b32_e32 v58, 16, v56
	v_and_b32_e32 v59, 0xffff0000, v56
	v_lshlrev_b32_e32 v56, 16, v57
	v_and_b32_e32 v57, 0xffff0000, v57
	v_pk_add_f32 v[54:55], v[54:55], v[58:59]
	v_pk_add_f32 v[52:53], v[52:53], v[56:57]
	v_pk_mul_f32 v[4:5], v[4:5], v[54:55]
	v_pk_mul_f32 v[6:7], v[6:7], v[52:53]
	v_pk_fma_f32 v[56:57], v[0:1], s[42:43], v[4:5] op_sel_hi:[1,0,1]
	v_pk_fma_f32 v[58:59], v[2:3], s[42:43], v[6:7] op_sel_hi:[1,0,1]
	v_mov_b32_e32 v2, v56
	v_pk_mov_b32 v[0:1], v[56:57], v[58:59] op_sel:[1,0]
	v_mov_b32_e32 v3, v59
	v_pk_add_f32 v[0:1], v[0:1], v[2:3]
	s_nop 0
	v_pk_add_f32 v[102:103], v[0:1], v[0:1] op_sel:[0,1] op_sel_hi:[1,0]
	v_mov_b64_e32 v[0:1], v[202:203]
	v_mov_b64_e32 v[2:3], v[204:205]
	v_mov_b64_e32 v[4:5], v[190:191]
	v_mov_b64_e32 v[6:7], v[192:193]
	v_mov_b64_e32 v[52:53], v[230:231]
	v_pk_mul_f32 v[6:7], v[6:7], 0.5 op_sel_hi:[1,0]
	v_mov_b64_e32 v[108:109], v[236:237]
	v_lshlrev_b32_e32 v54, 16, v52
	v_and_b32_e32 v55, 0xffff0000, v52
	v_lshlrev_b32_e32 v52, 16, v53
	v_and_b32_e32 v53, 0xffff0000, v53
	v_pk_mul_f32 v[4:5], v[4:5], 0.5 op_sel_hi:[1,0]
	v_lshlrev_b32_e32 v110, 16, v108
	v_and_b32_e32 v111, 0xffff0000, v108
	v_lshlrev_b32_e32 v108, 16, v109
	v_and_b32_e32 v109, 0xffff0000, v109
	v_pk_add_f32 v[52:53], v[52:53], v[108:109]
	v_pk_add_f32 v[54:55], v[54:55], v[110:111]
	v_pk_mul_f32 v[6:7], v[6:7], v[52:53]
	v_pk_mul_f32 v[4:5], v[4:5], v[54:55]
	v_pk_fma_f32 v[54:55], v[2:3], s[42:43], v[6:7] op_sel_hi:[1,0,1]
	v_pk_fma_f32 v[52:53], v[0:1], s[42:43], v[4:5] op_sel_hi:[1,0,1]
	v_mov_b64_e32 v[0:1], v[224:225]
	v_mov_b64_e32 v[2:3], v[226:227]
	v_mov_b64_e32 v[4:5], v[194:195]
	v_mov_b64_e32 v[6:7], v[196:197]
	s_nop 0
	v_mov_b64_e32 v[18:19], v[232:233]
	v_add_f32_e32 v108, v52, v53
	v_mov_b64_e32 v[46:47], v[238:239]
	v_add_f32_e32 v110, v54, v55
	v_pk_mul_f32 v[6:7], v[6:7], 0.5 op_sel_hi:[1,0]
	v_lshlrev_b32_e32 v48, 16, v18
	v_and_b32_e32 v49, 0xffff0000, v18
	v_lshlrev_b32_e32 v18, 16, v19
	v_and_b32_e32 v19, 0xffff0000, v19
	v_lshlrev_b32_e32 v112, 16, v46
	v_and_b32_e32 v113, 0xffff0000, v46
	v_lshlrev_b32_e32 v46, 16, v47
	v_and_b32_e32 v47, 0xffff0000, v47
	v_pk_mul_f32 v[4:5], v[4:5], 0.5 op_sel_hi:[1,0]
	v_pk_add_f32 v[18:19], v[18:19], v[46:47]
	v_pk_add_f32 v[46:47], v[48:49], v[112:113]
	v_pk_mul_f32 v[6:7], v[6:7], v[18:19]
	v_pk_mul_f32 v[4:5], v[4:5], v[46:47]
	v_pk_fma_f32 v[48:49], v[2:3], s[42:43], v[6:7] op_sel_hi:[1,0,1]
	v_pk_fma_f32 v[46:47], v[0:1], s[42:43], v[4:5] op_sel_hi:[1,0,1]
	v_mov_b32_e32 v109, v48
	v_mov_b32_e32 v99, v46
	v_mov_b32_e32 v103, v47
	v_mov_b32_e32 v111, v49
	v_pk_add_f32 v[0:1], v[98:99], v[102:103]
	v_pk_add_f32 v[2:3], v[108:109], v[110:111]
	v_lshlrev_b64 v[98:99], 11, v[16:17]
	v_pk_add_f32 v[0:1], v[0:1], v[2:3]
	v_lshl_add_u64 v[4:5], v[88:89], 0, s[28:29]
	v_add_f32_e32 v125, v0, v1
	v_lshlrev_b64 v[0:1], 12, v[16:17]
	v_lshl_add_u64 v[16:17], s[56:57], 0, v[98:99]
	v_lshl_add_u64 v[18:19], v[16:17], 0, s[8:9]
	v_mad_u64_u32 v[126:127], s[4:5], v4, s7, v[78:79]
	v_mad_i32_i24 v127, v5, s7, v127
	v_lshl_add_u64 v[16:17], v[16:17], 0, v[152:153]
	v_lshl_add_u64 v[112:113], v[18:19], 0, v[152:153]
	global_load_dwordx4 v[186:189], v[126:127], off offset:1024
	global_load_dwordx4 v[190:193], v[126:127], off offset:2048
	global_load_dwordx4 v[194:197], v[126:127], off offset:3072
	flat_load_dwordx4 v[4:7], v[126:127]
	global_load_dwordx2 v[228:229], v[16:17], off offset:512
	global_load_dwordx2 v[230:231], v[16:17], off offset:1024
	global_load_dwordx2 v[232:233], v[16:17], off offset:1536
	flat_load_dwordx2 v[108:109], v[16:17]
	v_lshl_add_u64 v[102:103], v[80:81], 0, v[0:1]
	global_load_dwordx2 v[234:235], v[112:113], off offset:512
	global_load_dwordx2 v[236:237], v[112:113], off offset:1024
	global_load_dwordx2 v[238:239], v[112:113], off offset:1536
	flat_load_dwordx2 v[112:113], v[112:113]
	v_lshl_add_u64 v[42:43], v[18:19], 0, v[42:43]
	global_load_dwordx4 v[198:201], v[102:103], off offset:1024
	global_load_dwordx4 v[202:205], v[102:103], off offset:2048
	global_load_dwordx4 v[224:227], v[102:103], off offset:3072
	flat_load_dwordx4 v[0:3], v[102:103]
	v_lshl_add_u64 v[104:105], v[18:19], 0, v[104:105]
	v_lshl_add_u64 v[18:19], v[18:19], 0, v[106:107]
	s_mov_b32 s4, 0x3727c5ac
	s_waitcnt vmcnt(0) lgkmcnt(0)
	v_pk_mul_f32 v[6:7], v[6:7], 0.5 op_sel_hi:[1,0]
	v_lshlrev_b32_e32 v110, 16, v108
	v_and_b32_e32 v111, 0xffff0000, v108
	v_lshlrev_b32_e32 v108, 16, v109
	v_and_b32_e32 v109, 0xffff0000, v109
	v_lshlrev_b32_e32 v114, 16, v112
	v_and_b32_e32 v115, 0xffff0000, v112
	v_lshlrev_b32_e32 v112, 16, v113
	v_and_b32_e32 v113, 0xffff0000, v113
	v_pk_mul_f32 v[4:5], v[4:5], 0.5 op_sel_hi:[1,0]
	v_pk_add_f32 v[110:111], v[110:111], v[114:115]
	v_pk_add_f32 v[108:109], v[108:109], v[112:113]
	v_pk_mul_f32 v[4:5], v[4:5], v[110:111]
	v_pk_mul_f32 v[6:7], v[6:7], v[108:109]
	v_pk_fma_f32 v[114:115], v[0:1], s[42:43], v[4:5] op_sel_hi:[1,0,1]
	v_pk_fma_f32 v[116:117], v[2:3], s[42:43], v[6:7] op_sel_hi:[1,0,1]
	v_mov_b32_e32 v2, v114
	v_pk_mov_b32 v[0:1], v[114:115], v[116:117] op_sel:[1,0]
	v_mov_b32_e32 v3, v117
	v_pk_add_f32 v[0:1], v[0:1], v[2:3]
	s_nop 0
	v_add_f32_e32 v0, v0, v1
	v_add_f32_e32 v128, 0, v0
	v_mov_b64_e32 v[0:1], v[198:199]
	v_mov_b64_e32 v[2:3], v[200:201]
	v_mov_b64_e32 v[4:5], v[186:187]
	v_mov_b64_e32 v[6:7], v[188:189]
	v_mov_b64_e32 v[108:109], v[228:229]
	v_pk_mul_f32 v[6:7], v[6:7], 0.5 op_sel_hi:[1,0]
	v_mov_b64_e32 v[42:43], v[234:235]
	v_lshlrev_b32_e32 v110, 16, v108
	v_and_b32_e32 v111, 0xffff0000, v108
	v_lshlrev_b32_e32 v108, 16, v109
	v_and_b32_e32 v109, 0xffff0000, v109
	v_pk_mul_f32 v[4:5], v[4:5], 0.5 op_sel_hi:[1,0]
	v_lshlrev_b32_e32 v112, 16, v42
	v_and_b32_e32 v113, 0xffff0000, v42
	v_lshlrev_b32_e32 v42, 16, v43
	v_and_b32_e32 v43, 0xffff0000, v43
	v_pk_add_f32 v[110:111], v[110:111], v[112:113]
	v_pk_add_f32 v[42:43], v[108:109], v[42:43]
	v_pk_mul_f32 v[4:5], v[4:5], v[110:111]
	v_pk_mul_f32 v[6:7], v[6:7], v[42:43]
	v_pk_fma_f32 v[42:43], v[0:1], s[42:43], v[4:5] op_sel_hi:[1,0,1]
	v_pk_fma_f32 v[112:113], v[2:3], s[42:43], v[6:7] op_sel_hi:[1,0,1]
	v_mov_b32_e32 v2, v42
	v_pk_mov_b32 v[0:1], v[42:43], v[112:113] op_sel:[1,0]
	v_mov_b32_e32 v3, v113
	v_pk_add_f32 v[0:1], v[0:1], v[2:3]
	s_nop 0
	v_pk_add_f32 v[130:131], v[0:1], v[0:1] op_sel:[0,1] op_sel_hi:[1,0]
	v_mov_b64_e32 v[0:1], v[202:203]
	v_mov_b64_e32 v[2:3], v[204:205]
	v_mov_b64_e32 v[4:5], v[190:191]
	v_mov_b64_e32 v[6:7], v[192:193]
	v_mov_b64_e32 v[108:109], v[230:231]
	v_pk_mul_f32 v[6:7], v[6:7], 0.5 op_sel_hi:[1,0]
	v_mov_b64_e32 v[104:105], v[236:237]
	v_lshlrev_b32_e32 v110, 16, v108
	v_and_b32_e32 v111, 0xffff0000, v108
	v_lshlrev_b32_e32 v108, 16, v109
	v_and_b32_e32 v109, 0xffff0000, v109
	v_pk_mul_f32 v[4:5], v[4:5], 0.5 op_sel_hi:[1,0]
	v_lshlrev_b32_e32 v132, 16, v104
	v_and_b32_e32 v133, 0xffff0000, v104
	v_lshlrev_b32_e32 v104, 16, v105
	v_and_b32_e32 v105, 0xffff0000, v105
	v_pk_add_f32 v[104:105], v[108:109], v[104:105]
	v_pk_add_f32 v[108:109], v[110:111], v[132:133]
	v_pk_mul_f32 v[6:7], v[6:7], v[104:105]
	v_pk_mul_f32 v[4:5], v[4:5], v[108:109]
	v_pk_fma_f32 v[110:111], v[2:3], s[42:43], v[6:7] op_sel_hi:[1,0,1]
	v_pk_fma_f32 v[108:109], v[0:1], s[42:43], v[4:5] op_sel_hi:[1,0,1]
	v_mov_b64_e32 v[0:1], v[224:225]
	v_mov_b64_e32 v[2:3], v[226:227]
	v_mov_b64_e32 v[4:5], v[194:195]
	v_mov_b64_e32 v[6:7], v[196:197]
	s_nop 0
	v_mov_b64_e32 v[16:17], v[232:233]
	v_add_f32_e32 v132, v108, v109
	v_mov_b64_e32 v[18:19], v[238:239]
	v_add_f32_e32 v134, v110, v111
	v_pk_mul_f32 v[6:7], v[6:7], 0.5 op_sel_hi:[1,0]
	v_lshlrev_b32_e32 v104, 16, v16
	v_and_b32_e32 v105, 0xffff0000, v16
	v_lshlrev_b32_e32 v16, 16, v17
	v_and_b32_e32 v17, 0xffff0000, v17
	v_lshlrev_b32_e32 v106, 16, v18
	v_and_b32_e32 v107, 0xffff0000, v18
	v_lshlrev_b32_e32 v18, 16, v19
	v_and_b32_e32 v19, 0xffff0000, v19
	v_pk_mul_f32 v[4:5], v[4:5], 0.5 op_sel_hi:[1,0]
	v_pk_add_f32 v[16:17], v[16:17], v[18:19]
	v_pk_add_f32 v[18:19], v[104:105], v[106:107]
	v_pk_mul_f32 v[6:7], v[6:7], v[16:17]
	v_pk_mul_f32 v[4:5], v[4:5], v[18:19]
	v_pk_fma_f32 v[106:107], v[2:3], s[42:43], v[6:7] op_sel_hi:[1,0,1]
	v_pk_fma_f32 v[104:105], v[0:1], s[42:43], v[4:5] op_sel_hi:[1,0,1]
	v_mov_b32_e32 v133, v106
	v_mov_b32_e32 v129, v104
	v_mov_b32_e32 v131, v105
	v_mov_b32_e32 v135, v107
	v_pk_add_f32 v[0:1], v[128:129], v[130:131]
	v_pk_add_f32 v[2:3], v[132:133], v[134:135]
	ds_bpermute_b32 v18, v67, v121
	v_pk_add_f32 v[0:1], v[0:1], v[2:3]
	s_waitcnt lgkmcnt(0)
	v_add_f32_e32 v18, v121, v18
	v_add_f32_e32 v65, v0, v1
	ds_bpermute_b32 v0, v67, v120
	ds_bpermute_b32 v19, v69, v18
	s_waitcnt lgkmcnt(1)
	v_add_f32_e32 v0, v120, v0
	ds_bpermute_b32 v1, v69, v0
	s_waitcnt lgkmcnt(1)
	v_add_f32_e32 v18, v18, v19
	ds_bpermute_b32 v19, v71, v18
	s_waitcnt lgkmcnt(1)
	v_add_f32_e32 v0, v0, v1
	ds_bpermute_b32 v1, v71, v0
	s_waitcnt lgkmcnt(1)
	v_add_f32_e32 v18, v18, v19
	ds_bpermute_b32 v19, v73, v18
	s_waitcnt lgkmcnt(1)
	v_add_f32_e32 v0, v0, v1
	ds_bpermute_b32 v1, v73, v0
	s_waitcnt lgkmcnt(1)
	v_add_f32_e32 v18, v18, v19
	ds_bpermute_b32 v19, v123, v18
	s_waitcnt lgkmcnt(1)
	v_add_f32_e32 v0, v0, v1
	ds_bpermute_b32 v1, v123, v0
	s_waitcnt lgkmcnt(1)
	v_add_f32_e32 v18, v18, v19
	ds_bpermute_b32 v19, v124, v18
	s_waitcnt lgkmcnt(1)
	v_add_f32_e32 v0, v0, v1
	ds_bpermute_b32 v1, v124, v0
	s_waitcnt lgkmcnt(1)
	v_add_f32_e32 v122, v18, v19
	v_fmamk_f32 v35, v122, 0xba800000, v35
	v_fmac_f32_e32 v34, 0xba800000, v122
	v_fmamk_f32 v37, v122, 0xba800000, v37
	s_waitcnt lgkmcnt(0)
	v_add_f32_e32 v16, v0, v1
	v_fmamk_f32 v9, v16, 0xba800000, v9
	v_fmac_f32_e32 v8, 0xba800000, v16
	v_fmamk_f32 v11, v16, 0xba800000, v11
	v_fmac_f32_e32 v10, 0xba800000, v16
	v_pk_mul_f32 v[0:1], v[10:11], v[10:11]
	v_pk_mul_f32 v[2:3], v[8:9], v[8:9]
	v_fmamk_f32 v13, v16, 0xba800000, v13
	v_pk_mov_b32 v[4:5], v[2:3], v[0:1] op_sel:[1,0]
	v_mov_b32_e32 v3, v1
	v_pk_add_f32 v[0:1], v[4:5], v[2:3]
	v_fmac_f32_e32 v12, 0xba800000, v16
	v_fmamk_f32 v15, v16, 0xba800000, v15
	v_fmac_f32_e32 v14, 0xba800000, v16
	v_pk_add_f32 v[0:1], v[0:1], v[0:1] op_sel_hi:[0,1]
	v_pk_mul_f32 v[2:3], v[14:15], v[14:15]
	v_pk_mul_f32 v[4:5], v[12:13], v[12:13]
	v_fmac_f32_e32 v20, 0xba800000, v16
	v_pk_mov_b32 v[6:7], v[4:5], v[2:3] op_sel:[1,0]
	v_mov_b32_e32 v5, v3
	v_fmamk_f32 v21, v16, 0xba800000, v21
	v_fmac_f32_e32 v22, 0xba800000, v16
	v_mul_f32_e32 v0, v20, v20
	v_pk_add_f32 v[2:3], v[6:7], v[4:5]
	v_fmamk_f32 v23, v16, 0xba800000, v23
	v_pk_fma_f32 v[4:5], v[20:21], v[20:21], v[0:1] op_sel_hi:[1,1,0]
	v_mul_f32_e32 v0, v22, v22
	v_pk_add_f32 v[2:3], v[2:3], v[2:3] op_sel_hi:[0,1]
	v_pk_fma_f32 v[6:7], v[22:23], v[22:23], v[0:1] op_sel_hi:[1,1,0]
	v_fmamk_f32 v27, v16, 0xba800000, v27
	v_fmac_f32_e32 v26, 0xba800000, v16
	v_fmamk_f32 v25, v16, 0xba800000, v25
	v_fmac_f32_e32 v24, 0xba800000, v16
	v_mul_f32_e32 v4, v24, v24
	v_mul_f32_e32 v6, v25, v25
	v_mul_f32_e32 v0, v26, v26
	v_mul_f32_e32 v2, v27, v27
	v_pk_add_f32 v[4:5], v[4:5], v[6:7]
	v_pk_add_f32 v[0:1], v[0:1], v[2:3]
	v_fmac_f32_e32 v36, 0xba800000, v122
	v_pk_add_f32 v[16:17], v[4:5], v[0:1]
	v_mov_b64_e32 v[0:1], v[154:155]
	v_mov_b64_e32 v[2:3], v[156:157]
	v_mov_b64_e32 v[4:5], v[158:159]
	v_mov_b64_e32 v[6:7], v[160:161]
	v_pk_mul_f32 v[18:19], v[36:37], v[36:37]
	v_pk_mul_f32 v[120:121], v[34:35], v[34:35]
	v_fmamk_f32 v39, v122, 0xba800000, v39
	v_pk_mov_b32 v[126:127], v[120:121], v[18:19] op_sel:[1,0]
	v_mov_b32_e32 v121, v19
	v_pk_add_f32 v[18:19], v[126:127], v[120:121]
	v_fmac_f32_e32 v38, 0xba800000, v122
	v_fmamk_f32 v61, v122, 0xba800000, v61
	v_fmac_f32_e32 v60, 0xba800000, v122
	v_pk_add_f32 v[18:19], v[18:19], v[18:19] op_sel_hi:[0,1]
	v_pk_mul_f32 v[120:121], v[60:61], v[60:61]
	v_pk_mul_f32 v[126:127], v[38:39], v[38:39]
	v_fmac_f32_e32 v28, 0xba800000, v122
	v_pk_mov_b32 v[128:129], v[126:127], v[120:121] op_sel:[1,0]
	v_mov_b32_e32 v127, v121
	v_fmamk_f32 v29, v122, 0xba800000, v29
	v_fmac_f32_e32 v30, 0xba800000, v122
	v_mul_f32_e32 v18, v28, v28
	v_pk_add_f32 v[120:121], v[128:129], v[126:127]
	v_fmamk_f32 v31, v122, 0xba800000, v31
	v_pk_fma_f32 v[126:127], v[28:29], v[28:29], v[18:19] op_sel_hi:[1,1,0]
	v_mul_f32_e32 v18, v30, v30
	v_pk_add_f32 v[120:121], v[120:121], v[120:121] op_sel_hi:[0,1]
	v_pk_fma_f32 v[128:129], v[30:31], v[30:31], v[18:19] op_sel_hi:[1,1,0]
	v_fmamk_f32 v119, v122, 0xba800000, v119
	v_fmac_f32_e32 v118, 0xba800000, v122
	v_fmamk_f32 v63, v122, 0xba800000, v63
	v_fmac_f32_e32 v62, 0xba800000, v122
	v_mul_f32_e32 v126, v62, v62
	v_mul_f32_e32 v128, v63, v63
	v_mul_f32_e32 v18, v118, v118
	v_mul_f32_e32 v120, v119, v119
	v_pk_add_f32 v[126:127], v[126:127], v[128:129]
	v_pk_add_f32 v[18:19], v[18:19], v[120:121]
	v_mov_b32_e32 v121, v16
	v_pk_add_f32 v[18:19], v[126:127], v[18:19]
	s_nop 0
	v_mov_b32_e32 v120, v18
	v_mov_b32_e32 v16, v19
	v_pk_add_f32 v[16:17], v[120:121], v[16:17]
	ds_bpermute_b32 v19, v67, v17
	ds_bpermute_b32 v18, v67, v16
	v_mov_b64_e32 v[120:121], s[4:5]
	s_mov_b32 s4, 0x3a800000
	s_waitcnt lgkmcnt(0)
	v_pk_add_f32 v[16:17], v[16:17], v[18:19]
	ds_bpermute_b32 v19, v69, v17
	ds_bpermute_b32 v18, v69, v16
	s_waitcnt lgkmcnt(0)
	v_pk_add_f32 v[16:17], v[16:17], v[18:19]
	ds_bpermute_b32 v19, v71, v17
	ds_bpermute_b32 v18, v71, v16
	s_waitcnt lgkmcnt(0)
	v_pk_add_f32 v[16:17], v[16:17], v[18:19]
	ds_bpermute_b32 v19, v73, v17
	ds_bpermute_b32 v18, v73, v16
	s_waitcnt lgkmcnt(0)
	v_pk_add_f32 v[16:17], v[16:17], v[18:19]
	ds_bpermute_b32 v19, v123, v17
	ds_bpermute_b32 v18, v123, v16
	s_waitcnt lgkmcnt(0)
	v_pk_add_f32 v[16:17], v[16:17], v[18:19]
	ds_bpermute_b32 v19, v124, v17
	ds_bpermute_b32 v18, v124, v16
	s_waitcnt lgkmcnt(0)
	v_pk_add_f32 v[16:17], v[16:17], v[18:19]
	s_nop 0
	v_pk_fma_f32 v[126:127], v[16:17], s[4:5], v[120:121] op_sel_hi:[1,0,0]
	s_nop 0
	v_mul_f32_e32 v16, 0x4b800000, v127
	v_cmp_gt_f32_e64 s[8:9], s68, v127
	v_cmp_gt_f32_e32 vcc, s68, v126
	s_nop 0
	v_cndmask_b32_e64 v16, v127, v16, s[8:9]
	v_rsq_f32_e32 v16, v16
	s_nop 0
	v_mul_f32_e32 v17, 0x45800000, v16
	v_cndmask_b32_e64 v122, v16, v17, s[8:9]
	v_pk_mul_f32 v[8:9], v[8:9], v[122:123] op_sel_hi:[1,0]
	v_pk_mul_f32 v[10:11], v[10:11], v[122:123] op_sel_hi:[1,0]
	v_pk_fma_f32 v[16:17], v[0:1], v[8:9], v[4:5]
	v_pk_fma_f32 v[18:19], v[2:3], v[10:11], v[6:7]
	flat_store_dwordx4 v[86:87], v[16:19] sc1
	v_mov_b64_e32 v[0:1], v[162:163]
	v_mov_b64_e32 v[2:3], v[164:165]
	v_mov_b64_e32 v[4:5], v[166:167]
	v_mov_b64_e32 v[6:7], v[168:169]
	v_pk_mul_f32 v[8:9], v[14:15], v[122:123] op_sel_hi:[1,0]
	v_pk_mul_f32 v[10:11], v[12:13], v[122:123] op_sel_hi:[1,0]
	v_pk_fma_f32 v[14:15], v[2:3], v[8:9], v[6:7]
	v_pk_fma_f32 v[12:13], v[0:1], v[10:11], v[4:5]
	flat_store_dwordx4 v[86:87], v[12:15] offset:1024 sc1
	v_mov_b64_e32 v[0:1], v[170:171]
	v_mov_b64_e32 v[2:3], v[172:173]
	v_mov_b64_e32 v[4:5], v[174:175]
	v_mov_b64_e32 v[6:7], v[176:177]
	v_pk_mul_f32 v[8:9], v[22:23], v[122:123] op_sel_hi:[1,0]
	v_pk_mul_f32 v[10:11], v[20:21], v[122:123] op_sel_hi:[1,0]
	v_pk_mul_f32 v[22:23], v[24:25], v[122:123] op_sel_hi:[1,0]
	v_pk_mul_f32 v[20:21], v[26:27], v[122:123] op_sel_hi:[1,0]
	v_pk_fma_f32 v[4:5], v[0:1], v[10:11], v[4:5]
	v_pk_fma_f32 v[6:7], v[2:3], v[8:9], v[6:7]
	flat_store_dwordx4 v[86:87], v[4:7] offset:2048 sc1
	v_mov_b64_e32 v[0:1], v[178:179]
	v_mov_b64_e32 v[2:3], v[180:181]
	v_mov_b64_e32 v[8:9], v[182:183]
	v_mov_b64_e32 v[10:11], v[184:185]
	v_pk_fma_f32 v[0:1], v[0:1], v[22:23], v[8:9]
	v_mul_f32_e32 v8, 0x4b800000, v126
	v_cndmask_b32_e32 v8, v126, v8, vcc
	v_rsq_f32_e32 v8, v8
	v_pk_fma_f32 v[2:3], v[2:3], v[20:21], v[10:11]
	flat_store_dwordx4 v[86:87], v[0:3] offset:3072 sc1
	v_mul_f32_e32 v9, 0x45800000, v8
	v_cndmask_b32_e32 v122, v8, v9, vcc
	v_mov_b64_e32 v[8:9], v[154:155]
	v_mov_b64_e32 v[10:11], v[156:157]
	v_mov_b64_e32 v[20:21], v[158:159]
	v_mov_b64_e32 v[22:23], v[160:161]
	v_pk_mul_f32 v[24:25], v[36:37], v[122:123] op_sel_hi:[1,0]
	v_pk_mul_f32 v[26:27], v[34:35], v[122:123] op_sel_hi:[1,0]
	v_pk_mul_f32 v[34:35], v[60:61], v[122:123] op_sel_hi:[1,0]
	v_pk_mul_f32 v[36:37], v[38:39], v[122:123] op_sel_hi:[1,0]
	v_pk_mul_f32 v[38:39], v[118:119], v[122:123] op_sel_hi:[1,0]
	v_pk_mul_f32 v[60:61], v[62:63], v[122:123] op_sel_hi:[1,0]
	ds_bpermute_b32 v62, v67, v65
	s_waitcnt lgkmcnt(0)
	v_add_f32_e32 v62, v65, v62
	ds_bpermute_b32 v63, v69, v62
	s_waitcnt lgkmcnt(0)
	v_add_f32_e32 v62, v62, v63
	ds_bpermute_b32 v63, v71, v62
	s_waitcnt lgkmcnt(0)
	v_add_f32_e32 v62, v62, v63
	ds_bpermute_b32 v63, v73, v62
	s_waitcnt lgkmcnt(0)
	v_add_f32_e32 v62, v62, v63
	ds_bpermute_b32 v63, v123, v62
	s_waitcnt lgkmcnt(0)
	v_add_f32_e32 v62, v62, v63
	ds_bpermute_b32 v63, v124, v62
	s_waitcnt lgkmcnt(0)
	v_add_f32_e32 v65, v62, v63
	v_fmamk_f32 v115, v65, 0xba800000, v115
	v_fmac_f32_e32 v114, 0xba800000, v65
	v_fmamk_f32 v117, v65, 0xba800000, v117
	v_fmac_f32_e32 v116, 0xba800000, v65
	v_pk_mul_f32 v[62:63], v[116:117], v[116:117]
	v_pk_mul_f32 v[118:119], v[114:115], v[114:115]
	v_fmamk_f32 v43, v65, 0xba800000, v43
	v_pk_mov_b32 v[126:127], v[118:119], v[62:63] op_sel:[1,0]
	v_mov_b32_e32 v119, v63
	v_pk_add_f32 v[62:63], v[126:127], v[118:119]
	v_fmac_f32_e32 v42, 0xba800000, v65
	v_fmamk_f32 v113, v65, 0xba800000, v113
	v_fmac_f32_e32 v112, 0xba800000, v65
	v_pk_add_f32 v[62:63], v[62:63], v[62:63] op_sel_hi:[0,1]
	v_pk_mul_f32 v[118:119], v[112:113], v[112:113]
	v_pk_mul_f32 v[126:127], v[42:43], v[42:43]
	v_fmac_f32_e32 v108, 0xba800000, v65
	v_pk_mov_b32 v[128:129], v[126:127], v[118:119] op_sel:[1,0]
	v_mov_b32_e32 v127, v119
	v_fmamk_f32 v109, v65, 0xba800000, v109
	v_fmac_f32_e32 v110, 0xba800000, v65
	v_mul_f32_e32 v62, v108, v108
	v_pk_add_f32 v[118:119], v[128:129], v[126:127]
	v_fmamk_f32 v111, v65, 0xba800000, v111
	v_pk_fma_f32 v[126:127], v[108:109], v[108:109], v[62:63] op_sel_hi:[1,1,0]
	v_mul_f32_e32 v62, v110, v110
	v_pk_add_f32 v[118:119], v[118:119], v[118:119] op_sel_hi:[0,1]
	v_pk_fma_f32 v[128:129], v[110:111], v[110:111], v[62:63] op_sel_hi:[1,1,0]
	v_fmamk_f32 v107, v65, 0xba800000, v107
	v_fmac_f32_e32 v106, 0xba800000, v65
	v_fmamk_f32 v105, v65, 0xba800000, v105
	v_fmac_f32_e32 v104, 0xba800000, v65
	v_mul_f32_e32 v126, v104, v104
	v_mul_f32_e32 v128, v105, v105
	v_mul_f32_e32 v62, v106, v106
	v_mul_f32_e32 v118, v107, v107
	v_pk_add_f32 v[126:127], v[126:127], v[128:129]
	v_pk_fma_f32 v[8:9], v[8:9], v[26:27], v[20:21]
	v_pk_fma_f32 v[10:11], v[10:11], v[24:25], v[22:23]
	flat_store_dwordx4 v[32:33], v[8:11] sc1
	v_mov_b64_e32 v[20:21], v[162:163]
	v_mov_b64_e32 v[22:23], v[164:165]
	v_mov_b64_e32 v[24:25], v[166:167]
	v_mov_b64_e32 v[26:27], v[168:169]
	v_pk_add_f32 v[62:63], v[62:63], v[118:119]
	v_pk_fma_f32 v[20:21], v[20:21], v[36:37], v[24:25]
	v_pk_fma_f32 v[22:23], v[22:23], v[34:35], v[26:27]
	flat_store_dwordx4 v[32:33], v[20:23] offset:1024 sc1
	v_pk_mul_f32 v[34:35], v[30:31], v[122:123] op_sel_hi:[1,0]
	v_pk_mul_f32 v[36:37], v[28:29], v[122:123] op_sel_hi:[1,0]
	v_mov_b64_e32 v[24:25], v[170:171]
	v_mov_b64_e32 v[26:27], v[172:173]
	v_mov_b64_e32 v[28:29], v[174:175]
	v_mov_b64_e32 v[30:31], v[176:177]
	v_pk_add_f32 v[62:63], v[126:127], v[62:63]
	v_pk_fma_f32 v[28:29], v[24:25], v[36:37], v[28:29]
	v_pk_fma_f32 v[30:31], v[26:27], v[34:35], v[30:31]
	flat_store_dwordx4 v[32:33], v[28:31] offset:2048 sc1
	v_mov_b64_e32 v[24:25], v[178:179]
	v_mov_b64_e32 v[26:27], v[180:181]
	v_mov_b64_e32 v[34:35], v[182:183]
	v_mov_b64_e32 v[36:37], v[184:185]
	v_mov_b32_e32 v118, v62
	v_pk_fma_f32 v[24:25], v[24:25], v[60:61], v[34:35]
	v_pk_fma_f32 v[26:27], v[26:27], v[38:39], v[36:37]
	flat_store_dwordx4 v[32:33], v[24:27] offset:3072 sc1
	ds_bpermute_b32 v32, v67, v125
	s_waitcnt lgkmcnt(0)
	v_add_f32_e32 v32, v125, v32
	ds_bpermute_b32 v33, v69, v32
	s_waitcnt lgkmcnt(0)
	v_add_f32_e32 v32, v32, v33
	ds_bpermute_b32 v33, v71, v32
	s_waitcnt lgkmcnt(0)
	v_add_f32_e32 v32, v32, v33
	ds_bpermute_b32 v33, v73, v32
	s_waitcnt lgkmcnt(0)
	v_add_f32_e32 v32, v32, v33
	ds_bpermute_b32 v33, v123, v32
	s_waitcnt lgkmcnt(0)
	v_add_f32_e32 v32, v32, v33
	ds_bpermute_b32 v33, v124, v32
	s_waitcnt lgkmcnt(0)
	v_add_f32_e32 v60, v32, v33
	v_fmamk_f32 v45, v60, 0xba800000, v45
	v_fmac_f32_e32 v44, 0xba800000, v60
	v_fmamk_f32 v51, v60, 0xba800000, v51
	v_fmac_f32_e32 v50, 0xba800000, v60
	v_pk_mul_f32 v[32:33], v[50:51], v[50:51]
	v_pk_mul_f32 v[34:35], v[44:45], v[44:45]
	v_fmamk_f32 v57, v60, 0xba800000, v57
	v_pk_mov_b32 v[36:37], v[34:35], v[32:33] op_sel:[1,0]
	v_mov_b32_e32 v35, v33
	v_pk_add_f32 v[32:33], v[36:37], v[34:35]
	v_fmac_f32_e32 v56, 0xba800000, v60
	v_fmamk_f32 v59, v60, 0xba800000, v59
	v_fmac_f32_e32 v58, 0xba800000, v60
	v_pk_add_f32 v[32:33], v[32:33], v[32:33] op_sel_hi:[0,1]
	v_pk_mul_f32 v[34:35], v[58:59], v[58:59]
	v_pk_mul_f32 v[36:37], v[56:57], v[56:57]
	v_fmac_f32_e32 v52, 0xba800000, v60
	v_pk_mov_b32 v[38:39], v[36:37], v[34:35] op_sel:[1,0]
	v_mov_b32_e32 v37, v35
	v_fmamk_f32 v53, v60, 0xba800000, v53
	v_fmac_f32_e32 v54, 0xba800000, v60
	v_mul_f32_e32 v32, v52, v52
	v_pk_add_f32 v[34:35], v[38:39], v[36:37]
	v_fmamk_f32 v55, v60, 0xba800000, v55
	v_pk_fma_f32 v[36:37], v[52:53], v[52:53], v[32:33] op_sel_hi:[1,1,0]
	v_mul_f32_e32 v32, v54, v54
	v_pk_add_f32 v[34:35], v[34:35], v[34:35] op_sel_hi:[0,1]
	v_pk_fma_f32 v[38:39], v[54:55], v[54:55], v[32:33] op_sel_hi:[1,1,0]
	v_fmamk_f32 v49, v60, 0xba800000, v49
	v_fmac_f32_e32 v48, 0xba800000, v60
	v_fmamk_f32 v47, v60, 0xba800000, v47
	v_fmac_f32_e32 v46, 0xba800000, v60
	v_mul_f32_e32 v36, v46, v46
	v_mul_f32_e32 v38, v47, v47
	v_mul_f32_e32 v32, v48, v48
	v_mul_f32_e32 v34, v49, v49
	v_pk_add_f32 v[36:37], v[36:37], v[38:39]
	v_pk_add_f32 v[32:33], v[32:33], v[34:35]
	s_nop 0
	v_pk_add_f32 v[60:61], v[36:37], v[32:33]
	v_mov_b64_e32 v[32:33], v[154:155]
	v_mov_b64_e32 v[34:35], v[156:157]
	v_mov_b64_e32 v[36:37], v[158:159]
	v_mov_b64_e32 v[38:39], v[160:161]
	v_mov_b32_e32 v119, v60
	v_mov_b32_e32 v60, v63
	v_pk_add_f32 v[60:61], v[118:119], v[60:61]
	ds_bpermute_b32 v63, v67, v61
	ds_bpermute_b32 v62, v67, v60
	s_waitcnt lgkmcnt(0)
	v_pk_add_f32 v[60:61], v[60:61], v[62:63]
	ds_bpermute_b32 v63, v69, v61
	ds_bpermute_b32 v62, v69, v60
	s_waitcnt lgkmcnt(0)
	v_pk_add_f32 v[60:61], v[60:61], v[62:63]
	ds_bpermute_b32 v63, v71, v61
	ds_bpermute_b32 v62, v71, v60
	s_waitcnt lgkmcnt(0)
	v_pk_add_f32 v[60:61], v[60:61], v[62:63]
	ds_bpermute_b32 v63, v73, v61
	ds_bpermute_b32 v62, v73, v60
	s_waitcnt lgkmcnt(0)
	v_pk_add_f32 v[60:61], v[60:61], v[62:63]
	ds_bpermute_b32 v63, v123, v61
	ds_bpermute_b32 v62, v123, v60
	s_waitcnt lgkmcnt(0)
	v_pk_add_f32 v[60:61], v[60:61], v[62:63]
	ds_bpermute_b32 v63, v124, v61
	ds_bpermute_b32 v62, v124, v60
	s_waitcnt lgkmcnt(0)
	v_pk_add_f32 v[60:61], v[60:61], v[62:63]
	s_nop 0
	v_pk_fma_f32 v[118:119], v[60:61], s[4:5], v[120:121] op_sel_hi:[1,0,0]
	s_nop 0
	v_mul_f32_e32 v60, 0x4b800000, v119
	v_cmp_gt_f32_e64 s[8:9], s68, v119
	v_cmp_gt_f32_e32 vcc, s68, v118
	s_nop 0
	v_cndmask_b32_e64 v60, v119, v60, s[8:9]
	v_rsq_f32_e32 v60, v60
	s_nop 0
	v_mul_f32_e32 v61, 0x45800000, v60
	v_cndmask_b32_e64 v120, v60, v61, s[8:9]
	v_pk_mul_f32 v[50:51], v[50:51], v[120:121] op_sel_hi:[1,0]
	v_pk_mul_f32 v[44:45], v[44:45], v[120:121] op_sel_hi:[1,0]
	v_pk_mul_f32 v[46:47], v[46:47], v[120:121] op_sel_hi:[1,0]
	v_pk_fma_f32 v[60:61], v[32:33], v[44:45], v[36:37]
	v_pk_fma_f32 v[62:63], v[34:35], v[50:51], v[38:39]
	flat_store_dwordx4 v[40:41], v[60:63] sc1
	v_mov_b64_e32 v[32:33], v[162:163]
	v_mov_b64_e32 v[34:35], v[164:165]
	v_mov_b64_e32 v[36:37], v[166:167]
	v_mov_b64_e32 v[38:39], v[168:169]
	v_pk_mul_f32 v[44:45], v[58:59], v[120:121] op_sel_hi:[1,0]
	v_pk_mul_f32 v[50:51], v[56:57], v[120:121] op_sel_hi:[1,0]
	v_pk_fma_f32 v[58:59], v[34:35], v[44:45], v[38:39]
	v_pk_fma_f32 v[56:57], v[32:33], v[50:51], v[36:37]
	flat_store_dwordx4 v[40:41], v[56:59] offset:1024 sc1
	v_mov_b64_e32 v[32:33], v[170:171]
	v_mov_b64_e32 v[34:35], v[172:173]
	v_mov_b64_e32 v[36:37], v[174:175]
	v_mov_b64_e32 v[38:39], v[176:177]
	v_pk_mul_f32 v[44:45], v[54:55], v[120:121] op_sel_hi:[1,0]
	v_pk_mul_f32 v[50:51], v[52:53], v[120:121] op_sel_hi:[1,0]
	v_pk_fma_f32 v[54:55], v[34:35], v[44:45], v[38:39]
	v_pk_fma_f32 v[52:53], v[32:33], v[50:51], v[36:37]
	flat_store_dwordx4 v[40:41], v[52:55] offset:2048 sc1
	v_mov_b64_e32 v[32:33], v[178:179]
	v_mov_b64_e32 v[34:35], v[180:181]
	v_mov_b64_e32 v[36:37], v[182:183]
	v_mov_b64_e32 v[38:39], v[184:185]
	v_pk_mul_f32 v[44:45], v[48:49], v[120:121] op_sel_hi:[1,0]
	v_pk_fma_f32 v[48:49], v[32:33], v[46:47], v[36:37]
	v_mul_f32_e32 v32, 0x4b800000, v118
	v_cndmask_b32_e32 v32, v118, v32, vcc
	v_rsq_f32_e32 v32, v32
	v_pk_fma_f32 v[50:51], v[34:35], v[44:45], v[38:39]
	flat_store_dwordx4 v[40:41], v[48:51] offset:3072 sc1
	v_mul_f32_e32 v33, 0x45800000, v32
	v_cndmask_b32_e32 v118, v32, v33, vcc
	v_mov_b64_e32 v[32:33], v[154:155]
	v_mov_b64_e32 v[34:35], v[156:157]
	v_mov_b64_e32 v[36:37], v[158:159]
	v_mov_b64_e32 v[38:39], v[160:161]
	v_pk_mul_f32 v[40:41], v[116:117], v[118:119] op_sel_hi:[1,0]
	v_pk_mul_f32 v[44:45], v[114:115], v[118:119] op_sel_hi:[1,0]
	v_pk_mul_f32 v[112:113], v[112:113], v[118:119] op_sel_hi:[1,0]
	v_pk_mul_f32 v[110:111], v[110:111], v[118:119] op_sel_hi:[1,0]
	v_pk_mul_f32 v[108:109], v[108:109], v[118:119] op_sel_hi:[1,0]
	s_andn2_b64 vcc, exec, s[14:15]
	v_pk_fma_f32 v[44:45], v[32:33], v[44:45], v[36:37]
	v_pk_fma_f32 v[46:47], v[34:35], v[40:41], v[38:39]
	flat_store_dwordx4 v[102:103], v[44:47] sc1
	v_mov_b64_e32 v[32:33], v[162:163]
	v_mov_b64_e32 v[34:35], v[164:165]
	v_mov_b64_e32 v[36:37], v[166:167]
	v_mov_b64_e32 v[38:39], v[168:169]
	v_pk_mul_f32 v[40:41], v[42:43], v[118:119] op_sel_hi:[1,0]
	v_pk_fma_f32 v[42:43], v[34:35], v[112:113], v[38:39]
	v_pk_fma_f32 v[40:41], v[32:33], v[40:41], v[36:37]
	flat_store_dwordx4 v[102:103], v[40:43] offset:1024 sc1
	v_mov_b64_e32 v[32:33], v[170:171]
	v_mov_b64_e32 v[34:35], v[172:173]
	v_mov_b64_e32 v[36:37], v[174:175]
	v_mov_b64_e32 v[38:39], v[176:177]
	v_pk_fma_f32 v[36:37], v[32:33], v[108:109], v[36:37]
	v_pk_fma_f32 v[38:39], v[34:35], v[110:111], v[38:39]
	flat_store_dwordx4 v[102:103], v[36:39] offset:2048 sc1
	v_pk_mul_f32 v[108:109], v[106:107], v[118:119] op_sel_hi:[1,0]
	v_pk_mul_f32 v[110:111], v[104:105], v[118:119] op_sel_hi:[1,0]
	v_mov_b64_e32 v[32:33], v[178:179]
	v_mov_b64_e32 v[34:35], v[180:181]
	v_mov_b64_e32 v[104:105], v[182:183]
	v_mov_b64_e32 v[106:107], v[184:185]
	v_pk_fma_f32 v[32:33], v[32:33], v[110:111], v[104:105]
	v_pk_fma_f32 v[34:35], v[34:35], v[108:109], v[106:107]
	flat_store_dwordx4 v[102:103], v[32:35] offset:3072 sc1
	s_cbranch_vccnz .LBB0_224
	v_lshl_add_u64 v[102:103], v[94:95], 0, s[2:3]
	v_mov_b64_e32 v[94:95], s[60:61]
	v_mad_u64_u32 v[104:105], s[4:5], v102, s7, v[94:95]
	v_mad_i32_i24 v105, v103, s7, v105
	v_lshl_add_u64 v[110:111], v[104:105], 0, s[30:31]
	v_lshlrev_b32_e32 v152, 2, v66
	v_lshl_add_u64 v[112:113], v[104:105], 0, v[152:153]
	v_lshl_add_u64 v[106:107], v[110:111], 0, v[152:153]
	global_load_dwordx4 v[186:189], v[112:113], off offset:1024
	global_load_dwordx4 v[190:193], v[112:113], off offset:2048
	global_load_dwordx4 v[194:197], v[112:113], off offset:3072
	flat_load_dwordx4 v[102:105], v[112:113]
	s_nop 0
	global_load_dwordx4 v[198:201], v[106:107], off offset:1024
	global_load_dwordx4 v[202:205], v[106:107], off offset:2048
	global_load_dwordx4 v[224:227], v[106:107], off offset:3072
	flat_load_dwordx4 v[106:109], v[106:107]
	s_waitcnt vmcnt(0) lgkmcnt(0)
	v_pk_add_f32 v[108:109], v[108:109], 1.0 op_sel_hi:[1,0]
	v_pk_add_f32 v[106:107], v[106:107], 1.0 op_sel_hi:[1,0]
	v_pk_fma_f32 v[18:19], v[18:19], v[108:109], v[104:105]
	v_pk_fma_f32 v[16:17], v[16:17], v[106:107], v[102:103]
	s_nop 0
	v_cvt_pk_bf16_f32 v16, v16, v17
	v_cvt_pk_bf16_f32 v17, v18, v19
	flat_store_dwordx2 v[84:85], v[16:17] sc1
	v_lshlrev_b32_e32 v16, 2, v68
	v_mov_b32_e32 v17, v153
	v_lshl_add_u64 v[18:19], v[110:111], 0, v[16:17]
	v_mov_b64_e32 v[102:103], v[186:187]
	v_mov_b64_e32 v[104:105], v[188:189]
	v_mov_b64_e32 v[106:107], v[198:199]
	v_mov_b64_e32 v[108:109], v[200:201]
	v_pk_add_f32 v[18:19], v[108:109], 1.0 op_sel_hi:[1,0]
	v_pk_add_f32 v[106:107], v[106:107], 1.0 op_sel_hi:[1,0]
	v_pk_fma_f32 v[14:15], v[14:15], v[18:19], v[104:105]
	v_pk_fma_f32 v[12:13], v[12:13], v[106:107], v[102:103]
	s_nop 0
	v_cvt_pk_bf16_f32 v12, v12, v13
	v_cvt_pk_bf16_f32 v13, v14, v15
	flat_store_dwordx2 v[84:85], v[12:13] offset:512 sc1
	v_lshlrev_b32_e32 v12, 2, v70
	v_mov_b32_e32 v13, v153
	v_lshl_add_u64 v[14:15], v[110:111], 0, v[12:13]
	v_mov_b64_e32 v[102:103], v[190:191]
	v_mov_b64_e32 v[104:105], v[192:193]
	v_mov_b64_e32 v[106:107], v[202:203]
	v_mov_b64_e32 v[108:109], v[204:205]
	v_pk_add_f32 v[14:15], v[108:109], 1.0 op_sel_hi:[1,0]
	v_pk_add_f32 v[18:19], v[106:107], 1.0 op_sel_hi:[1,0]
	v_pk_fma_f32 v[6:7], v[6:7], v[14:15], v[104:105]
	v_pk_fma_f32 v[4:5], v[4:5], v[18:19], v[102:103]
	s_nop 0
	v_cvt_pk_bf16_f32 v4, v4, v5
	v_cvt_pk_bf16_f32 v5, v6, v7
	flat_store_dwordx2 v[84:85], v[4:5] offset:1024 sc1
	v_lshlrev_b32_e32 v4, 2, v72
	v_mov_b32_e32 v5, v153
	v_lshl_add_u64 v[6:7], v[110:111], 0, v[4:5]
	v_mov_b64_e32 v[102:103], v[194:195]
	v_mov_b64_e32 v[104:105], v[196:197]
	v_mov_b64_e32 v[106:107], v[224:225]
	v_mov_b64_e32 v[108:109], v[226:227]
	v_pk_add_f32 v[6:7], v[108:109], 1.0 op_sel_hi:[1,0]
	v_pk_add_f32 v[14:15], v[106:107], 1.0 op_sel_hi:[1,0]
	v_pk_fma_f32 v[2:3], v[2:3], v[6:7], v[104:105]
	v_pk_fma_f32 v[0:1], v[0:1], v[14:15], v[102:103]
	s_nop 0
	v_cvt_pk_bf16_f32 v0, v0, v1
	v_cvt_pk_bf16_f32 v1, v2, v3
	flat_store_dwordx2 v[84:85], v[0:1] offset:1536 sc1
	v_lshl_add_u64 v[0:1], v[92:93], 0, s[2:3]
	v_mad_u64_u32 v[2:3], s[4:5], v0, s7, v[94:95]
	v_mad_i32_i24 v3, v1, s7, v3
	v_lshl_add_u64 v[0:1], v[2:3], 0, s[30:31]
	v_lshl_add_u64 v[2:3], v[2:3], 0, v[152:153]
	v_lshl_add_u64 v[6:7], v[0:1], 0, v[152:153]
	global_load_dwordx4 v[186:189], v[2:3], off offset:1024
	global_load_dwordx4 v[190:193], v[2:3], off offset:2048
	global_load_dwordx4 v[194:197], v[2:3], off offset:3072
	flat_load_dwordx4 v[102:105], v[2:3]
	global_load_dwordx4 v[198:201], v[6:7], off offset:1024
	global_load_dwordx4 v[202:205], v[6:7], off offset:2048
	global_load_dwordx4 v[224:227], v[6:7], off offset:3072
	flat_load_dwordx4 v[106:109], v[6:7]
	s_waitcnt vmcnt(0) lgkmcnt(0)
	v_pk_add_f32 v[6:7], v[108:109], 1.0 op_sel_hi:[1,0]
	v_pk_add_f32 v[14:15], v[106:107], 1.0 op_sel_hi:[1,0]
	v_pk_fma_f32 v[6:7], v[10:11], v[6:7], v[104:105]
	v_pk_fma_f32 v[8:9], v[8:9], v[14:15], v[102:103]
	v_lshl_add_u64 v[10:11], v[82:83], 0, v[96:97]
	v_cvt_pk_bf16_f32 v8, v8, v9
	v_cvt_pk_bf16_f32 v9, v6, v7
	flat_store_dwordx2 v[10:11], v[8:9] sc1
	v_lshl_add_u64 v[14:15], v[0:1], 0, v[16:17]
	v_mov_b64_e32 v[6:7], v[186:187]
	v_mov_b64_e32 v[8:9], v[188:189]
	v_mov_b64_e32 v[102:103], v[198:199]
	v_mov_b64_e32 v[104:105], v[200:201]
	v_pk_add_f32 v[14:15], v[104:105], 1.0 op_sel_hi:[1,0]
	v_pk_add_f32 v[18:19], v[102:103], 1.0 op_sel_hi:[1,0]
	v_pk_fma_f32 v[8:9], v[22:23], v[14:15], v[8:9]
	v_pk_fma_f32 v[6:7], v[20:21], v[18:19], v[6:7]
	v_lshl_add_u64 v[14:15], v[0:1], 0, v[12:13]
	v_cvt_pk_bf16_f32 v6, v6, v7
	v_cvt_pk_bf16_f32 v7, v8, v9
	flat_store_dwordx2 v[10:11], v[6:7] offset:512 sc1
	v_mov_b64_e32 v[6:7], v[190:191]
	v_mov_b64_e32 v[8:9], v[192:193]
	v_lshl_add_u64 v[0:1], v[0:1], 0, v[4:5]
	v_mov_b64_e32 v[18:19], v[202:203]
	v_mov_b64_e32 v[20:21], v[204:205]
	v_pk_add_f32 v[14:15], v[20:21], 1.0 op_sel_hi:[1,0]
	v_pk_add_f32 v[18:19], v[18:19], 1.0 op_sel_hi:[1,0]
	v_pk_fma_f32 v[8:9], v[30:31], v[14:15], v[8:9]
	v_pk_fma_f32 v[6:7], v[28:29], v[18:19], v[6:7]
	s_nop 0
	v_cvt_pk_bf16_f32 v6, v6, v7
	v_cvt_pk_bf16_f32 v7, v8, v9
	flat_store_dwordx2 v[10:11], v[6:7] offset:1024 sc1
	v_mov_b64_e32 v[6:7], v[194:195]
	v_mov_b64_e32 v[8:9], v[196:197]
	s_nop 0
	v_mov_b64_e32 v[0:1], v[224:225]
	v_mov_b64_e32 v[2:3], v[226:227]
	v_pk_add_f32 v[2:3], v[2:3], 1.0 op_sel_hi:[1,0]
	v_pk_add_f32 v[0:1], v[0:1], 1.0 op_sel_hi:[1,0]
	v_pk_fma_f32 v[2:3], v[26:27], v[2:3], v[8:9]
	v_pk_fma_f32 v[0:1], v[24:25], v[0:1], v[6:7]
	s_nop 0
	v_cvt_pk_bf16_f32 v0, v0, v1
	v_cvt_pk_bf16_f32 v1, v2, v3
	flat_store_dwordx2 v[10:11], v[0:1] offset:1536 sc1
	v_lshl_add_u64 v[0:1], v[90:91], 0, s[2:3]
	v_mad_u64_u32 v[2:3], s[4:5], v0, s7, v[94:95]
	v_mad_i32_i24 v3, v1, s7, v3
	v_lshl_add_u64 v[0:1], v[2:3], 0, s[30:31]
	v_lshl_add_u64 v[2:3], v[2:3], 0, v[152:153]
	v_lshl_add_u64 v[10:11], v[0:1], 0, v[152:153]
	global_load_dwordx4 v[186:189], v[2:3], off offset:1024
	global_load_dwordx4 v[190:193], v[2:3], off offset:2048
	global_load_dwordx4 v[194:197], v[2:3], off offset:3072
	flat_load_dwordx4 v[6:9], v[2:3]
	global_load_dwordx4 v[198:201], v[10:11], off offset:1024
	global_load_dwordx4 v[202:205], v[10:11], off offset:2048
	global_load_dwordx4 v[224:227], v[10:11], off offset:3072
	flat_load_dwordx4 v[18:21], v[10:11]
	s_waitcnt vmcnt(0) lgkmcnt(0)
	v_pk_add_f32 v[10:11], v[20:21], 1.0 op_sel_hi:[1,0]
	v_pk_add_f32 v[14:15], v[18:19], 1.0 op_sel_hi:[1,0]
	v_pk_fma_f32 v[8:9], v[62:63], v[10:11], v[8:9]
	v_pk_fma_f32 v[6:7], v[60:61], v[14:15], v[6:7]
	v_lshl_add_u64 v[10:11], v[82:83], 0, v[100:101]
	v_cvt_pk_bf16_f32 v6, v6, v7
	v_cvt_pk_bf16_f32 v7, v8, v9
	flat_store_dwordx2 v[10:11], v[6:7] sc1
	v_lshl_add_u64 v[14:15], v[0:1], 0, v[16:17]
	v_mov_b64_e32 v[6:7], v[186:187]
	v_mov_b64_e32 v[8:9], v[188:189]
	v_mov_b64_e32 v[18:19], v[198:199]
	v_mov_b64_e32 v[20:21], v[200:201]
	v_pk_add_f32 v[14:15], v[20:21], 1.0 op_sel_hi:[1,0]
	v_pk_add_f32 v[18:19], v[18:19], 1.0 op_sel_hi:[1,0]
	v_pk_fma_f32 v[8:9], v[58:59], v[14:15], v[8:9]
	v_pk_fma_f32 v[6:7], v[56:57], v[18:19], v[6:7]
	v_lshl_add_u64 v[14:15], v[0:1], 0, v[12:13]
	v_cvt_pk_bf16_f32 v6, v6, v7
	v_cvt_pk_bf16_f32 v7, v8, v9
	flat_store_dwordx2 v[10:11], v[6:7] offset:512 sc1
	v_mov_b64_e32 v[6:7], v[190:191]
	v_mov_b64_e32 v[8:9], v[192:193]
	v_lshl_add_u64 v[0:1], v[0:1], 0, v[4:5]
	v_mov_b64_e32 v[18:19], v[202:203]
	v_mov_b64_e32 v[20:21], v[204:205]
	v_pk_add_f32 v[14:15], v[20:21], 1.0 op_sel_hi:[1,0]
	v_pk_add_f32 v[18:19], v[18:19], 1.0 op_sel_hi:[1,0]
	v_pk_fma_f32 v[8:9], v[54:55], v[14:15], v[8:9]
	v_pk_fma_f32 v[6:7], v[52:53], v[18:19], v[6:7]
	s_nop 0
	v_cvt_pk_bf16_f32 v6, v6, v7
	v_cvt_pk_bf16_f32 v7, v8, v9
	flat_store_dwordx2 v[10:11], v[6:7] offset:1024 sc1
	v_mov_b64_e32 v[6:7], v[194:195]
	v_mov_b64_e32 v[8:9], v[196:197]
	s_nop 0
	v_mov_b64_e32 v[0:1], v[224:225]
	v_mov_b64_e32 v[2:3], v[226:227]
	v_pk_add_f32 v[2:3], v[2:3], 1.0 op_sel_hi:[1,0]
	v_pk_add_f32 v[0:1], v[0:1], 1.0 op_sel_hi:[1,0]
	v_pk_fma_f32 v[2:3], v[50:51], v[2:3], v[8:9]
	v_pk_fma_f32 v[0:1], v[48:49], v[0:1], v[6:7]
	s_nop 0
	v_cvt_pk_bf16_f32 v0, v0, v1
	v_cvt_pk_bf16_f32 v1, v2, v3
	flat_store_dwordx2 v[10:11], v[0:1] offset:1536 sc1
	v_lshl_add_u64 v[0:1], v[88:89], 0, s[2:3]
	v_mad_u64_u32 v[2:3], s[4:5], v0, s7, v[94:95]
	v_mad_i32_i24 v3, v1, s7, v3
	v_lshl_add_u64 v[0:1], v[2:3], 0, s[30:31]
	v_lshl_add_u64 v[2:3], v[2:3], 0, v[152:153]
	v_lshl_add_u64 v[10:11], v[0:1], 0, v[152:153]
	global_load_dwordx4 v[186:189], v[2:3], off offset:1024
	global_load_dwordx4 v[190:193], v[2:3], off offset:2048
	global_load_dwordx4 v[194:197], v[2:3], off offset:3072
	flat_load_dwordx4 v[6:9], v[2:3]
	global_load_dwordx4 v[198:201], v[10:11], off offset:1024
	global_load_dwordx4 v[202:205], v[10:11], off offset:2048
	global_load_dwordx4 v[224:227], v[10:11], off offset:3072
	flat_load_dwordx4 v[18:21], v[10:11]
	s_waitcnt vmcnt(0) lgkmcnt(0)
	v_pk_add_f32 v[10:11], v[20:21], 1.0 op_sel_hi:[1,0]
	v_pk_add_f32 v[14:15], v[18:19], 1.0 op_sel_hi:[1,0]
	v_pk_fma_f32 v[8:9], v[46:47], v[10:11], v[8:9]
	v_pk_fma_f32 v[6:7], v[44:45], v[14:15], v[6:7]
	v_lshl_add_u64 v[18:19], v[82:83], 0, v[98:99]
	v_cvt_pk_bf16_f32 v6, v6, v7
	v_cvt_pk_bf16_f32 v7, v8, v9
	flat_store_dwordx2 v[18:19], v[6:7] sc1
	v_lshl_add_u64 v[10:11], v[0:1], 0, v[16:17]
	v_mov_b64_e32 v[6:7], v[186:187]
	v_mov_b64_e32 v[8:9], v[188:189]
	v_mov_b64_e32 v[14:15], v[198:199]
	v_mov_b64_e32 v[16:17], v[200:201]
	v_pk_add_f32 v[10:11], v[16:17], 1.0 op_sel_hi:[1,0]
	v_pk_add_f32 v[14:15], v[14:15], 1.0 op_sel_hi:[1,0]
	v_pk_fma_f32 v[8:9], v[42:43], v[10:11], v[8:9]
	v_pk_fma_f32 v[6:7], v[40:41], v[14:15], v[6:7]
	v_lshl_add_u64 v[10:11], v[0:1], 0, v[12:13]
	v_cvt_pk_bf16_f32 v6, v6, v7
	v_cvt_pk_bf16_f32 v7, v8, v9
	flat_store_dwordx2 v[18:19], v[6:7] offset:512 sc1
	v_mov_b64_e32 v[6:7], v[190:191]
	v_mov_b64_e32 v[8:9], v[192:193]
	v_lshl_add_u64 v[0:1], v[0:1], 0, v[4:5]
	v_mov_b64_e32 v[10:11], v[202:203]
	v_mov_b64_e32 v[12:13], v[204:205]
	v_pk_add_f32 v[12:13], v[12:13], 1.0 op_sel_hi:[1,0]
	v_pk_add_f32 v[10:11], v[10:11], 1.0 op_sel_hi:[1,0]
	v_pk_fma_f32 v[8:9], v[38:39], v[12:13], v[8:9]
	v_pk_fma_f32 v[6:7], v[36:37], v[10:11], v[6:7]
	s_nop 0
	v_cvt_pk_bf16_f32 v6, v6, v7
	v_cvt_pk_bf16_f32 v7, v8, v9
	flat_store_dwordx2 v[18:19], v[6:7] offset:1024 sc1
	v_mov_b64_e32 v[6:7], v[194:195]
	v_mov_b64_e32 v[8:9], v[196:197]
	s_nop 0
	v_mov_b64_e32 v[0:1], v[224:225]
	v_mov_b64_e32 v[2:3], v[226:227]
	v_pk_add_f32 v[2:3], v[2:3], 1.0 op_sel_hi:[1,0]
	v_pk_add_f32 v[0:1], v[0:1], 1.0 op_sel_hi:[1,0]
	v_pk_fma_f32 v[2:3], v[34:35], v[2:3], v[8:9]
	v_pk_fma_f32 v[0:1], v[32:33], v[0:1], v[6:7]
	s_nop 0
	v_cvt_pk_bf16_f32 v0, v0, v1
	v_cvt_pk_bf16_f32 v1, v2, v3
	flat_store_dwordx2 v[18:19], v[0:1] offset:1536 sc1
	s_branch .LBB0_224
